# GEMM tile loops (P2,P6,P8,P10): first k-iteration peeled with C=0 on each accumulator's first MFMA, 128-instruction zero-init per tile removed
# speedup vs baseline: 1.0152x; 1.0099x over previous
.LBB0_376:
	s_ashr_i32 s17, s16, 31
	v_cmp_lt_i64_e32 vcc, s[20:21], v[140:141]
	s_lshl_b64 s[20:21], s[16:17], 20
	s_add_u32 s20, s35, s20
	s_addc_u32 s21, s36, s21
	s_and_b64 s[22:23], vcc, exec
	s_cselect_b32 s17, s21, s25
	s_cselect_b32 s19, s20, s24
	s_ashr_i32 s15, s14, 31
	s_lshl_b64 s[22:23], s[14:15], 20
	s_add_u32 s22, s37, s22
	s_addc_u32 s23, s38, s23
	s_and_b64 s[28:29], vcc, exec
	s_cselect_b32 s15, s23, s27
	s_cselect_b32 s51, s22, s26
	s_add_u32 s24, s24, 0x80080
	s_addc_u32 s25, s25, 0
	s_add_u32 s52, s26, 0x100
	s_addc_u32 s53, s27, 0
	s_mov_b32 s54, -2
	ds_read_b128 v[152:155], v149
	ds_read_b128 v[156:159], v149 offset:1024
	ds_read_b128 v[160:163], v149 offset:2048
	ds_read_b128 v[168:171], v149 offset:3072
	s_add_u32 s26, s24, 0xfff80080
	s_addc_u32 s27, s25, -1
	s_cmp_eq_u32 s54, 28
	s_cselect_b32 s29, s17, s27
	s_cselect_b32 s28, s19, s26
	s_cselect_b32 s27, s15, s53
	s_cselect_b32 s26, s51, s52
	v_lshl_add_u64 v[144:145], s[24:25], 0, v[136:137]
	s_add_i32 m0, s39, 0xc000
	ds_read_b128 v[172:175], v150
	ds_read_b128 v[176:179], v150 offset:1024
	ds_read_b128 v[180:183], v150 offset:2048
	ds_read_b128 v[184:187], v150 offset:3072
	ds_read_b128 v[188:191], v150 offset:4096
	ds_read_b128 v[192:195], v150 offset:5120
	ds_read_b128 v[196:199], v150 offset:6144
	ds_read_b128 v[200:203], v150 offset:7168
	global_load_lds_dwordx4 v[144:145], off
	v_lshl_add_u64 v[144:145], s[24:25], 0, v[138:139]
	s_add_i32 m0, s39, 0xe000
	s_nop 0
	global_load_lds_dwordx4 v[144:145], off
	s_waitcnt lgkmcnt(8)
	s_barrier
	s_waitcnt lgkmcnt(0)
	s_setprio 1
	s_waitcnt lgkmcnt(0)
	v_mfma_f32_16x16x32_bf16 v[126:129], v[152:155], v[172:175], 0
	v_mfma_f32_16x16x32_bf16 v[122:125], v[160:163], v[172:175], 0
	v_mfma_f32_16x16x32_bf16 v[118:121], v[152:155], v[180:183], 0
	v_mfma_f32_16x16x32_bf16 v[114:117], v[160:163], v[180:183], 0
	v_mfma_f32_16x16x32_bf16 v[102:105], v[152:155], v[188:191], 0
	v_mfma_f32_16x16x32_bf16 v[98:101], v[160:163], v[188:191], 0
	v_mfma_f32_16x16x32_bf16 v[86:89], v[152:155], v[196:199], 0
	v_mfma_f32_16x16x32_bf16 v[82:85], v[160:163], v[196:199], 0
	v_mfma_f32_16x16x32_bf16 v[126:129], v[156:159], v[176:179], v[126:129]
	v_mfma_f32_16x16x32_bf16 v[122:125], v[168:171], v[176:179], v[122:125]
	v_mfma_f32_16x16x32_bf16 v[118:121], v[156:159], v[184:187], v[118:121]
	v_mfma_f32_16x16x32_bf16 v[114:117], v[168:171], v[184:187], v[114:117]
	v_mfma_f32_16x16x32_bf16 v[102:105], v[156:159], v[192:195], v[102:105]
	v_mfma_f32_16x16x32_bf16 v[98:101], v[168:171], v[192:195], v[98:101]
	v_mfma_f32_16x16x32_bf16 v[86:89], v[156:159], v[200:203], v[86:89]
	v_mfma_f32_16x16x32_bf16 v[82:85], v[168:171], v[200:203], v[82:85]
	s_setprio 0
	s_barrier
	s_add_i32 s55, s47, s34
	v_lshl_add_u64 v[144:145], s[26:27], 0, v[130:131]
	s_mov_b32 m0, s55
	ds_read_b128 v[204:207], v151
	ds_read_b128 v[208:211], v151 offset:1024
	ds_read_b128 v[212:215], v151 offset:2048
	ds_read_b128 v[216:219], v151 offset:3072
	global_load_lds_dwordx4 v[144:145], off
	v_lshl_add_u64 v[164:165], s[26:27], 0, v[132:133]
	s_add_i32 m0, s55, 0x2000
	s_nop 0
	global_load_lds_dwordx4 v[164:165], off
	s_barrier
	s_waitcnt lgkmcnt(0)
	s_setprio 1
	s_waitcnt lgkmcnt(0)
	v_mfma_f32_16x16x32_bf16 v[110:113], v[204:207], v[172:175], 0
	v_mfma_f32_16x16x32_bf16 v[106:109], v[212:215], v[172:175], 0
	v_mfma_f32_16x16x32_bf16 v[94:97], v[204:207], v[180:183], 0
	v_mfma_f32_16x16x32_bf16 v[90:93], v[212:215], v[180:183], 0
	v_mfma_f32_16x16x32_bf16 v[78:81], v[204:207], v[188:191], 0
	v_mfma_f32_16x16x32_bf16 v[74:77], v[212:215], v[188:191], 0
	v_mfma_f32_16x16x32_bf16 v[70:73], v[204:207], v[196:199], 0
	v_mfma_f32_16x16x32_bf16 v[66:69], v[212:215], v[196:199], 0
	v_mfma_f32_16x16x32_bf16 v[110:113], v[208:211], v[176:179], v[110:113]
	v_mfma_f32_16x16x32_bf16 v[106:109], v[216:219], v[176:179], v[106:109]
	v_mfma_f32_16x16x32_bf16 v[94:97], v[208:211], v[184:187], v[94:97]
	v_mfma_f32_16x16x32_bf16 v[90:93], v[216:219], v[184:187], v[90:93]
	v_mfma_f32_16x16x32_bf16 v[78:81], v[208:211], v[192:195], v[78:81]
	v_mfma_f32_16x16x32_bf16 v[74:77], v[216:219], v[192:195], v[74:77]
	v_mfma_f32_16x16x32_bf16 v[70:73], v[208:211], v[200:203], v[70:73]
	v_mfma_f32_16x16x32_bf16 v[66:69], v[216:219], v[200:203], v[66:69]
	s_setprio 0
	s_mov_b32 m0, s39
	v_lshl_add_u64 v[166:167], s[28:29], 0, v[130:131]
	s_barrier
	ds_read_b128 v[172:175], v150 offset:16384
	ds_read_b128 v[176:179], v150 offset:17408
	ds_read_b128 v[180:183], v150 offset:18432
	ds_read_b128 v[184:187], v150 offset:19456
	ds_read_b128 v[188:191], v150 offset:20480
	ds_read_b128 v[192:195], v150 offset:21504
	ds_read_b128 v[196:199], v150 offset:22528
	ds_read_b128 v[200:203], v150 offset:23552
	global_load_lds_dwordx4 v[166:167], off
	v_lshl_add_u64 v[220:221], s[28:29], 0, v[132:133]
	s_mov_b32 m0, s40
	s_nop 0
	global_load_lds_dwordx4 v[220:221], off
	s_barrier
	s_waitcnt lgkmcnt(0)
	s_setprio 1
	s_waitcnt lgkmcnt(0)
	v_mfma_f32_16x16x32_bf16 v[62:65], v[152:155], v[172:175], 0
	v_mfma_f32_16x16x32_bf16 v[58:61], v[160:163], v[172:175], 0
	v_mfma_f32_16x16x32_bf16 v[54:57], v[152:155], v[180:183], 0
	v_mfma_f32_16x16x32_bf16 v[50:53], v[160:163], v[180:183], 0
	v_mfma_f32_16x16x32_bf16 v[38:41], v[152:155], v[188:191], 0
	v_mfma_f32_16x16x32_bf16 v[34:37], v[160:163], v[188:191], 0
	v_mfma_f32_16x16x32_bf16 v[22:25], v[152:155], v[196:199], 0
	v_mfma_f32_16x16x32_bf16 v[18:21], v[160:163], v[196:199], 0
	v_mfma_f32_16x16x32_bf16 v[62:65], v[156:159], v[176:179], v[62:65]
	v_mfma_f32_16x16x32_bf16 v[58:61], v[168:171], v[176:179], v[58:61]
	v_mfma_f32_16x16x32_bf16 v[54:57], v[156:159], v[184:187], v[54:57]
	v_mfma_f32_16x16x32_bf16 v[50:53], v[168:171], v[184:187], v[50:53]
	v_mfma_f32_16x16x32_bf16 v[38:41], v[156:159], v[192:195], v[38:41]
	v_mfma_f32_16x16x32_bf16 v[34:37], v[168:171], v[192:195], v[34:37]
	v_mfma_f32_16x16x32_bf16 v[22:25], v[156:159], v[200:203], v[22:25]
	v_mfma_f32_16x16x32_bf16 v[18:21], v[168:171], v[200:203], v[18:21]
	s_setprio 0
	s_barrier
	s_add_u32 s56, s26, 0x80000
	s_addc_u32 s57, s27, 0
	s_add_i32 s55, s48, s34
	v_lshl_add_u64 v[152:153], s[56:57], 0, v[130:131]
	s_mov_b32 m0, s55
	s_nop 0
	global_load_lds_dwordx4 v[152:153], off
	v_lshl_add_u64 v[152:153], s[56:57], 0, v[132:133]
	s_add_i32 m0, s55, 0x2000
	s_nop 0
	global_load_lds_dwordx4 v[152:153], off
	s_waitcnt vmcnt(6)
	s_barrier
	s_setprio 1
	v_mfma_f32_16x16x32_bf16 v[46:49], v[204:207], v[172:175], 0
	v_mfma_f32_16x16x32_bf16 v[42:45], v[212:215], v[172:175], 0
	v_mfma_f32_16x16x32_bf16 v[30:33], v[204:207], v[180:183], 0
	v_mfma_f32_16x16x32_bf16 v[26:29], v[212:215], v[180:183], 0
	v_mfma_f32_16x16x32_bf16 v[14:17], v[204:207], v[188:191], 0
	v_mfma_f32_16x16x32_bf16 v[10:13], v[212:215], v[188:191], 0
	v_mfma_f32_16x16x32_bf16 v[6:9], v[204:207], v[196:199], 0
	v_mfma_f32_16x16x32_bf16 v[2:5], v[212:215], v[196:199], 0
	v_mfma_f32_16x16x32_bf16 v[46:49], v[208:211], v[176:179], v[46:49]
	v_mfma_f32_16x16x32_bf16 v[42:45], v[216:219], v[176:179], v[42:45]
	v_mfma_f32_16x16x32_bf16 v[30:33], v[208:211], v[184:187], v[30:33]
	v_mfma_f32_16x16x32_bf16 v[26:29], v[216:219], v[184:187], v[26:29]
	v_mfma_f32_16x16x32_bf16 v[14:17], v[208:211], v[192:195], v[14:17]
	v_mfma_f32_16x16x32_bf16 v[10:13], v[216:219], v[192:195], v[10:13]
	v_mfma_f32_16x16x32_bf16 v[6:9], v[208:211], v[200:203], v[6:9]
	v_mfma_f32_16x16x32_bf16 v[2:5], v[216:219], v[200:203], v[2:5]
	s_setprio 0
	s_add_i32 s55, 0, 0x18000
	v_add_u32_e32 v168, s55, v147
	s_barrier
	ds_read_b128 v[152:155], v168
	ds_read_b128 v[156:159], v168 offset:1024
	ds_read_b128 v[160:163], v168 offset:2048
	ds_read_b128 v[168:171], v168 offset:3072
	s_add_u32 s28, s28, 0x80000
	s_addc_u32 s29, s29, 0
	s_mov_b32 m0, s41
	v_lshl_add_u64 v[204:205], s[28:29], 0, v[130:131]
	ds_read_b128 v[172:175], v150 offset:32768
	ds_read_b128 v[176:179], v150 offset:33792
	ds_read_b128 v[180:183], v150 offset:34816
	ds_read_b128 v[184:187], v150 offset:35840
	ds_read_b128 v[188:191], v150 offset:36864
	ds_read_b128 v[192:195], v150 offset:37888
	ds_read_b128 v[196:199], v150 offset:38912
	ds_read_b128 v[200:203], v150 offset:39936
	global_load_lds_dwordx4 v[204:205], off
	v_lshl_add_u64 v[204:205], s[28:29], 0, v[132:133]
	s_mov_b32 m0, s42
	s_nop 0
	global_load_lds_dwordx4 v[204:205], off
	s_waitcnt lgkmcnt(8)
	s_barrier
	s_waitcnt lgkmcnt(0)
	s_setprio 1
	s_waitcnt lgkmcnt(0)
	v_mfma_f32_16x16x32_bf16 v[126:129], v[152:155], v[172:175], v[126:129]
	v_mfma_f32_16x16x32_bf16 v[122:125], v[160:163], v[172:175], v[122:125]
	v_mfma_f32_16x16x32_bf16 v[118:121], v[152:155], v[180:183], v[118:121]
	v_mfma_f32_16x16x32_bf16 v[114:117], v[160:163], v[180:183], v[114:117]
	v_mfma_f32_16x16x32_bf16 v[102:105], v[152:155], v[188:191], v[102:105]
	v_mfma_f32_16x16x32_bf16 v[98:101], v[160:163], v[188:191], v[98:101]
	v_mfma_f32_16x16x32_bf16 v[86:89], v[152:155], v[196:199], v[86:89]
	v_mfma_f32_16x16x32_bf16 v[82:85], v[160:163], v[196:199], v[82:85]
	v_mfma_f32_16x16x32_bf16 v[126:129], v[156:159], v[176:179], v[126:129]
	v_mfma_f32_16x16x32_bf16 v[122:125], v[168:171], v[176:179], v[122:125]
	v_mfma_f32_16x16x32_bf16 v[118:121], v[156:159], v[184:187], v[118:121]
	v_mfma_f32_16x16x32_bf16 v[114:117], v[168:171], v[184:187], v[114:117]
	v_mfma_f32_16x16x32_bf16 v[102:105], v[156:159], v[192:195], v[102:105]
	v_mfma_f32_16x16x32_bf16 v[98:101], v[168:171], v[192:195], v[98:101]
	v_mfma_f32_16x16x32_bf16 v[86:89], v[156:159], v[200:203], v[86:89]
	v_mfma_f32_16x16x32_bf16 v[82:85], v[168:171], v[200:203], v[82:85]
	s_setprio 0
	s_barrier
	s_add_i32 s28, 0, 0x1c000
	s_add_i32 s29, s55, s34
	v_add_u32_e32 v216, s28, v147
	v_lshl_add_u64 v[144:145], v[144:145], 0, s[10:11]
	s_mov_b32 m0, s29
	ds_read_b128 v[204:207], v216
	ds_read_b128 v[208:211], v216 offset:1024
	ds_read_b128 v[212:215], v216 offset:2048
	ds_read_b128 v[216:219], v216 offset:3072
	global_load_lds_dwordx4 v[144:145], off
	v_lshl_add_u64 v[144:145], v[164:165], 0, s[10:11]
	s_add_i32 m0, s29, 0x2000
	s_nop 0
	global_load_lds_dwordx4 v[144:145], off
	s_barrier
	s_waitcnt lgkmcnt(0)
	s_setprio 1
	s_waitcnt lgkmcnt(0)
	v_mfma_f32_16x16x32_bf16 v[110:113], v[204:207], v[172:175], v[110:113]
	v_mfma_f32_16x16x32_bf16 v[106:109], v[212:215], v[172:175], v[106:109]
	v_mfma_f32_16x16x32_bf16 v[94:97], v[204:207], v[180:183], v[94:97]
	v_mfma_f32_16x16x32_bf16 v[90:93], v[212:215], v[180:183], v[90:93]
	v_mfma_f32_16x16x32_bf16 v[78:81], v[204:207], v[188:191], v[78:81]
	v_mfma_f32_16x16x32_bf16 v[74:77], v[212:215], v[188:191], v[74:77]
	v_mfma_f32_16x16x32_bf16 v[70:73], v[204:207], v[196:199], v[70:73]
	v_mfma_f32_16x16x32_bf16 v[66:69], v[212:215], v[196:199], v[66:69]
	v_mfma_f32_16x16x32_bf16 v[110:113], v[208:211], v[176:179], v[110:113]
	v_mfma_f32_16x16x32_bf16 v[106:109], v[216:219], v[176:179], v[106:109]
	v_mfma_f32_16x16x32_bf16 v[94:97], v[208:211], v[184:187], v[94:97]
	v_mfma_f32_16x16x32_bf16 v[90:93], v[216:219], v[184:187], v[90:93]
	v_mfma_f32_16x16x32_bf16 v[78:81], v[208:211], v[192:195], v[78:81]
	v_mfma_f32_16x16x32_bf16 v[74:77], v[216:219], v[192:195], v[74:77]
	v_mfma_f32_16x16x32_bf16 v[70:73], v[208:211], v[200:203], v[70:73]
	v_mfma_f32_16x16x32_bf16 v[66:69], v[216:219], v[200:203], v[66:69]
	s_setprio 0
	s_mov_b32 m0, s45
	v_lshl_add_u64 v[144:145], v[166:167], 0, s[10:11]
	s_barrier
	ds_read_b128 v[172:175], v150 offset:49152
	ds_read_b128 v[176:179], v150 offset:50176
	ds_read_b128 v[180:183], v150 offset:51200
	ds_read_b128 v[184:187], v150 offset:52224
	ds_read_b128 v[188:191], v150 offset:53248
	ds_read_b128 v[192:195], v150 offset:54272
	ds_read_b128 v[196:199], v150 offset:55296
	ds_read_b128 v[200:203], v150 offset:56320
	global_load_lds_dwordx4 v[144:145], off
	v_lshl_add_u64 v[144:145], v[220:221], 0, s[10:11]
	s_mov_b32 m0, s46
	s_nop 0
	global_load_lds_dwordx4 v[144:145], off
	s_barrier
	s_waitcnt lgkmcnt(0)
	s_setprio 1
	s_waitcnt lgkmcnt(0)
	v_mfma_f32_16x16x32_bf16 v[62:65], v[152:155], v[172:175], v[62:65]
	v_mfma_f32_16x16x32_bf16 v[58:61], v[160:163], v[172:175], v[58:61]
	v_mfma_f32_16x16x32_bf16 v[54:57], v[152:155], v[180:183], v[54:57]
	v_mfma_f32_16x16x32_bf16 v[50:53], v[160:163], v[180:183], v[50:53]
	v_mfma_f32_16x16x32_bf16 v[38:41], v[152:155], v[188:191], v[38:41]
	v_mfma_f32_16x16x32_bf16 v[34:37], v[160:163], v[188:191], v[34:37]
	v_mfma_f32_16x16x32_bf16 v[22:25], v[152:155], v[196:199], v[22:25]
	v_mfma_f32_16x16x32_bf16 v[18:21], v[160:163], v[196:199], v[18:21]
	v_mfma_f32_16x16x32_bf16 v[62:65], v[156:159], v[176:179], v[62:65]
	v_mfma_f32_16x16x32_bf16 v[58:61], v[168:171], v[176:179], v[58:61]
	v_mfma_f32_16x16x32_bf16 v[54:57], v[156:159], v[184:187], v[54:57]
	v_mfma_f32_16x16x32_bf16 v[50:53], v[168:171], v[184:187], v[50:53]
	v_mfma_f32_16x16x32_bf16 v[38:41], v[156:159], v[192:195], v[38:41]
	v_mfma_f32_16x16x32_bf16 v[34:37], v[168:171], v[192:195], v[34:37]
	v_mfma_f32_16x16x32_bf16 v[22:25], v[156:159], v[200:203], v[22:25]
	v_mfma_f32_16x16x32_bf16 v[18:21], v[168:171], v[200:203], v[18:21]
	s_setprio 0
	s_barrier
	s_add_u32 s26, s26, 0x80080
	s_addc_u32 s27, s27, 0
	s_add_i32 s28, s28, s34
	v_lshl_add_u64 v[144:145], s[26:27], 0, v[130:131]
	s_mov_b32 m0, s28
	s_nop 0
	global_load_lds_dwordx4 v[144:145], off
	v_lshl_add_u64 v[144:145], s[26:27], 0, v[132:133]
	s_add_i32 m0, s28, 0x2000
	s_nop 0
	global_load_lds_dwordx4 v[144:145], off
	s_waitcnt vmcnt(6)
	s_barrier
	s_setprio 1
	v_mfma_f32_16x16x32_bf16 v[46:49], v[204:207], v[172:175], v[46:49]
	v_mfma_f32_16x16x32_bf16 v[42:45], v[212:215], v[172:175], v[42:45]
	v_mfma_f32_16x16x32_bf16 v[30:33], v[204:207], v[180:183], v[30:33]
	v_mfma_f32_16x16x32_bf16 v[26:29], v[212:215], v[180:183], v[26:29]
	v_mfma_f32_16x16x32_bf16 v[14:17], v[204:207], v[188:191], v[14:17]
	v_mfma_f32_16x16x32_bf16 v[10:13], v[212:215], v[188:191], v[10:13]
	v_mfma_f32_16x16x32_bf16 v[6:9], v[204:207], v[196:199], v[6:9]
	v_mfma_f32_16x16x32_bf16 v[2:5], v[212:215], v[196:199], v[2:5]
	v_mfma_f32_16x16x32_bf16 v[46:49], v[208:211], v[176:179], v[46:49]
	v_mfma_f32_16x16x32_bf16 v[42:45], v[216:219], v[176:179], v[42:45]
	v_mfma_f32_16x16x32_bf16 v[30:33], v[208:211], v[184:187], v[30:33]
	v_mfma_f32_16x16x32_bf16 v[26:29], v[216:219], v[184:187], v[26:29]
	v_mfma_f32_16x16x32_bf16 v[14:17], v[208:211], v[192:195], v[14:17]
	v_mfma_f32_16x16x32_bf16 v[10:13], v[216:219], v[192:195], v[10:13]
	v_mfma_f32_16x16x32_bf16 v[6:9], v[208:211], v[200:203], v[6:9]
	v_mfma_f32_16x16x32_bf16 v[2:5], v[216:219], v[200:203], v[2:5]
	s_setprio 0
	s_add_i32 s54, s54, 2
	s_add_u32 s24, s24, 0x100
	s_addc_u32 s25, s25, 0
	s_add_u32 s52, s52, 0x100
	s_addc_u32 s53, s53, 0
	s_cmp_gt_u32 s54, 29
	s_barrier
	s_cbranch_scc0 .LBB0_377
	s_branch .Lp2_loop_exit

.Lp2_loop_exit:
	v_lshl_add_u32 v144, s18, 8, v146
	s_cmp_gt_i32 s50, 21
	s_mov_b64 s[18:19], -1
	s_cbranch_scc0 .LBB0_382
	s_andn2_b64 vcc, exec, s[12:13]
	s_cbranch_vccnz .LBB0_381
	v_or_b32_e32 v154, 16, v144
	v_ashrrev_i32_e32 v155, 31, v154
	v_lshlrev_b64 v[154:155], 6, v[154:155]
	v_lshl_add_u64 v[154:155], v[134:135], 0, v[154:155]
	global_store_dwordx4 v[154:155], v[118:121], off
	v_or_b32_e32 v154, 32, v144
	v_ashrrev_i32_e32 v155, 31, v154
	v_lshlrev_b64 v[154:155], 6, v[154:155]
	v_ashrrev_i32_e32 v145, 31, v144
	v_lshl_add_u64 v[154:155], v[134:135], 0, v[154:155]
	v_lshlrev_b64 v[152:153], 6, v[144:145]
	global_store_dwordx4 v[154:155], v[102:105], off
	v_or_b32_e32 v154, 48, v144
	v_lshl_add_u64 v[152:153], v[134:135], 0, v[152:153]
	v_ashrrev_i32_e32 v155, 31, v154
	global_store_dwordx4 v[152:153], v[126:129], off
	v_lshlrev_b64 v[154:155], 6, v[154:155]
	v_add_co_u32_e32 v152, vcc, 0x2000, v152
	v_lshl_add_u64 v[154:155], v[134:135], 0, v[154:155]
	s_nop 0
	v_addc_co_u32_e32 v153, vcc, 0, v153, vcc
	global_store_dwordx4 v[154:155], v[86:89], off
	global_store_dwordx4 v[152:153], v[62:65], off
	global_store_dwordx4 v[152:153], v[54:57], off offset:1024
	global_store_dwordx4 v[152:153], v[38:41], off offset:2048
	global_store_dwordx4 v[152:153], v[22:25], off offset:3072

.LBB0_944:
	s_ashr_i32 s29, s28, 31
	v_cmp_lt_i64_e32 vcc, s[30:31], v[154:155]
	s_lshl_b64 s[30:31], s[28:29], 20
	s_add_u32 s30, s48, s30
	s_addc_u32 s31, s49, s31
	s_and_b64 s[34:35], vcc, exec
	s_cselect_b32 s29, s31, s39
	s_cselect_b32 s63, s30, s38
	s_ashr_i32 s27, s26, 31
	s_lshl_b64 s[34:35], s[26:27], 20
	s_add_u32 s34, s54, s34
	s_addc_u32 s35, s55, s35
	s_and_b64 s[42:43], vcc, exec
	s_cselect_b32 s27, s35, s41
	s_cselect_b32 s64, s34, s40
	s_add_u32 s38, s38, 0x80080
	s_addc_u32 s39, s39, 0
	s_add_u32 s65, s40, 0x100
	s_addc_u32 s66, s41, 0
	s_mov_b32 s67, -2
	ds_read_b128 v[130:133], v167
	ds_read_b128 v[134:137], v167 offset:1024
	ds_read_b128 v[138:141], v167 offset:2048
	ds_read_b128 v[142:145], v167 offset:3072
	s_add_u32 s40, s38, 0xfff80080
	s_addc_u32 s41, s39, -1
	s_cmp_eq_u32 s67, 28
	s_cselect_b32 s43, s29, s41
	s_cselect_b32 s42, s63, s40
	s_cselect_b32 s41, s27, s66
	s_cselect_b32 s40, s64, s65
	v_lshl_add_u64 v[158:159], s[38:39], 0, v[150:151]
	s_add_i32 m0, s37, 0xc000
	ds_read_b128 v[172:175], v170
	ds_read_b128 v[176:179], v170 offset:1024
	ds_read_b128 v[180:183], v170 offset:2048
	ds_read_b128 v[184:187], v170 offset:3072
	ds_read_b128 v[188:191], v170 offset:4096
	ds_read_b128 v[192:195], v170 offset:5120
	ds_read_b128 v[196:199], v170 offset:6144
	ds_read_b128 v[200:203], v170 offset:7168
	global_load_lds_dwordx4 v[158:159], off
	v_lshl_add_u64 v[158:159], s[38:39], 0, v[152:153]
	s_add_i32 m0, s37, 0xe000
	s_nop 0
	global_load_lds_dwordx4 v[158:159], off
	s_waitcnt lgkmcnt(8)
	s_barrier
	s_waitcnt lgkmcnt(0)
	s_setprio 1
	s_waitcnt lgkmcnt(0)
	v_mfma_f32_16x16x32_bf16 v[126:129], v[130:133], v[172:175], 0
	v_mfma_f32_16x16x32_bf16 v[122:125], v[138:141], v[172:175], 0
	v_mfma_f32_16x16x32_bf16 v[114:117], v[130:133], v[180:183], 0
	v_mfma_f32_16x16x32_bf16 v[106:109], v[138:141], v[180:183], 0
	v_mfma_f32_16x16x32_bf16 v[98:101], v[130:133], v[188:191], 0
	v_mfma_f32_16x16x32_bf16 v[90:93], v[138:141], v[188:191], 0
	v_mfma_f32_16x16x32_bf16 v[82:85], v[130:133], v[196:199], 0
	v_mfma_f32_16x16x32_bf16 v[74:77], v[138:141], v[196:199], 0
	v_mfma_f32_16x16x32_bf16 v[126:129], v[134:137], v[176:179], v[126:129]
	v_mfma_f32_16x16x32_bf16 v[122:125], v[142:145], v[176:179], v[122:125]
	v_mfma_f32_16x16x32_bf16 v[114:117], v[134:137], v[184:187], v[114:117]
	v_mfma_f32_16x16x32_bf16 v[106:109], v[142:145], v[184:187], v[106:109]
	v_mfma_f32_16x16x32_bf16 v[98:101], v[134:137], v[192:195], v[98:101]
	v_mfma_f32_16x16x32_bf16 v[90:93], v[142:145], v[192:195], v[90:93]
	v_mfma_f32_16x16x32_bf16 v[82:85], v[134:137], v[200:203], v[82:85]
	v_mfma_f32_16x16x32_bf16 v[74:77], v[142:145], v[200:203], v[74:77]
	s_setprio 0
	s_barrier
	s_add_i32 s68, s59, s47
	v_lshl_add_u64 v[158:159], s[40:41], 0, v[146:147]
	s_mov_b32 m0, s68
	ds_read_b128 v[204:207], v171
	ds_read_b128 v[208:211], v171 offset:1024
	ds_read_b128 v[212:215], v171 offset:2048
	ds_read_b128 v[216:219], v171 offset:3072
	global_load_lds_dwordx4 v[158:159], off
	v_lshl_add_u64 v[168:169], s[40:41], 0, v[148:149]
	s_add_i32 m0, s68, 0x2000
	s_nop 0
	global_load_lds_dwordx4 v[168:169], off
	s_barrier
	s_waitcnt lgkmcnt(0)
	s_setprio 1
	s_waitcnt lgkmcnt(0)
	v_mfma_f32_16x16x32_bf16 v[118:121], v[204:207], v[172:175], 0
	v_mfma_f32_16x16x32_bf16 v[110:113], v[212:215], v[172:175], 0
	v_mfma_f32_16x16x32_bf16 v[102:105], v[204:207], v[180:183], 0
	v_mfma_f32_16x16x32_bf16 v[94:97], v[212:215], v[180:183], 0
	v_mfma_f32_16x16x32_bf16 v[86:89], v[204:207], v[188:191], 0
	v_mfma_f32_16x16x32_bf16 v[78:81], v[212:215], v[188:191], 0
	v_mfma_f32_16x16x32_bf16 v[70:73], v[204:207], v[196:199], 0
	v_mfma_f32_16x16x32_bf16 v[66:69], v[212:215], v[196:199], 0
	v_mfma_f32_16x16x32_bf16 v[118:121], v[208:211], v[176:179], v[118:121]
	v_mfma_f32_16x16x32_bf16 v[110:113], v[216:219], v[176:179], v[110:113]
	v_mfma_f32_16x16x32_bf16 v[102:105], v[208:211], v[184:187], v[102:105]
	v_mfma_f32_16x16x32_bf16 v[94:97], v[216:219], v[184:187], v[94:97]
	v_mfma_f32_16x16x32_bf16 v[86:89], v[208:211], v[192:195], v[86:89]
	v_mfma_f32_16x16x32_bf16 v[78:81], v[216:219], v[192:195], v[78:81]
	v_mfma_f32_16x16x32_bf16 v[70:73], v[208:211], v[200:203], v[70:73]
	v_mfma_f32_16x16x32_bf16 v[66:69], v[216:219], v[200:203], v[66:69]
	s_setprio 0
	s_mov_b32 m0, s37
	v_lshl_add_u64 v[220:221], s[42:43], 0, v[146:147]
	s_barrier
	ds_read_b128 v[172:175], v170 offset:16384
	ds_read_b128 v[176:179], v170 offset:17408
	ds_read_b128 v[180:183], v170 offset:18432
	ds_read_b128 v[184:187], v170 offset:19456
	ds_read_b128 v[188:191], v170 offset:20480
	ds_read_b128 v[192:195], v170 offset:21504
	ds_read_b128 v[196:199], v170 offset:22528
	ds_read_b128 v[200:203], v170 offset:23552
	global_load_lds_dwordx4 v[220:221], off
	v_lshl_add_u64 v[222:223], s[42:43], 0, v[148:149]
	s_mov_b32 m0, s50
	s_nop 0
	global_load_lds_dwordx4 v[222:223], off
	s_barrier
	s_waitcnt lgkmcnt(0)
	s_setprio 1
	s_waitcnt lgkmcnt(0)
	v_mfma_f32_16x16x32_bf16 v[62:65], v[130:133], v[172:175], 0
	v_mfma_f32_16x16x32_bf16 v[58:61], v[138:141], v[172:175], 0
	v_mfma_f32_16x16x32_bf16 v[54:57], v[130:133], v[180:183], 0
	v_mfma_f32_16x16x32_bf16 v[46:49], v[138:141], v[180:183], 0
	v_mfma_f32_16x16x32_bf16 v[38:41], v[130:133], v[188:191], 0
	v_mfma_f32_16x16x32_bf16 v[30:33], v[138:141], v[188:191], 0
	v_mfma_f32_16x16x32_bf16 v[22:25], v[130:133], v[196:199], 0
	v_mfma_f32_16x16x32_bf16 v[14:17], v[138:141], v[196:199], 0
	v_mfma_f32_16x16x32_bf16 v[62:65], v[134:137], v[176:179], v[62:65]
	v_mfma_f32_16x16x32_bf16 v[58:61], v[142:145], v[176:179], v[58:61]
	v_mfma_f32_16x16x32_bf16 v[54:57], v[134:137], v[184:187], v[54:57]
	v_mfma_f32_16x16x32_bf16 v[46:49], v[142:145], v[184:187], v[46:49]
	v_mfma_f32_16x16x32_bf16 v[38:41], v[134:137], v[192:195], v[38:41]
	v_mfma_f32_16x16x32_bf16 v[30:33], v[142:145], v[192:195], v[30:33]
	v_mfma_f32_16x16x32_bf16 v[22:25], v[134:137], v[200:203], v[22:25]
	v_mfma_f32_16x16x32_bf16 v[14:17], v[142:145], v[200:203], v[14:17]
	s_setprio 0
	s_barrier
	s_add_u32 s68, s40, 0x80000
	s_addc_u32 s69, s41, 0
	s_add_i32 s70, s60, s47
	v_lshl_add_u64 v[130:131], s[68:69], 0, v[146:147]
	s_mov_b32 m0, s70
	s_nop 0
	global_load_lds_dwordx4 v[130:131], off
	v_lshl_add_u64 v[130:131], s[68:69], 0, v[148:149]
	s_add_i32 m0, s70, 0x2000
	s_nop 0
	global_load_lds_dwordx4 v[130:131], off
	s_waitcnt vmcnt(6)
	s_barrier
	s_setprio 1
	v_mfma_f32_16x16x32_bf16 v[50:53], v[204:207], v[172:175], 0
	v_mfma_f32_16x16x32_bf16 v[42:45], v[212:215], v[172:175], 0
	v_mfma_f32_16x16x32_bf16 v[34:37], v[204:207], v[180:183], 0
	v_mfma_f32_16x16x32_bf16 v[26:29], v[212:215], v[180:183], 0
	v_mfma_f32_16x16x32_bf16 v[18:21], v[204:207], v[188:191], 0
	v_mfma_f32_16x16x32_bf16 v[10:13], v[212:215], v[188:191], 0
	v_mfma_f32_16x16x32_bf16 v[6:9], v[204:207], v[196:199], 0
	v_mfma_f32_16x16x32_bf16 v[2:5], v[212:215], v[196:199], 0
	v_mfma_f32_16x16x32_bf16 v[50:53], v[208:211], v[176:179], v[50:53]
	v_mfma_f32_16x16x32_bf16 v[42:45], v[216:219], v[176:179], v[42:45]
	v_mfma_f32_16x16x32_bf16 v[34:37], v[208:211], v[184:187], v[34:37]
	v_mfma_f32_16x16x32_bf16 v[26:29], v[216:219], v[184:187], v[26:29]
	v_mfma_f32_16x16x32_bf16 v[18:21], v[208:211], v[192:195], v[18:21]
	v_mfma_f32_16x16x32_bf16 v[10:13], v[216:219], v[192:195], v[10:13]
	v_mfma_f32_16x16x32_bf16 v[6:9], v[208:211], v[200:203], v[6:9]
	v_mfma_f32_16x16x32_bf16 v[2:5], v[216:219], v[200:203], v[2:5]
	s_setprio 0
	s_add_i32 s68, 0, 0x18000
	v_add_u32_e32 v142, s68, v164
	s_barrier
	ds_read_b128 v[130:133], v142
	ds_read_b128 v[134:137], v142 offset:1024
	ds_read_b128 v[138:141], v142 offset:2048
	ds_read_b128 v[142:145], v142 offset:3072
	s_add_u32 s42, s42, 0x80000
	s_addc_u32 s43, s43, 0
	s_mov_b32 m0, s51
	v_lshl_add_u64 v[204:205], s[42:43], 0, v[146:147]
	ds_read_b128 v[172:175], v170 offset:32768
	ds_read_b128 v[176:179], v170 offset:33792
	ds_read_b128 v[180:183], v170 offset:34816
	ds_read_b128 v[184:187], v170 offset:35840
	ds_read_b128 v[188:191], v170 offset:36864
	ds_read_b128 v[192:195], v170 offset:37888
	ds_read_b128 v[196:199], v170 offset:38912
	ds_read_b128 v[200:203], v170 offset:39936
	global_load_lds_dwordx4 v[204:205], off
	v_lshl_add_u64 v[204:205], s[42:43], 0, v[148:149]
	s_mov_b32 m0, s52
	s_nop 0
	global_load_lds_dwordx4 v[204:205], off
	s_waitcnt lgkmcnt(8)
	s_barrier
	s_waitcnt lgkmcnt(0)
	s_setprio 1
	s_waitcnt lgkmcnt(0)
	v_mfma_f32_16x16x32_bf16 v[126:129], v[130:133], v[172:175], v[126:129]
	v_mfma_f32_16x16x32_bf16 v[122:125], v[138:141], v[172:175], v[122:125]
	v_mfma_f32_16x16x32_bf16 v[114:117], v[130:133], v[180:183], v[114:117]
	v_mfma_f32_16x16x32_bf16 v[106:109], v[138:141], v[180:183], v[106:109]
	v_mfma_f32_16x16x32_bf16 v[98:101], v[130:133], v[188:191], v[98:101]
	v_mfma_f32_16x16x32_bf16 v[90:93], v[138:141], v[188:191], v[90:93]
	v_mfma_f32_16x16x32_bf16 v[82:85], v[130:133], v[196:199], v[82:85]
	v_mfma_f32_16x16x32_bf16 v[74:77], v[138:141], v[196:199], v[74:77]
	v_mfma_f32_16x16x32_bf16 v[126:129], v[134:137], v[176:179], v[126:129]
	v_mfma_f32_16x16x32_bf16 v[122:125], v[142:145], v[176:179], v[122:125]
	v_mfma_f32_16x16x32_bf16 v[114:117], v[134:137], v[184:187], v[114:117]
	v_mfma_f32_16x16x32_bf16 v[106:109], v[142:145], v[184:187], v[106:109]
	v_mfma_f32_16x16x32_bf16 v[98:101], v[134:137], v[192:195], v[98:101]
	v_mfma_f32_16x16x32_bf16 v[90:93], v[142:145], v[192:195], v[90:93]
	v_mfma_f32_16x16x32_bf16 v[82:85], v[134:137], v[200:203], v[82:85]
	v_mfma_f32_16x16x32_bf16 v[74:77], v[142:145], v[200:203], v[74:77]
	s_setprio 0
	s_barrier
	s_add_i32 s42, 0, 0x1c000
	s_add_i32 s43, s68, s47
	v_add_u32_e32 v166, s42, v164
	v_lshl_add_u64 v[158:159], v[158:159], 0, s[14:15]
	s_mov_b32 m0, s43
	ds_read_b128 v[204:207], v166
	ds_read_b128 v[208:211], v166 offset:1024
	ds_read_b128 v[212:215], v166 offset:2048
	ds_read_b128 v[216:219], v166 offset:3072
	global_load_lds_dwordx4 v[158:159], off
	v_lshl_add_u64 v[158:159], v[168:169], 0, s[14:15]
	s_add_i32 m0, s43, 0x2000
	s_nop 0
	global_load_lds_dwordx4 v[158:159], off
	s_barrier
	s_waitcnt lgkmcnt(0)
	s_setprio 1
	s_waitcnt lgkmcnt(0)
	v_mfma_f32_16x16x32_bf16 v[118:121], v[204:207], v[172:175], v[118:121]
	v_mfma_f32_16x16x32_bf16 v[110:113], v[212:215], v[172:175], v[110:113]
	v_mfma_f32_16x16x32_bf16 v[102:105], v[204:207], v[180:183], v[102:105]
	v_mfma_f32_16x16x32_bf16 v[94:97], v[212:215], v[180:183], v[94:97]
	v_mfma_f32_16x16x32_bf16 v[86:89], v[204:207], v[188:191], v[86:89]
	v_mfma_f32_16x16x32_bf16 v[78:81], v[212:215], v[188:191], v[78:81]
	v_mfma_f32_16x16x32_bf16 v[70:73], v[204:207], v[196:199], v[70:73]
	v_mfma_f32_16x16x32_bf16 v[66:69], v[212:215], v[196:199], v[66:69]
	v_mfma_f32_16x16x32_bf16 v[118:121], v[208:211], v[176:179], v[118:121]
	v_mfma_f32_16x16x32_bf16 v[110:113], v[216:219], v[176:179], v[110:113]
	v_mfma_f32_16x16x32_bf16 v[102:105], v[208:211], v[184:187], v[102:105]
	v_mfma_f32_16x16x32_bf16 v[94:97], v[216:219], v[184:187], v[94:97]
	v_mfma_f32_16x16x32_bf16 v[86:89], v[208:211], v[192:195], v[86:89]
	v_mfma_f32_16x16x32_bf16 v[78:81], v[216:219], v[192:195], v[78:81]
	v_mfma_f32_16x16x32_bf16 v[70:73], v[208:211], v[200:203], v[70:73]
	v_mfma_f32_16x16x32_bf16 v[66:69], v[216:219], v[200:203], v[66:69]
	s_setprio 0
	s_mov_b32 m0, s57
	v_lshl_add_u64 v[158:159], v[220:221], 0, s[14:15]
	s_barrier
	ds_read_b128 v[172:175], v170 offset:49152
	ds_read_b128 v[176:179], v170 offset:50176
	ds_read_b128 v[180:183], v170 offset:51200
	ds_read_b128 v[184:187], v170 offset:52224
	ds_read_b128 v[188:191], v170 offset:53248
	ds_read_b128 v[192:195], v170 offset:54272
	ds_read_b128 v[196:199], v170 offset:55296
	ds_read_b128 v[200:203], v170 offset:56320
	global_load_lds_dwordx4 v[158:159], off
	v_lshl_add_u64 v[158:159], v[222:223], 0, s[14:15]
	s_mov_b32 m0, s58
	s_nop 0
	global_load_lds_dwordx4 v[158:159], off
	s_barrier
	s_waitcnt lgkmcnt(0)
	s_setprio 1
	s_waitcnt lgkmcnt(0)
	v_mfma_f32_16x16x32_bf16 v[62:65], v[130:133], v[172:175], v[62:65]
	v_mfma_f32_16x16x32_bf16 v[58:61], v[138:141], v[172:175], v[58:61]
	v_mfma_f32_16x16x32_bf16 v[54:57], v[130:133], v[180:183], v[54:57]
	v_mfma_f32_16x16x32_bf16 v[46:49], v[138:141], v[180:183], v[46:49]
	v_mfma_f32_16x16x32_bf16 v[38:41], v[130:133], v[188:191], v[38:41]
	v_mfma_f32_16x16x32_bf16 v[30:33], v[138:141], v[188:191], v[30:33]
	v_mfma_f32_16x16x32_bf16 v[22:25], v[130:133], v[196:199], v[22:25]
	v_mfma_f32_16x16x32_bf16 v[14:17], v[138:141], v[196:199], v[14:17]
	v_mfma_f32_16x16x32_bf16 v[62:65], v[134:137], v[176:179], v[62:65]
	v_mfma_f32_16x16x32_bf16 v[58:61], v[142:145], v[176:179], v[58:61]
	v_mfma_f32_16x16x32_bf16 v[54:57], v[134:137], v[184:187], v[54:57]
	v_mfma_f32_16x16x32_bf16 v[46:49], v[142:145], v[184:187], v[46:49]
	v_mfma_f32_16x16x32_bf16 v[38:41], v[134:137], v[192:195], v[38:41]
	v_mfma_f32_16x16x32_bf16 v[30:33], v[142:145], v[192:195], v[30:33]
	v_mfma_f32_16x16x32_bf16 v[22:25], v[134:137], v[200:203], v[22:25]
	v_mfma_f32_16x16x32_bf16 v[14:17], v[142:145], v[200:203], v[14:17]
	s_setprio 0
	s_barrier
	s_add_u32 s40, s40, 0x80080
	s_addc_u32 s41, s41, 0
	s_add_i32 s42, s42, s47
	v_lshl_add_u64 v[130:131], s[40:41], 0, v[146:147]
	s_mov_b32 m0, s42
	s_nop 0
	global_load_lds_dwordx4 v[130:131], off
	v_lshl_add_u64 v[130:131], s[40:41], 0, v[148:149]
	s_add_i32 m0, s42, 0x2000
	s_nop 0
	global_load_lds_dwordx4 v[130:131], off
	s_waitcnt vmcnt(6)
	s_barrier
	s_setprio 1
	v_mfma_f32_16x16x32_bf16 v[50:53], v[204:207], v[172:175], v[50:53]
	v_mfma_f32_16x16x32_bf16 v[42:45], v[212:215], v[172:175], v[42:45]
	v_mfma_f32_16x16x32_bf16 v[34:37], v[204:207], v[180:183], v[34:37]
	v_mfma_f32_16x16x32_bf16 v[26:29], v[212:215], v[180:183], v[26:29]
	v_mfma_f32_16x16x32_bf16 v[18:21], v[204:207], v[188:191], v[18:21]
	v_mfma_f32_16x16x32_bf16 v[10:13], v[212:215], v[188:191], v[10:13]
	v_mfma_f32_16x16x32_bf16 v[6:9], v[204:207], v[196:199], v[6:9]
	v_mfma_f32_16x16x32_bf16 v[2:5], v[212:215], v[196:199], v[2:5]
	v_mfma_f32_16x16x32_bf16 v[50:53], v[208:211], v[176:179], v[50:53]
	v_mfma_f32_16x16x32_bf16 v[42:45], v[216:219], v[176:179], v[42:45]
	v_mfma_f32_16x16x32_bf16 v[34:37], v[208:211], v[184:187], v[34:37]
	v_mfma_f32_16x16x32_bf16 v[26:29], v[216:219], v[184:187], v[26:29]
	v_mfma_f32_16x16x32_bf16 v[18:21], v[208:211], v[192:195], v[18:21]
	v_mfma_f32_16x16x32_bf16 v[10:13], v[216:219], v[192:195], v[10:13]
	v_mfma_f32_16x16x32_bf16 v[6:9], v[208:211], v[200:203], v[6:9]
	v_mfma_f32_16x16x32_bf16 v[2:5], v[216:219], v[200:203], v[2:5]
	s_setprio 0
	s_add_i32 s67, s67, 2
	s_add_u32 s38, s38, 0x100
	s_addc_u32 s39, s39, 0
	s_add_u32 s65, s65, 0x100
	s_addc_u32 s66, s66, 0
	s_cmp_gt_u32 s67, 29
	s_barrier
	s_cbranch_scc0 .LBB0_945
	s_branch .Lp6_loop_exit

.Lp6_loop_exit:
	s_lshl_b32 s27, s36, 8
	s_add_i32 s38, s27, 0xffffc000
	s_lshr_b32 s38, s38, 4
	s_ashr_i32 s29, s36, 4
	s_or_b32 s38, s38, 4
	s_cmp_lt_i32 s36, 64
	s_cselect_b32 s29, s29, s38
	v_lshl_or_b32 v130, s62, 8, v165
	s_mul_hi_i32 s36, s29, 0xc000
	s_mul_i32 s29, s29, 0xc000
	v_add_u32_e32 v168, s27, v163
	s_add_u32 s38, s10, s29
	v_ashrrev_i32_e32 v131, 31, v130
	v_ashrrev_i32_e32 v169, 31, v168
	s_addc_u32 s39, s11, s36
	v_lshlrev_b64 v[158:159], 2, v[130:131]
	v_lshlrev_b64 v[238:239], 13, v[168:169]
	v_or_b32_e32 v188, 16, v168
	v_or_b32_e32 v204, 32, v168
	v_or_b32_e32 v168, 48, v168
	v_lshl_add_u64 v[130:131], s[38:39], 0, v[158:159]
	v_ashrrev_i32_e32 v189, 31, v188
	v_ashrrev_i32_e32 v205, 31, v204
	v_ashrrev_i32_e32 v169, 31, v168
	v_lshl_add_u64 v[132:133], v[130:131], 0, s[16:17]
	v_add_co_u32_e32 v130, vcc, s61, v130
	v_lshl_add_u64 v[236:237], s[6:7], 0, v[158:159]
	v_lshlrev_b64 v[240:241], 13, v[188:189]
	v_lshlrev_b64 v[242:243], 13, v[204:205]
	v_lshlrev_b64 v[168:169], 13, v[168:169]
	v_addc_co_u32_e32 v131, vcc, 0, v131, vcc
	v_lshl_add_u64 v[184:185], v[236:237], 0, v[238:239]
	v_lshl_add_u64 v[200:201], v[236:237], 0, v[240:241]
	v_lshl_add_u64 v[216:217], v[236:237], 0, v[242:243]
	v_lshl_add_u64 v[232:233], v[236:237], 0, v[168:169]
	global_load_dwordx4 v[138:141], v[132:133], off offset:64
	global_load_dwordx4 v[134:137], v[132:133], off offset:512
	global_load_dwordx4 v[142:145], v[130:131], off
	s_nop 0
	global_load_dwordx4 v[130:133], v[132:133], off offset:576
	s_nop 0
	global_load_dwordx4 v[172:175], v[184:185], off
	global_load_dwordx4 v[176:179], v[184:185], off offset:64
	global_load_dwordx4 v[180:183], v[184:185], off offset:512
	s_nop 0
	global_load_dwordx4 v[184:187], v[184:185], off offset:576
	s_nop 0
	global_load_dwordx4 v[188:191], v[200:201], off
	global_load_dwordx4 v[192:195], v[200:201], off offset:64
	global_load_dwordx4 v[196:199], v[200:201], off offset:512
	s_nop 0
	global_load_dwordx4 v[200:203], v[200:201], off offset:576
	s_nop 0
	global_load_dwordx4 v[204:207], v[216:217], off
	global_load_dwordx4 v[208:211], v[216:217], off offset:64
	global_load_dwordx4 v[212:215], v[216:217], off offset:512
	s_nop 0
	global_load_dwordx4 v[216:219], v[216:217], off offset:576
	s_nop 0
	global_load_dwordx4 v[220:223], v[232:233], off
	global_load_dwordx4 v[224:227], v[232:233], off offset:64
	global_load_dwordx4 v[228:231], v[232:233], off offset:512
	s_nop 0
	global_load_dwordx4 v[232:235], v[232:233], off offset:576
	v_lshl_add_u64 v[244:245], s[8:9], 0, v[238:239]
	v_lshl_add_u64 v[244:245], v[244:245], 0, v[158:159]
	s_waitcnt vmcnt(0)
	v_pk_fma_f32 v[112:113], v[112:113], v[132:133], v[186:187]
	v_pk_fma_f32 v[110:111], v[110:111], v[130:131], v[184:185]
	v_pk_fma_f32 v[120:121], v[120:121], v[136:137], v[182:183]
	v_pk_fma_f32 v[118:119], v[118:119], v[134:135], v[180:181]
	global_store_dwordx4 v[244:245], v[110:113], off offset:576
	global_store_dwordx4 v[244:245], v[118:121], off offset:512
	v_pk_fma_f32 v[96:97], v[96:97], v[132:133], v[202:203]
	v_lshl_add_u64 v[110:111], s[8:9], 0, v[240:241]
	v_lshl_add_u64 v[118:119], v[110:111], 0, v[158:159]
	v_pk_fma_f32 v[94:95], v[94:95], v[130:131], v[200:201]
	v_pk_fma_f32 v[104:105], v[104:105], v[136:137], v[198:199]
	v_pk_fma_f32 v[102:103], v[102:103], v[134:135], v[196:197]
	global_store_dwordx4 v[118:119], v[94:97], off offset:576
	global_store_dwordx4 v[118:119], v[102:105], off offset:512
	v_pk_fma_f32 v[80:81], v[80:81], v[132:133], v[218:219]
	v_lshl_add_u64 v[94:95], s[8:9], 0, v[242:243]
	v_lshl_add_u64 v[102:103], v[94:95], 0, v[158:159]
	v_pk_fma_f32 v[78:79], v[78:79], v[130:131], v[216:217]
	v_pk_fma_f32 v[88:89], v[88:89], v[136:137], v[214:215]
	v_pk_fma_f32 v[86:87], v[86:87], v[134:135], v[212:213]
	global_store_dwordx4 v[102:103], v[78:81], off offset:576
	v_pk_fma_f32 v[128:129], v[128:129], v[144:145], v[174:175]
	v_pk_fma_f32 v[126:127], v[126:127], v[142:143], v[172:173]
	v_lshl_add_u64 v[78:79], s[8:9], 0, v[168:169]
	v_pk_fma_f32 v[124:125], v[124:125], v[140:141], v[178:179]
	v_pk_fma_f32 v[122:123], v[122:123], v[138:139], v[176:177]
	v_pk_fma_f32 v[112:113], v[116:117], v[144:145], v[190:191]
	v_pk_fma_f32 v[110:111], v[114:115], v[142:143], v[188:189]
	v_pk_fma_f32 v[108:109], v[108:109], v[140:141], v[194:195]
	v_pk_fma_f32 v[106:107], v[106:107], v[138:139], v[192:193]
	v_pk_fma_f32 v[96:97], v[100:101], v[144:145], v[206:207]
	v_pk_fma_f32 v[94:95], v[98:99], v[142:143], v[204:205]
	v_pk_fma_f32 v[92:93], v[92:93], v[140:141], v[210:211]
	v_pk_fma_f32 v[90:91], v[90:91], v[138:139], v[208:209]
	global_store_dwordx4 v[102:103], v[86:89], off offset:512
	v_pk_fma_f32 v[80:81], v[84:85], v[144:145], v[222:223]
	v_pk_fma_f32 v[76:77], v[76:77], v[140:141], v[226:227]
	v_lshl_add_u64 v[86:87], v[78:79], 0, v[158:159]
	v_pk_fma_f32 v[78:79], v[82:83], v[142:143], v[220:221]
	v_pk_fma_f32 v[74:75], v[74:75], v[138:139], v[224:225]
	v_pk_fma_f32 v[72:73], v[72:73], v[136:137], v[230:231]
	v_pk_fma_f32 v[70:71], v[70:71], v[134:135], v[228:229]
	v_pk_fma_f32 v[68:69], v[68:69], v[132:133], v[234:235]
	v_pk_fma_f32 v[66:67], v[66:67], v[130:131], v[232:233]
	v_lshl_add_u64 v[168:169], v[238:239], 0, s[18:19]
	v_lshl_add_u64 v[172:173], v[238:239], 0, s[20:21]
	v_lshl_add_u64 v[174:175], v[238:239], 0, s[22:23]
	v_lshl_add_u64 v[176:177], v[238:239], 0, s[24:25]
	global_store_dwordx4 v[244:245], v[126:129], off
	global_store_dwordx4 v[244:245], v[122:125], off offset:64
	global_store_dwordx4 v[118:119], v[110:113], off
	global_store_dwordx4 v[118:119], v[106:109], off offset:64
	global_store_dwordx4 v[102:103], v[94:97], off
	global_store_dwordx4 v[102:103], v[90:93], off offset:64
	global_store_dwordx4 v[86:87], v[78:81], off
	global_store_dwordx4 v[86:87], v[74:77], off offset:64
	global_store_dwordx4 v[86:87], v[70:73], off offset:512
	global_store_dwordx4 v[86:87], v[66:69], off offset:576
	v_lshl_add_u64 v[78:79], v[236:237], 0, v[168:169]
	v_lshl_add_u64 v[94:95], v[236:237], 0, v[172:173]
	v_lshl_add_u64 v[110:111], v[236:237], 0, v[174:175]
	v_lshl_add_u64 v[126:127], v[236:237], 0, v[176:177]
	global_load_dwordx4 v[66:69], v[78:79], off
	global_load_dwordx4 v[70:73], v[78:79], off offset:64
	global_load_dwordx4 v[74:77], v[78:79], off offset:512
	s_nop 0
	global_load_dwordx4 v[78:81], v[78:79], off offset:576
	s_nop 0
	global_load_dwordx4 v[82:85], v[94:95], off
	global_load_dwordx4 v[86:89], v[94:95], off offset:64
	global_load_dwordx4 v[90:93], v[94:95], off offset:512
	s_nop 0
	global_load_dwordx4 v[94:97], v[94:95], off offset:576
	s_nop 0
	global_load_dwordx4 v[98:101], v[110:111], off
	global_load_dwordx4 v[102:105], v[110:111], off offset:64
	global_load_dwordx4 v[106:109], v[110:111], off offset:512
	s_nop 0
	global_load_dwordx4 v[110:113], v[110:111], off offset:576
	s_nop 0
	global_load_dwordx4 v[114:117], v[126:127], off
	global_load_dwordx4 v[118:121], v[126:127], off offset:64
	global_load_dwordx4 v[122:125], v[126:127], off offset:512
	s_nop 0
	global_load_dwordx4 v[126:129], v[126:127], off offset:576
	v_lshl_add_u64 v[168:169], s[8:9], 0, v[168:169]
	v_lshl_add_u64 v[168:169], v[168:169], 0, v[158:159]
	s_waitcnt vmcnt(0)
	v_pk_fma_f32 v[44:45], v[44:45], v[132:133], v[80:81]
	v_pk_fma_f32 v[42:43], v[42:43], v[130:131], v[78:79]
	v_pk_fma_f32 v[52:53], v[52:53], v[136:137], v[76:77]
	v_pk_fma_f32 v[50:51], v[50:51], v[134:135], v[74:75]
	global_store_dwordx4 v[168:169], v[42:45], off offset:576
	global_store_dwordx4 v[168:169], v[50:53], off offset:512
	v_pk_fma_f32 v[28:29], v[28:29], v[132:133], v[96:97]
	v_lshl_add_u64 v[42:43], s[8:9], 0, v[172:173]
	v_lshl_add_u64 v[50:51], v[42:43], 0, v[158:159]
	v_pk_fma_f32 v[26:27], v[26:27], v[130:131], v[94:95]
	v_pk_fma_f32 v[36:37], v[36:37], v[136:137], v[92:93]
	v_pk_fma_f32 v[34:35], v[34:35], v[134:135], v[90:91]
	global_store_dwordx4 v[50:51], v[26:29], off offset:576
	global_store_dwordx4 v[50:51], v[34:37], off offset:512
	v_pk_fma_f32 v[12:13], v[12:13], v[132:133], v[112:113]
	v_lshl_add_u64 v[26:27], s[8:9], 0, v[174:175]
	v_lshl_add_u64 v[34:35], v[26:27], 0, v[158:159]
	v_pk_fma_f32 v[10:11], v[10:11], v[130:131], v[110:111]
	v_pk_fma_f32 v[20:21], v[20:21], v[136:137], v[108:109]
	v_pk_fma_f32 v[18:19], v[18:19], v[134:135], v[106:107]
	global_store_dwordx4 v[34:35], v[10:13], off offset:576
	v_pk_fma_f32 v[44:45], v[56:57], v[144:145], v[84:85]
	v_pk_fma_f32 v[42:43], v[54:55], v[142:143], v[82:83]
	v_lshl_add_u64 v[10:11], s[8:9], 0, v[176:177]
	v_pk_fma_f32 v[28:29], v[40:41], v[144:145], v[100:101]
	v_pk_fma_f32 v[26:27], v[38:39], v[142:143], v[98:99]
	global_store_dwordx4 v[34:35], v[18:21], off offset:512
	v_pk_fma_f32 v[12:13], v[24:25], v[144:145], v[116:117]
	v_pk_fma_f32 v[64:65], v[64:65], v[144:145], v[68:69]
	v_lshl_add_u64 v[18:19], v[10:11], 0, v[158:159]
	v_pk_fma_f32 v[10:11], v[22:23], v[142:143], v[114:115]
	v_pk_fma_f32 v[62:63], v[62:63], v[142:143], v[66:67]
	v_pk_fma_f32 v[60:61], v[60:61], v[140:141], v[72:73]
	v_pk_fma_f32 v[58:59], v[58:59], v[138:139], v[70:71]
	global_store_dwordx4 v[50:51], v[42:45], off
	global_store_dwordx4 v[34:35], v[26:29], off
	global_store_dwordx4 v[18:19], v[10:13], off
	v_pk_fma_f32 v[44:45], v[48:49], v[140:141], v[88:89]
	v_pk_fma_f32 v[42:43], v[46:47], v[138:139], v[86:87]
	v_pk_fma_f32 v[28:29], v[32:33], v[140:141], v[104:105]
	v_pk_fma_f32 v[26:27], v[30:31], v[138:139], v[102:103]
	v_pk_fma_f32 v[12:13], v[16:17], v[140:141], v[120:121]
	v_pk_fma_f32 v[10:11], v[14:15], v[138:139], v[118:119]
	v_pk_fma_f32 v[8:9], v[8:9], v[136:137], v[124:125]
	v_pk_fma_f32 v[6:7], v[6:7], v[134:135], v[122:123]
	v_pk_fma_f32 v[4:5], v[4:5], v[132:133], v[128:129]
	v_pk_fma_f32 v[2:3], v[2:3], v[130:131], v[126:127]
	s_and_b64 vcc, exec, s[4:5]
	s_mov_b32 s62, s26
	s_mov_b32 s36, s28
	s_mov_b64 s[40:41], s[34:35]
	s_mov_b64 s[38:39], s[30:31]
	global_store_dwordx4 v[168:169], v[62:65], off
	global_store_dwordx4 v[168:169], v[58:61], off offset:64
	global_store_dwordx4 v[50:51], v[42:45], off offset:64
	global_store_dwordx4 v[34:35], v[26:29], off offset:64
	global_store_dwordx4 v[18:19], v[10:13], off offset:64
	global_store_dwordx4 v[18:19], v[6:9], off offset:512
	global_store_dwordx4 v[18:19], v[2:5], off offset:576
	s_cbranch_vccz .LBB0_938
	s_waitcnt vmcnt(0)
	s_cmpk_gt_u32 s45, 0xff
	s_cbranch_scc1 .LBB0_949
	s_barrier

.LBB0_1097:
	s_ashr_i32 s41, s40, 31
	v_cmp_lt_i64_e32 vcc, s[42:43], v[172:173]
	s_lshl_b64 s[42:43], s[40:41], 20
	s_add_u32 s42, s57, s42
	s_addc_u32 s43, s58, s43
	s_add_u32 s42, s42, s89
	s_addc_u32 s43, s43, 0
	s_and_b64 s[44:45], vcc, exec
	s_cselect_b32 s41, s43, s49
	s_cselect_b32 s47, s42, s48
	s_ashr_i32 s39, s38, 31
	s_lshl_b64 s[44:45], s[38:39], 20
	s_add_u32 s44, s18, s44
	s_addc_u32 s45, s19, s45
	s_add_u32 s44, s44, s89
	s_addc_u32 s45, s45, 0
	s_and_b64 s[52:53], vcc, exec
	s_cselect_b32 s39, s45, s51
	s_cselect_b32 s73, s44, s50
	s_add_u32 s48, s48, 0x80080
	s_addc_u32 s49, s49, 0
	s_add_u32 s74, s50, 0x100
	s_addc_u32 s75, s51, 0
	s_mov_b32 s80, -2
	s_cmpk_gt_u32 s56, 0xfff
	s_cbranch_scc1 .Lp8_nostage
	s_lshr_b32 s84, s56, 10
	s_mul_i32 s85, s84, 0xb000
	s_add_u32 s94, s12, s85
	s_addc_u32 s95, s13, 0
	s_cmp_eq_u32 s84, 3
	s_cselect_b32 s94, s14, s94
	s_cselect_b32 s95, s15, s95
	s_lshl_b32 s85, s46, 9
	s_add_u32 s94, s94, s85
	s_addc_u32 s95, s95, 0
	s_add_i32 m0, s86, s56
	s_nop 0
	global_load_lds_dwordx4 v245, s[94:95]
.Lp8_nostage:
	ds_read_b128 v[130:133], v240
	ds_read_b128 v[134:137], v240 offset:1024
	ds_read_b128 v[138:141], v240 offset:2048
	ds_read_b128 v[142:145], v240 offset:3072
	s_add_u32 s50, s48, 0xfff80080
	s_addc_u32 s51, s49, -1
	s_cmp_eq_u32 s80, s87
	s_cselect_b32 s53, s41, s51
	s_cselect_b32 s52, s47, s50
	s_cselect_b32 s51, s39, s75
	s_cselect_b32 s50, s73, s74
	v_lshl_add_u64 v[168:169], s[48:49], 0, v[166:167]
	s_add_i32 m0, s21, 0xc000
	ds_read_b128 v[146:149], v241
	ds_read_b128 v[150:153], v241 offset:1024
	ds_read_b128 v[154:157], v241 offset:2048
	ds_read_b128 v[158:161], v241 offset:3072
	ds_read_b128 v[176:179], v241 offset:4096
	ds_read_b128 v[180:183], v241 offset:5120
	ds_read_b128 v[184:187], v241 offset:6144
	ds_read_b128 v[188:191], v241 offset:7168
	global_load_lds_dwordx4 v[168:169], off
	v_lshl_add_u64 v[168:169], s[48:49], 0, v[170:171]
	s_add_i32 m0, s21, 0xe000
	s_nop 0
	global_load_lds_dwordx4 v[168:169], off
	s_waitcnt lgkmcnt(8)
	s_barrier
	s_waitcnt lgkmcnt(0)
	s_setprio 1
	s_waitcnt lgkmcnt(0)
	v_mfma_f32_16x16x32_bf16 v[126:129], v[130:133], v[146:149], 0
	v_mfma_f32_16x16x32_bf16 v[122:125], v[138:141], v[146:149], 0
	v_mfma_f32_16x16x32_bf16 v[118:121], v[130:133], v[154:157], 0
	v_mfma_f32_16x16x32_bf16 v[114:117], v[138:141], v[154:157], 0
	v_mfma_f32_16x16x32_bf16 v[106:109], v[130:133], v[176:179], 0
	v_mfma_f32_16x16x32_bf16 v[98:101], v[138:141], v[176:179], 0
	v_mfma_f32_16x16x32_bf16 v[90:93], v[130:133], v[184:187], 0
	v_mfma_f32_16x16x32_bf16 v[82:85], v[138:141], v[184:187], 0
	v_mfma_f32_16x16x32_bf16 v[126:129], v[134:137], v[150:153], v[126:129]
	v_mfma_f32_16x16x32_bf16 v[122:125], v[142:145], v[150:153], v[122:125]
	v_mfma_f32_16x16x32_bf16 v[118:121], v[134:137], v[158:161], v[118:121]
	v_mfma_f32_16x16x32_bf16 v[114:117], v[142:145], v[158:161], v[114:117]
	v_mfma_f32_16x16x32_bf16 v[106:109], v[134:137], v[180:183], v[106:109]
	v_mfma_f32_16x16x32_bf16 v[98:101], v[142:145], v[180:183], v[98:101]
	v_mfma_f32_16x16x32_bf16 v[90:93], v[134:137], v[188:191], v[90:93]
	v_mfma_f32_16x16x32_bf16 v[82:85], v[142:145], v[188:191], v[82:85]
	s_setprio 0
	s_barrier
	s_add_i32 s81, s68, s56
	v_lshl_add_u64 v[168:169], s[50:51], 0, v[162:163]
	s_mov_b32 m0, s81
	ds_read_b128 v[192:195], v242
	ds_read_b128 v[196:199], v242 offset:1024
	ds_read_b128 v[200:203], v242 offset:2048
	ds_read_b128 v[204:207], v242 offset:3072
	global_load_lds_dwordx4 v[168:169], off
	v_lshl_add_u64 v[208:209], s[50:51], 0, v[164:165]
	s_add_i32 m0, s81, 0x2000
	s_nop 0
	global_load_lds_dwordx4 v[208:209], off
	s_barrier
	s_waitcnt lgkmcnt(0)
	s_setprio 1
	s_waitcnt lgkmcnt(0)
	v_mfma_f32_16x16x32_bf16 v[110:113], v[192:195], v[146:149], 0
	v_mfma_f32_16x16x32_bf16 v[102:105], v[200:203], v[146:149], 0
	v_mfma_f32_16x16x32_bf16 v[94:97], v[192:195], v[154:157], 0
	v_mfma_f32_16x16x32_bf16 v[86:89], v[200:203], v[154:157], 0
	v_mfma_f32_16x16x32_bf16 v[78:81], v[192:195], v[176:179], 0
	v_mfma_f32_16x16x32_bf16 v[74:77], v[200:203], v[176:179], 0
	v_mfma_f32_16x16x32_bf16 v[70:73], v[192:195], v[184:187], 0
	v_mfma_f32_16x16x32_bf16 v[66:69], v[200:203], v[184:187], 0
	v_mfma_f32_16x16x32_bf16 v[110:113], v[196:199], v[150:153], v[110:113]
	v_mfma_f32_16x16x32_bf16 v[102:105], v[204:207], v[150:153], v[102:105]
	v_mfma_f32_16x16x32_bf16 v[94:97], v[196:199], v[158:161], v[94:97]
	v_mfma_f32_16x16x32_bf16 v[86:89], v[204:207], v[158:161], v[86:89]
	v_mfma_f32_16x16x32_bf16 v[78:81], v[196:199], v[180:183], v[78:81]
	v_mfma_f32_16x16x32_bf16 v[74:77], v[204:207], v[180:183], v[74:77]
	v_mfma_f32_16x16x32_bf16 v[70:73], v[196:199], v[188:191], v[70:73]
	v_mfma_f32_16x16x32_bf16 v[66:69], v[204:207], v[188:191], v[66:69]
	s_setprio 0
	s_mov_b32 m0, s21
	v_lshl_add_u64 v[210:211], s[52:53], 0, v[162:163]
	s_barrier
	ds_read_b128 v[146:149], v241 offset:16384
	ds_read_b128 v[150:153], v241 offset:17408
	ds_read_b128 v[154:157], v241 offset:18432
	ds_read_b128 v[158:161], v241 offset:19456
	ds_read_b128 v[176:179], v241 offset:20480
	ds_read_b128 v[180:183], v241 offset:21504
	ds_read_b128 v[184:187], v241 offset:22528
	ds_read_b128 v[188:191], v241 offset:23552
	global_load_lds_dwordx4 v[210:211], off
	v_lshl_add_u64 v[212:213], s[52:53], 0, v[164:165]
	s_mov_b32 m0, s59
	s_nop 0
	global_load_lds_dwordx4 v[212:213], off
	s_barrier
	s_waitcnt lgkmcnt(0)
	s_setprio 1
	s_waitcnt lgkmcnt(0)
	v_mfma_f32_16x16x32_bf16 v[62:65], v[130:133], v[146:149], 0
	v_mfma_f32_16x16x32_bf16 v[58:61], v[138:141], v[146:149], 0
	v_mfma_f32_16x16x32_bf16 v[54:57], v[130:133], v[154:157], 0
	v_mfma_f32_16x16x32_bf16 v[50:53], v[138:141], v[154:157], 0
	v_mfma_f32_16x16x32_bf16 v[42:45], v[130:133], v[176:179], 0
	v_mfma_f32_16x16x32_bf16 v[34:37], v[138:141], v[176:179], 0
	v_mfma_f32_16x16x32_bf16 v[26:29], v[130:133], v[184:187], 0
	v_mfma_f32_16x16x32_bf16 v[18:21], v[138:141], v[184:187], 0
	v_mfma_f32_16x16x32_bf16 v[62:65], v[134:137], v[150:153], v[62:65]
	v_mfma_f32_16x16x32_bf16 v[58:61], v[142:145], v[150:153], v[58:61]
	v_mfma_f32_16x16x32_bf16 v[54:57], v[134:137], v[158:161], v[54:57]
	v_mfma_f32_16x16x32_bf16 v[50:53], v[142:145], v[158:161], v[50:53]
	v_mfma_f32_16x16x32_bf16 v[42:45], v[134:137], v[180:183], v[42:45]
	v_mfma_f32_16x16x32_bf16 v[34:37], v[142:145], v[180:183], v[34:37]
	v_mfma_f32_16x16x32_bf16 v[26:29], v[134:137], v[188:191], v[26:29]
	v_mfma_f32_16x16x32_bf16 v[18:21], v[142:145], v[188:191], v[18:21]
	s_setprio 0
	s_barrier
	s_add_u32 s82, s50, 0x80000
	s_addc_u32 s83, s51, 0
	s_add_i32 s81, s69, s56
	v_lshl_add_u64 v[130:131], s[82:83], 0, v[162:163]
	s_mov_b32 m0, s81
	s_nop 0
	global_load_lds_dwordx4 v[130:131], off
	v_lshl_add_u64 v[130:131], s[82:83], 0, v[164:165]
	s_add_i32 m0, s81, 0x2000
	s_nop 0
	global_load_lds_dwordx4 v[130:131], off
	s_waitcnt vmcnt(6)
	s_barrier
	s_setprio 1
	v_mfma_f32_16x16x32_bf16 v[46:49], v[192:195], v[146:149], 0
	v_mfma_f32_16x16x32_bf16 v[38:41], v[200:203], v[146:149], 0
	v_mfma_f32_16x16x32_bf16 v[30:33], v[192:195], v[154:157], 0
	v_mfma_f32_16x16x32_bf16 v[22:25], v[200:203], v[154:157], 0
	v_mfma_f32_16x16x32_bf16 v[14:17], v[192:195], v[176:179], 0
	v_mfma_f32_16x16x32_bf16 v[10:13], v[200:203], v[176:179], 0
	v_mfma_f32_16x16x32_bf16 v[6:9], v[192:195], v[184:187], 0
	v_mfma_f32_16x16x32_bf16 v[2:5], v[200:203], v[184:187], 0
	v_mfma_f32_16x16x32_bf16 v[46:49], v[196:199], v[150:153], v[46:49]
	v_mfma_f32_16x16x32_bf16 v[38:41], v[204:207], v[150:153], v[38:41]
	v_mfma_f32_16x16x32_bf16 v[30:33], v[196:199], v[158:161], v[30:33]
	v_mfma_f32_16x16x32_bf16 v[22:25], v[204:207], v[158:161], v[22:25]
	v_mfma_f32_16x16x32_bf16 v[14:17], v[196:199], v[180:183], v[14:17]
	v_mfma_f32_16x16x32_bf16 v[10:13], v[204:207], v[180:183], v[10:13]
	v_mfma_f32_16x16x32_bf16 v[6:9], v[196:199], v[188:191], v[6:9]
	v_mfma_f32_16x16x32_bf16 v[2:5], v[204:207], v[188:191], v[2:5]
	s_setprio 0
	s_add_i32 s81, 0, 0x18000
	v_add_u32_e32 v142, s81, v236
	s_barrier
	ds_read_b128 v[130:133], v142
	ds_read_b128 v[134:137], v142 offset:1024
	ds_read_b128 v[138:141], v142 offset:2048
	ds_read_b128 v[142:145], v142 offset:3072
	s_add_u32 s52, s52, 0x80000
	s_addc_u32 s53, s53, 0
	s_mov_b32 m0, s60
	v_lshl_add_u64 v[192:193], s[52:53], 0, v[162:163]
	ds_read_b128 v[146:149], v241 offset:32768
	ds_read_b128 v[150:153], v241 offset:33792
	ds_read_b128 v[154:157], v241 offset:34816
	ds_read_b128 v[158:161], v241 offset:35840
	ds_read_b128 v[176:179], v241 offset:36864
	ds_read_b128 v[180:183], v241 offset:37888
	ds_read_b128 v[184:187], v241 offset:38912
	ds_read_b128 v[188:191], v241 offset:39936
	global_load_lds_dwordx4 v[192:193], off
	v_lshl_add_u64 v[192:193], s[52:53], 0, v[164:165]
	s_mov_b32 m0, s61
	s_nop 0
	global_load_lds_dwordx4 v[192:193], off
	s_waitcnt lgkmcnt(8)
	s_barrier
	s_waitcnt lgkmcnt(0)
	s_setprio 1
	s_waitcnt lgkmcnt(0)
	v_mfma_f32_16x16x32_bf16 v[126:129], v[130:133], v[146:149], v[126:129]
	v_mfma_f32_16x16x32_bf16 v[122:125], v[138:141], v[146:149], v[122:125]
	v_mfma_f32_16x16x32_bf16 v[118:121], v[130:133], v[154:157], v[118:121]
	v_mfma_f32_16x16x32_bf16 v[114:117], v[138:141], v[154:157], v[114:117]
	v_mfma_f32_16x16x32_bf16 v[106:109], v[130:133], v[176:179], v[106:109]
	v_mfma_f32_16x16x32_bf16 v[98:101], v[138:141], v[176:179], v[98:101]
	v_mfma_f32_16x16x32_bf16 v[90:93], v[130:133], v[184:187], v[90:93]
	v_mfma_f32_16x16x32_bf16 v[82:85], v[138:141], v[184:187], v[82:85]
	v_mfma_f32_16x16x32_bf16 v[126:129], v[134:137], v[150:153], v[126:129]
	v_mfma_f32_16x16x32_bf16 v[122:125], v[142:145], v[150:153], v[122:125]
	v_mfma_f32_16x16x32_bf16 v[118:121], v[134:137], v[158:161], v[118:121]
	v_mfma_f32_16x16x32_bf16 v[114:117], v[142:145], v[158:161], v[114:117]
	v_mfma_f32_16x16x32_bf16 v[106:109], v[134:137], v[180:183], v[106:109]
	v_mfma_f32_16x16x32_bf16 v[98:101], v[142:145], v[180:183], v[98:101]
	v_mfma_f32_16x16x32_bf16 v[90:93], v[134:137], v[188:191], v[90:93]
	v_mfma_f32_16x16x32_bf16 v[82:85], v[142:145], v[188:191], v[82:85]
	s_setprio 0
	s_barrier
	s_add_i32 s52, 0, 0x1c000
	s_add_i32 s53, s81, s56
	v_add_u32_e32 v204, s52, v236
	v_lshl_add_u64 v[168:169], v[168:169], 0, s[36:37]
	s_mov_b32 m0, s53
	ds_read_b128 v[192:195], v204
	ds_read_b128 v[196:199], v204 offset:1024
	ds_read_b128 v[200:203], v204 offset:2048
	ds_read_b128 v[204:207], v204 offset:3072
	global_load_lds_dwordx4 v[168:169], off
	v_lshl_add_u64 v[168:169], v[208:209], 0, s[36:37]
	s_add_i32 m0, s53, 0x2000
	s_nop 0
	global_load_lds_dwordx4 v[168:169], off
	s_barrier
	s_waitcnt lgkmcnt(0)
	s_setprio 1
	s_waitcnt lgkmcnt(0)
	v_mfma_f32_16x16x32_bf16 v[110:113], v[192:195], v[146:149], v[110:113]
	v_mfma_f32_16x16x32_bf16 v[102:105], v[200:203], v[146:149], v[102:105]
	v_mfma_f32_16x16x32_bf16 v[94:97], v[192:195], v[154:157], v[94:97]
	v_mfma_f32_16x16x32_bf16 v[86:89], v[200:203], v[154:157], v[86:89]
	v_mfma_f32_16x16x32_bf16 v[78:81], v[192:195], v[176:179], v[78:81]
	v_mfma_f32_16x16x32_bf16 v[74:77], v[200:203], v[176:179], v[74:77]
	v_mfma_f32_16x16x32_bf16 v[70:73], v[192:195], v[184:187], v[70:73]
	v_mfma_f32_16x16x32_bf16 v[66:69], v[200:203], v[184:187], v[66:69]
	v_mfma_f32_16x16x32_bf16 v[110:113], v[196:199], v[150:153], v[110:113]
	v_mfma_f32_16x16x32_bf16 v[102:105], v[204:207], v[150:153], v[102:105]
	v_mfma_f32_16x16x32_bf16 v[94:97], v[196:199], v[158:161], v[94:97]
	v_mfma_f32_16x16x32_bf16 v[86:89], v[204:207], v[158:161], v[86:89]
	v_mfma_f32_16x16x32_bf16 v[78:81], v[196:199], v[180:183], v[78:81]
	v_mfma_f32_16x16x32_bf16 v[74:77], v[204:207], v[180:183], v[74:77]
	v_mfma_f32_16x16x32_bf16 v[70:73], v[196:199], v[188:191], v[70:73]
	v_mfma_f32_16x16x32_bf16 v[66:69], v[204:207], v[188:191], v[66:69]
	s_setprio 0
	s_mov_b32 m0, s64
	v_lshl_add_u64 v[168:169], v[210:211], 0, s[36:37]
	s_barrier
	ds_read_b128 v[146:149], v241 offset:49152
	ds_read_b128 v[150:153], v241 offset:50176
	ds_read_b128 v[154:157], v241 offset:51200
	ds_read_b128 v[158:161], v241 offset:52224
	ds_read_b128 v[176:179], v241 offset:53248
	ds_read_b128 v[180:183], v241 offset:54272
	ds_read_b128 v[184:187], v241 offset:55296
	ds_read_b128 v[188:191], v241 offset:56320
	global_load_lds_dwordx4 v[168:169], off
	v_lshl_add_u64 v[168:169], v[212:213], 0, s[36:37]
	s_mov_b32 m0, s65
	s_nop 0
	global_load_lds_dwordx4 v[168:169], off
	s_barrier
	s_waitcnt lgkmcnt(0)
	s_setprio 1
	s_waitcnt lgkmcnt(0)
	v_mfma_f32_16x16x32_bf16 v[62:65], v[130:133], v[146:149], v[62:65]
	v_mfma_f32_16x16x32_bf16 v[58:61], v[138:141], v[146:149], v[58:61]
	v_mfma_f32_16x16x32_bf16 v[54:57], v[130:133], v[154:157], v[54:57]
	v_mfma_f32_16x16x32_bf16 v[50:53], v[138:141], v[154:157], v[50:53]
	v_mfma_f32_16x16x32_bf16 v[42:45], v[130:133], v[176:179], v[42:45]
	v_mfma_f32_16x16x32_bf16 v[34:37], v[138:141], v[176:179], v[34:37]
	v_mfma_f32_16x16x32_bf16 v[26:29], v[130:133], v[184:187], v[26:29]
	v_mfma_f32_16x16x32_bf16 v[18:21], v[138:141], v[184:187], v[18:21]
	v_mfma_f32_16x16x32_bf16 v[62:65], v[134:137], v[150:153], v[62:65]
	v_mfma_f32_16x16x32_bf16 v[58:61], v[142:145], v[150:153], v[58:61]
	v_mfma_f32_16x16x32_bf16 v[54:57], v[134:137], v[158:161], v[54:57]
	v_mfma_f32_16x16x32_bf16 v[50:53], v[142:145], v[158:161], v[50:53]
	v_mfma_f32_16x16x32_bf16 v[42:45], v[134:137], v[180:183], v[42:45]
	v_mfma_f32_16x16x32_bf16 v[34:37], v[142:145], v[180:183], v[34:37]
	v_mfma_f32_16x16x32_bf16 v[26:29], v[134:137], v[188:191], v[26:29]
	v_mfma_f32_16x16x32_bf16 v[18:21], v[142:145], v[188:191], v[18:21]
	s_setprio 0
	s_barrier
	s_add_u32 s50, s50, 0x80080
	s_addc_u32 s51, s51, 0
	s_add_i32 s52, s52, s56
	v_lshl_add_u64 v[130:131], s[50:51], 0, v[162:163]
	s_mov_b32 m0, s52
	s_nop 0
	global_load_lds_dwordx4 v[130:131], off
	v_lshl_add_u64 v[130:131], s[50:51], 0, v[164:165]
	s_add_i32 m0, s52, 0x2000
	s_nop 0
	global_load_lds_dwordx4 v[130:131], off
	s_waitcnt vmcnt(6)
	s_barrier
	s_setprio 1
	v_mfma_f32_16x16x32_bf16 v[46:49], v[192:195], v[146:149], v[46:49]
	v_mfma_f32_16x16x32_bf16 v[38:41], v[200:203], v[146:149], v[38:41]
	v_mfma_f32_16x16x32_bf16 v[30:33], v[192:195], v[154:157], v[30:33]
	v_mfma_f32_16x16x32_bf16 v[22:25], v[200:203], v[154:157], v[22:25]
	v_mfma_f32_16x16x32_bf16 v[14:17], v[192:195], v[176:179], v[14:17]
	v_mfma_f32_16x16x32_bf16 v[10:13], v[200:203], v[176:179], v[10:13]
	v_mfma_f32_16x16x32_bf16 v[6:9], v[192:195], v[184:187], v[6:9]
	v_mfma_f32_16x16x32_bf16 v[2:5], v[200:203], v[184:187], v[2:5]
	v_mfma_f32_16x16x32_bf16 v[46:49], v[196:199], v[150:153], v[46:49]
	v_mfma_f32_16x16x32_bf16 v[38:41], v[204:207], v[150:153], v[38:41]
	v_mfma_f32_16x16x32_bf16 v[30:33], v[196:199], v[158:161], v[30:33]
	v_mfma_f32_16x16x32_bf16 v[22:25], v[204:207], v[158:161], v[22:25]
	v_mfma_f32_16x16x32_bf16 v[14:17], v[196:199], v[180:183], v[14:17]
	v_mfma_f32_16x16x32_bf16 v[10:13], v[204:207], v[180:183], v[10:13]
	v_mfma_f32_16x16x32_bf16 v[6:9], v[196:199], v[188:191], v[6:9]
	v_mfma_f32_16x16x32_bf16 v[2:5], v[204:207], v[188:191], v[2:5]
	s_setprio 0
	s_add_i32 s80, s80, 2
	s_add_u32 s48, s48, 0x100
	s_addc_u32 s49, s49, 0
	s_add_u32 s74, s74, 0x100
	s_addc_u32 s75, s75, 0
	s_cmp_gt_u32 s80, s87
	s_barrier
	s_cbranch_scc0 .LBB0_1098
	s_branch .Lp8_loop_exit

.Lp8_loop_exit:
	v_lshl_or_b32 v176, s46, 7, v239
	s_cmp_gt_i32 s20, 63
	v_ashrrev_i32_e32 v177, 31, v176
	s_mov_b64 s[46:47], -1
	s_cbranch_scc1 .LBB0_1141
	v_add_u32_e32 v251, s86, v250
	ds_read_b128 v[130:133], v251
	ds_read_b128 v[146:149], v251 offset:512
	ds_read_b128 v[134:137], v251 offset:1024
	ds_read_b128 v[150:153], v251 offset:1536
	ds_read_b128 v[138:141], v251 offset:2048
	ds_read_b128 v[154:157], v251 offset:2560
	ds_read_b128 v[142:145], v251 offset:3072
	ds_read_b128 v[158:161], v251 offset:3584
	ds_read_b128 v[178:181], v251 offset:64
	ds_read_b128 v[194:197], v251 offset:576
	ds_read_b128 v[182:185], v251 offset:1088
	ds_read_b128 v[198:201], v251 offset:1600
	ds_read_b128 v[186:189], v251 offset:2112
	ds_read_b128 v[202:205], v251 offset:2624
	ds_read_b128 v[190:193], v251 offset:3136
	ds_read_b128 v[206:209], v251 offset:3648
	s_lshl_b32 s39, s20, 2
	s_add_i32 s39, s39, s55
	s_mov_b32 s96, 0x2c000
	s_mov_b32 s97, 0
	s_mov_b32 s48, 0xbfb8aa3b
	v_mov_b32_e32 v211, 0
	v_mov_b32_e32 v213, 0
	v_mov_b32_e32 v215, 0
	v_mov_b32_e32 v217, 0
	v_mov_b32_e32 v219, 0
	v_lshlrev_b32_e32 v243, 2, v176
	v_lshlrev_b32_e32 v244, 1, v176
	v_mul_u32_u24_e32 v210, 0x2c00, v1
	v_add_u32_e32 v210, v210, v244
	v_mul_u32_u24_e32 v212, 0xb000, v1
	v_add_u32_e32 v212, v212, v243
	v_add_u32_e32 v214, 0x5800, v212
	v_mul_i32_i24_e32 v216, 0xb000, v237
	v_add_u32_e32 v216, v216, v243
	v_add_u32_e32 v218, 0x5800, v216
	s_waitcnt lgkmcnt(0)
	s_add_i32 s84, s39, 0
	s_mul_i32 s85, s84, 0xb0000
	s_add_u32 s94, s22, s85
	s_addc_u32 s95, s23, 0
	v_lshl_add_u64 v[220:221], s[94:95], 0, v[210:211]
	s_mul_i32 s85, s84, 0x16000
	s_add_u32 s94, s24, s85
	s_addc_u32 s95, s25, 0
	v_lshl_add_u64 v[222:223], s[94:95], 0, v[212:213]
	v_lshl_add_u64 v[246:247], s[94:95], 0, v[214:215]
	s_and_saveexec_b64 s[46:47], s[4:5]
	global_store_dwordx4 v[222:223], v[126:129], off
	global_store_dwordx4 v[246:247], v[110:113], off
	s_or_b64 exec, exec, s[46:47]
	v_pk_fma_f32 v[224:225], v[126:127], v[138:139], v[142:143]
	v_pk_fma_f32 v[226:227], v[128:129], v[140:141], v[144:145]
	v_pk_fma_f32 v[228:229], v[110:111], v[154:155], v[158:159]
	v_pk_fma_f32 v[230:231], v[112:113], v[156:157], v[160:161]
	v_fmac_f32_dpp v224, v126, v134 row_shr:1 row_mask:0xf bank_mask:0xf bound_ctrl:1
	v_fmac_f32_dpp v225, v127, v135 row_shr:1 row_mask:0xf bank_mask:0xf bound_ctrl:1
	v_fmac_f32_dpp v226, v128, v136 row_shr:1 row_mask:0xf bank_mask:0xf bound_ctrl:1
	v_fmac_f32_dpp v227, v129, v137 row_shr:1 row_mask:0xf bank_mask:0xf bound_ctrl:1
	v_fmac_f32_dpp v228, v110, v150 row_shr:1 row_mask:0xf bank_mask:0xf bound_ctrl:1
	v_fmac_f32_dpp v229, v111, v151 row_shr:1 row_mask:0xf bank_mask:0xf bound_ctrl:1
	v_fmac_f32_dpp v230, v112, v152 row_shr:1 row_mask:0xf bank_mask:0xf bound_ctrl:1
	v_fmac_f32_dpp v231, v113, v153 row_shr:1 row_mask:0xf bank_mask:0xf bound_ctrl:1
	v_fmac_f32_dpp v224, v126, v130 row_shr:2 row_mask:0xf bank_mask:0xf bound_ctrl:1
	v_fmac_f32_dpp v225, v127, v131 row_shr:2 row_mask:0xf bank_mask:0xf bound_ctrl:1
	v_fmac_f32_dpp v226, v128, v132 row_shr:2 row_mask:0xf bank_mask:0xf bound_ctrl:1
	v_fmac_f32_dpp v227, v129, v133 row_shr:2 row_mask:0xf bank_mask:0xf bound_ctrl:1
	v_fmac_f32_dpp v228, v110, v146 row_shr:2 row_mask:0xf bank_mask:0xf bound_ctrl:1
	v_fmac_f32_dpp v229, v111, v147 row_shr:2 row_mask:0xf bank_mask:0xf bound_ctrl:1
	v_fmac_f32_dpp v230, v112, v148 row_shr:2 row_mask:0xf bank_mask:0xf bound_ctrl:1
	v_fmac_f32_dpp v231, v113, v149 row_shr:2 row_mask:0xf bank_mask:0xf bound_ctrl:1
	v_pk_mul_f32 v[232:233], v[224:225], s[48:49] op_sel_hi:[1,0]
	v_pk_mul_f32 v[234:235], v[226:227], s[48:49] op_sel_hi:[1,0]
	v_exp_f32_e32 v232, v232
	v_exp_f32_e32 v233, v233
	v_exp_f32_e32 v234, v234
	v_exp_f32_e32 v235, v235
	s_nop 0
	v_pk_add_f32 v[232:233], v[232:233], 1.0 op_sel_hi:[1,0]
	v_pk_add_f32 v[234:235], v[234:235], 1.0 op_sel_hi:[1,0]
	v_rcp_f32_e32 v232, v232
	v_rcp_f32_e32 v233, v233
	v_rcp_f32_e32 v234, v234
	v_rcp_f32_e32 v235, v235
	s_nop 0
	v_pk_mul_f32 v[224:225], v[224:225], v[232:233]
	v_pk_mul_f32 v[226:227], v[226:227], v[234:235]
	v_pk_mul_f32 v[224:225], v[224:225], v[228:229]
	v_pk_mul_f32 v[226:227], v[226:227], v[230:231]
	s_nop 0
	v_cvt_pk_bf16_f32 v168, v224, v225
	v_cvt_pk_bf16_f32 v169, v226, v227
	s_and_saveexec_b64 s[46:47], s[8:9]
	global_store_dwordx2 v[220:221], v[168:169], off
	s_or_b64 exec, exec, s[46:47]
	v_pk_fma_f32 v[224:225], v[118:119], v[138:139], v[142:143]
	v_pk_fma_f32 v[226:227], v[120:121], v[140:141], v[144:145]
	v_pk_fma_f32 v[228:229], v[94:95], v[154:155], v[158:159]
	v_pk_fma_f32 v[230:231], v[96:97], v[156:157], v[160:161]
	v_fmac_f32_dpp v224, v118, v134 row_shr:1 row_mask:0xf bank_mask:0xf bound_ctrl:1
	v_fmac_f32_dpp v225, v119, v135 row_shr:1 row_mask:0xf bank_mask:0xf bound_ctrl:1
	v_fmac_f32_dpp v226, v120, v136 row_shr:1 row_mask:0xf bank_mask:0xf bound_ctrl:1
	v_fmac_f32_dpp v227, v121, v137 row_shr:1 row_mask:0xf bank_mask:0xf bound_ctrl:1
	v_fmac_f32_dpp v228, v94, v150 row_shr:1 row_mask:0xf bank_mask:0xf bound_ctrl:1
	v_fmac_f32_dpp v229, v95, v151 row_shr:1 row_mask:0xf bank_mask:0xf bound_ctrl:1
	v_fmac_f32_dpp v230, v96, v152 row_shr:1 row_mask:0xf bank_mask:0xf bound_ctrl:1
	v_fmac_f32_dpp v231, v97, v153 row_shr:1 row_mask:0xf bank_mask:0xf bound_ctrl:1
	v_fmac_f32_dpp v224, v118, v130 row_shr:2 row_mask:0xf bank_mask:0xf bound_ctrl:1
	v_fmac_f32_dpp v225, v119, v131 row_shr:2 row_mask:0xf bank_mask:0xf bound_ctrl:1
	v_fmac_f32_dpp v226, v120, v132 row_shr:2 row_mask:0xf bank_mask:0xf bound_ctrl:1
	v_fmac_f32_dpp v227, v121, v133 row_shr:2 row_mask:0xf bank_mask:0xf bound_ctrl:1
	v_fmac_f32_dpp v228, v94, v146 row_shr:2 row_mask:0xf bank_mask:0xf bound_ctrl:1
	v_fmac_f32_dpp v229, v95, v147 row_shr:2 row_mask:0xf bank_mask:0xf bound_ctrl:1
	v_fmac_f32_dpp v230, v96, v148 row_shr:2 row_mask:0xf bank_mask:0xf bound_ctrl:1
	v_fmac_f32_dpp v231, v97, v149 row_shr:2 row_mask:0xf bank_mask:0xf bound_ctrl:1
	v_fmac_f32_dpp v224, v126, v134 row_shl:15 row_mask:0xf bank_mask:0xf bound_ctrl:1
	v_fmac_f32_dpp v225, v127, v135 row_shl:15 row_mask:0xf bank_mask:0xf bound_ctrl:1
	v_fmac_f32_dpp v226, v128, v136 row_shl:15 row_mask:0xf bank_mask:0xf bound_ctrl:1
	v_fmac_f32_dpp v227, v129, v137 row_shl:15 row_mask:0xf bank_mask:0xf bound_ctrl:1
	v_fmac_f32_dpp v228, v110, v150 row_shl:15 row_mask:0xf bank_mask:0xf bound_ctrl:1
	v_fmac_f32_dpp v229, v111, v151 row_shl:15 row_mask:0xf bank_mask:0xf bound_ctrl:1
	v_fmac_f32_dpp v230, v112, v152 row_shl:15 row_mask:0xf bank_mask:0xf bound_ctrl:1
	v_fmac_f32_dpp v231, v113, v153 row_shl:15 row_mask:0xf bank_mask:0xf bound_ctrl:1
	v_fmac_f32_dpp v224, v126, v130 row_shl:14 row_mask:0xf bank_mask:0xf bound_ctrl:1
	v_fmac_f32_dpp v225, v127, v131 row_shl:14 row_mask:0xf bank_mask:0xf bound_ctrl:1
	v_fmac_f32_dpp v226, v128, v132 row_shl:14 row_mask:0xf bank_mask:0xf bound_ctrl:1
	v_fmac_f32_dpp v227, v129, v133 row_shl:14 row_mask:0xf bank_mask:0xf bound_ctrl:1
	v_fmac_f32_dpp v228, v110, v146 row_shl:14 row_mask:0xf bank_mask:0xf bound_ctrl:1
	v_fmac_f32_dpp v229, v111, v147 row_shl:14 row_mask:0xf bank_mask:0xf bound_ctrl:1
	v_fmac_f32_dpp v230, v112, v148 row_shl:14 row_mask:0xf bank_mask:0xf bound_ctrl:1
	v_fmac_f32_dpp v231, v113, v149 row_shl:14 row_mask:0xf bank_mask:0xf bound_ctrl:1
	v_pk_mul_f32 v[232:233], v[224:225], s[48:49] op_sel_hi:[1,0]
	v_pk_mul_f32 v[234:235], v[226:227], s[48:49] op_sel_hi:[1,0]
	v_exp_f32_e32 v232, v232
	v_exp_f32_e32 v233, v233
	v_exp_f32_e32 v234, v234
	v_exp_f32_e32 v235, v235
	s_nop 0
	v_pk_add_f32 v[232:233], v[232:233], 1.0 op_sel_hi:[1,0]
	v_pk_add_f32 v[234:235], v[234:235], 1.0 op_sel_hi:[1,0]
	v_rcp_f32_e32 v232, v232
	v_rcp_f32_e32 v233, v233
	v_rcp_f32_e32 v234, v234
	v_rcp_f32_e32 v235, v235
	v_lshl_add_u64 v[220:221], v[220:221], 0, s[96:97]
	v_pk_mul_f32 v[224:225], v[224:225], v[232:233]
	v_pk_mul_f32 v[226:227], v[226:227], v[234:235]
	v_pk_mul_f32 v[224:225], v[224:225], v[228:229]
	v_pk_mul_f32 v[226:227], v[226:227], v[230:231]
	s_nop 0
	v_cvt_pk_bf16_f32 v168, v224, v225
	v_cvt_pk_bf16_f32 v169, v226, v227
	global_store_dwordx2 v[220:221], v[168:169], off
	v_pk_fma_f32 v[224:225], v[106:107], v[138:139], v[142:143]
	v_pk_fma_f32 v[226:227], v[108:109], v[140:141], v[144:145]
	v_pk_fma_f32 v[228:229], v[78:79], v[154:155], v[158:159]
	v_pk_fma_f32 v[230:231], v[80:81], v[156:157], v[160:161]
	v_fmac_f32_dpp v224, v106, v134 row_shr:1 row_mask:0xf bank_mask:0xf bound_ctrl:1
	v_fmac_f32_dpp v225, v107, v135 row_shr:1 row_mask:0xf bank_mask:0xf bound_ctrl:1
	v_fmac_f32_dpp v226, v108, v136 row_shr:1 row_mask:0xf bank_mask:0xf bound_ctrl:1
	v_fmac_f32_dpp v227, v109, v137 row_shr:1 row_mask:0xf bank_mask:0xf bound_ctrl:1
	v_fmac_f32_dpp v228, v78, v150 row_shr:1 row_mask:0xf bank_mask:0xf bound_ctrl:1
	v_fmac_f32_dpp v229, v79, v151 row_shr:1 row_mask:0xf bank_mask:0xf bound_ctrl:1
	v_fmac_f32_dpp v230, v80, v152 row_shr:1 row_mask:0xf bank_mask:0xf bound_ctrl:1
	v_fmac_f32_dpp v231, v81, v153 row_shr:1 row_mask:0xf bank_mask:0xf bound_ctrl:1
	v_fmac_f32_dpp v224, v106, v130 row_shr:2 row_mask:0xf bank_mask:0xf bound_ctrl:1
	v_fmac_f32_dpp v225, v107, v131 row_shr:2 row_mask:0xf bank_mask:0xf bound_ctrl:1
	v_fmac_f32_dpp v226, v108, v132 row_shr:2 row_mask:0xf bank_mask:0xf bound_ctrl:1
	v_fmac_f32_dpp v227, v109, v133 row_shr:2 row_mask:0xf bank_mask:0xf bound_ctrl:1
	v_fmac_f32_dpp v228, v78, v146 row_shr:2 row_mask:0xf bank_mask:0xf bound_ctrl:1
	v_fmac_f32_dpp v229, v79, v147 row_shr:2 row_mask:0xf bank_mask:0xf bound_ctrl:1
	v_fmac_f32_dpp v230, v80, v148 row_shr:2 row_mask:0xf bank_mask:0xf bound_ctrl:1
	v_fmac_f32_dpp v231, v81, v149 row_shr:2 row_mask:0xf bank_mask:0xf bound_ctrl:1
	v_fmac_f32_dpp v224, v118, v134 row_shl:15 row_mask:0xf bank_mask:0xf bound_ctrl:1
	v_fmac_f32_dpp v225, v119, v135 row_shl:15 row_mask:0xf bank_mask:0xf bound_ctrl:1
	v_fmac_f32_dpp v226, v120, v136 row_shl:15 row_mask:0xf bank_mask:0xf bound_ctrl:1
	v_fmac_f32_dpp v227, v121, v137 row_shl:15 row_mask:0xf bank_mask:0xf bound_ctrl:1
	v_fmac_f32_dpp v228, v94, v150 row_shl:15 row_mask:0xf bank_mask:0xf bound_ctrl:1
	v_fmac_f32_dpp v229, v95, v151 row_shl:15 row_mask:0xf bank_mask:0xf bound_ctrl:1
	v_fmac_f32_dpp v230, v96, v152 row_shl:15 row_mask:0xf bank_mask:0xf bound_ctrl:1
	v_fmac_f32_dpp v231, v97, v153 row_shl:15 row_mask:0xf bank_mask:0xf bound_ctrl:1
	v_fmac_f32_dpp v224, v118, v130 row_shl:14 row_mask:0xf bank_mask:0xf bound_ctrl:1
	v_fmac_f32_dpp v225, v119, v131 row_shl:14 row_mask:0xf bank_mask:0xf bound_ctrl:1
	v_fmac_f32_dpp v226, v120, v132 row_shl:14 row_mask:0xf bank_mask:0xf bound_ctrl:1
	v_fmac_f32_dpp v227, v121, v133 row_shl:14 row_mask:0xf bank_mask:0xf bound_ctrl:1
	v_fmac_f32_dpp v228, v94, v146 row_shl:14 row_mask:0xf bank_mask:0xf bound_ctrl:1
	v_fmac_f32_dpp v229, v95, v147 row_shl:14 row_mask:0xf bank_mask:0xf bound_ctrl:1
	v_fmac_f32_dpp v230, v96, v148 row_shl:14 row_mask:0xf bank_mask:0xf bound_ctrl:1
	v_fmac_f32_dpp v231, v97, v149 row_shl:14 row_mask:0xf bank_mask:0xf bound_ctrl:1
	v_pk_mul_f32 v[232:233], v[224:225], s[48:49] op_sel_hi:[1,0]
	v_pk_mul_f32 v[234:235], v[226:227], s[48:49] op_sel_hi:[1,0]
	v_exp_f32_e32 v232, v232
	v_exp_f32_e32 v233, v233
	v_exp_f32_e32 v234, v234
	v_exp_f32_e32 v235, v235
	s_nop 0
	v_pk_add_f32 v[232:233], v[232:233], 1.0 op_sel_hi:[1,0]
	v_pk_add_f32 v[234:235], v[234:235], 1.0 op_sel_hi:[1,0]
	v_rcp_f32_e32 v232, v232
	v_rcp_f32_e32 v233, v233
	v_rcp_f32_e32 v234, v234
	v_rcp_f32_e32 v235, v235
	v_lshl_add_u64 v[220:221], v[220:221], 0, s[96:97]
	v_pk_mul_f32 v[224:225], v[224:225], v[232:233]
	v_pk_mul_f32 v[226:227], v[226:227], v[234:235]
	v_pk_mul_f32 v[224:225], v[224:225], v[228:229]
	v_pk_mul_f32 v[226:227], v[226:227], v[230:231]
	s_nop 0
	v_cvt_pk_bf16_f32 v168, v224, v225
	v_cvt_pk_bf16_f32 v169, v226, v227
	global_store_dwordx2 v[220:221], v[168:169], off
	s_add_u32 s94, s26, s85
	s_addc_u32 s95, s27, 0
	v_lshl_add_u64 v[222:223], s[94:95], 0, v[216:217]
	v_lshl_add_u64 v[246:247], s[94:95], 0, v[218:219]
	s_and_saveexec_b64 s[46:47], s[6:7]
	global_store_dwordx4 v[222:223], v[90:93], off
	global_store_dwordx4 v[246:247], v[70:73], off
	s_or_b64 exec, exec, s[46:47]
	v_pk_fma_f32 v[224:225], v[90:91], v[138:139], v[142:143]
	v_pk_fma_f32 v[226:227], v[92:93], v[140:141], v[144:145]
	v_pk_fma_f32 v[228:229], v[70:71], v[154:155], v[158:159]
	v_pk_fma_f32 v[230:231], v[72:73], v[156:157], v[160:161]
	v_fmac_f32_dpp v224, v90, v134 row_shr:1 row_mask:0xf bank_mask:0xf bound_ctrl:1
	v_fmac_f32_dpp v225, v91, v135 row_shr:1 row_mask:0xf bank_mask:0xf bound_ctrl:1
	v_fmac_f32_dpp v226, v92, v136 row_shr:1 row_mask:0xf bank_mask:0xf bound_ctrl:1
	v_fmac_f32_dpp v227, v93, v137 row_shr:1 row_mask:0xf bank_mask:0xf bound_ctrl:1
	v_fmac_f32_dpp v228, v70, v150 row_shr:1 row_mask:0xf bank_mask:0xf bound_ctrl:1
	v_fmac_f32_dpp v229, v71, v151 row_shr:1 row_mask:0xf bank_mask:0xf bound_ctrl:1
	v_fmac_f32_dpp v230, v72, v152 row_shr:1 row_mask:0xf bank_mask:0xf bound_ctrl:1
	v_fmac_f32_dpp v231, v73, v153 row_shr:1 row_mask:0xf bank_mask:0xf bound_ctrl:1
	v_fmac_f32_dpp v224, v90, v130 row_shr:2 row_mask:0xf bank_mask:0xf bound_ctrl:1
	v_fmac_f32_dpp v225, v91, v131 row_shr:2 row_mask:0xf bank_mask:0xf bound_ctrl:1
	v_fmac_f32_dpp v226, v92, v132 row_shr:2 row_mask:0xf bank_mask:0xf bound_ctrl:1
	v_fmac_f32_dpp v227, v93, v133 row_shr:2 row_mask:0xf bank_mask:0xf bound_ctrl:1
	v_fmac_f32_dpp v228, v70, v146 row_shr:2 row_mask:0xf bank_mask:0xf bound_ctrl:1
	v_fmac_f32_dpp v229, v71, v147 row_shr:2 row_mask:0xf bank_mask:0xf bound_ctrl:1
	v_fmac_f32_dpp v230, v72, v148 row_shr:2 row_mask:0xf bank_mask:0xf bound_ctrl:1
	v_fmac_f32_dpp v231, v73, v149 row_shr:2 row_mask:0xf bank_mask:0xf bound_ctrl:1
	v_fmac_f32_dpp v224, v106, v134 row_shl:15 row_mask:0xf bank_mask:0xf bound_ctrl:1
	v_fmac_f32_dpp v225, v107, v135 row_shl:15 row_mask:0xf bank_mask:0xf bound_ctrl:1
	v_fmac_f32_dpp v226, v108, v136 row_shl:15 row_mask:0xf bank_mask:0xf bound_ctrl:1
	v_fmac_f32_dpp v227, v109, v137 row_shl:15 row_mask:0xf bank_mask:0xf bound_ctrl:1
	v_fmac_f32_dpp v228, v78, v150 row_shl:15 row_mask:0xf bank_mask:0xf bound_ctrl:1
	v_fmac_f32_dpp v229, v79, v151 row_shl:15 row_mask:0xf bank_mask:0xf bound_ctrl:1
	v_fmac_f32_dpp v230, v80, v152 row_shl:15 row_mask:0xf bank_mask:0xf bound_ctrl:1
	v_fmac_f32_dpp v231, v81, v153 row_shl:15 row_mask:0xf bank_mask:0xf bound_ctrl:1
	v_fmac_f32_dpp v224, v106, v130 row_shl:14 row_mask:0xf bank_mask:0xf bound_ctrl:1
	v_fmac_f32_dpp v225, v107, v131 row_shl:14 row_mask:0xf bank_mask:0xf bound_ctrl:1
	v_fmac_f32_dpp v226, v108, v132 row_shl:14 row_mask:0xf bank_mask:0xf bound_ctrl:1
	v_fmac_f32_dpp v227, v109, v133 row_shl:14 row_mask:0xf bank_mask:0xf bound_ctrl:1
	v_fmac_f32_dpp v228, v78, v146 row_shl:14 row_mask:0xf bank_mask:0xf bound_ctrl:1
	v_fmac_f32_dpp v229, v79, v147 row_shl:14 row_mask:0xf bank_mask:0xf bound_ctrl:1
	v_fmac_f32_dpp v230, v80, v148 row_shl:14 row_mask:0xf bank_mask:0xf bound_ctrl:1
	v_fmac_f32_dpp v231, v81, v149 row_shl:14 row_mask:0xf bank_mask:0xf bound_ctrl:1
	v_pk_mul_f32 v[232:233], v[224:225], s[48:49] op_sel_hi:[1,0]
	v_pk_mul_f32 v[234:235], v[226:227], s[48:49] op_sel_hi:[1,0]
	v_exp_f32_e32 v232, v232
	v_exp_f32_e32 v233, v233
	v_exp_f32_e32 v234, v234
	v_exp_f32_e32 v235, v235
	s_nop 0
	v_pk_add_f32 v[232:233], v[232:233], 1.0 op_sel_hi:[1,0]
	v_pk_add_f32 v[234:235], v[234:235], 1.0 op_sel_hi:[1,0]
	v_rcp_f32_e32 v232, v232
	v_rcp_f32_e32 v233, v233
	v_rcp_f32_e32 v234, v234
	v_rcp_f32_e32 v235, v235
	v_lshl_add_u64 v[220:221], v[220:221], 0, s[96:97]
	v_pk_mul_f32 v[224:225], v[224:225], v[232:233]
	v_pk_mul_f32 v[226:227], v[226:227], v[234:235]
	v_pk_mul_f32 v[224:225], v[224:225], v[228:229]
	v_pk_mul_f32 v[226:227], v[226:227], v[230:231]
	s_nop 0
	v_cvt_pk_bf16_f32 v168, v224, v225
	v_cvt_pk_bf16_f32 v169, v226, v227
	global_store_dwordx2 v[220:221], v[168:169], off
	s_add_i32 s84, s39, 2
	s_mul_i32 s85, s84, 0xb0000
	s_add_u32 s94, s22, s85
	s_addc_u32 s95, s23, 0
	v_lshl_add_u64 v[220:221], s[94:95], 0, v[210:211]
	s_mul_i32 s85, s84, 0x16000
	s_add_u32 s94, s24, s85
	s_addc_u32 s95, s25, 0
	v_lshl_add_u64 v[222:223], s[94:95], 0, v[212:213]
	v_lshl_add_u64 v[246:247], s[94:95], 0, v[214:215]
	s_and_saveexec_b64 s[46:47], s[4:5]
	global_store_dwordx4 v[222:223], v[62:65], off
	global_store_dwordx4 v[246:247], v[46:49], off
	s_or_b64 exec, exec, s[46:47]
	v_pk_fma_f32 v[224:225], v[62:63], v[138:139], v[142:143]
	v_pk_fma_f32 v[226:227], v[64:65], v[140:141], v[144:145]
	v_pk_fma_f32 v[228:229], v[46:47], v[154:155], v[158:159]
	v_pk_fma_f32 v[230:231], v[48:49], v[156:157], v[160:161]
	v_fmac_f32_dpp v224, v62, v134 row_shr:1 row_mask:0xf bank_mask:0xf bound_ctrl:1
	v_fmac_f32_dpp v225, v63, v135 row_shr:1 row_mask:0xf bank_mask:0xf bound_ctrl:1
	v_fmac_f32_dpp v226, v64, v136 row_shr:1 row_mask:0xf bank_mask:0xf bound_ctrl:1
	v_fmac_f32_dpp v227, v65, v137 row_shr:1 row_mask:0xf bank_mask:0xf bound_ctrl:1
	v_fmac_f32_dpp v228, v46, v150 row_shr:1 row_mask:0xf bank_mask:0xf bound_ctrl:1
	v_fmac_f32_dpp v229, v47, v151 row_shr:1 row_mask:0xf bank_mask:0xf bound_ctrl:1
	v_fmac_f32_dpp v230, v48, v152 row_shr:1 row_mask:0xf bank_mask:0xf bound_ctrl:1
	v_fmac_f32_dpp v231, v49, v153 row_shr:1 row_mask:0xf bank_mask:0xf bound_ctrl:1
	v_fmac_f32_dpp v224, v62, v130 row_shr:2 row_mask:0xf bank_mask:0xf bound_ctrl:1
	v_fmac_f32_dpp v225, v63, v131 row_shr:2 row_mask:0xf bank_mask:0xf bound_ctrl:1
	v_fmac_f32_dpp v226, v64, v132 row_shr:2 row_mask:0xf bank_mask:0xf bound_ctrl:1
	v_fmac_f32_dpp v227, v65, v133 row_shr:2 row_mask:0xf bank_mask:0xf bound_ctrl:1
	v_fmac_f32_dpp v228, v46, v146 row_shr:2 row_mask:0xf bank_mask:0xf bound_ctrl:1
	v_fmac_f32_dpp v229, v47, v147 row_shr:2 row_mask:0xf bank_mask:0xf bound_ctrl:1
	v_fmac_f32_dpp v230, v48, v148 row_shr:2 row_mask:0xf bank_mask:0xf bound_ctrl:1
	v_fmac_f32_dpp v231, v49, v149 row_shr:2 row_mask:0xf bank_mask:0xf bound_ctrl:1
	v_pk_mul_f32 v[232:233], v[224:225], s[48:49] op_sel_hi:[1,0]
	v_pk_mul_f32 v[234:235], v[226:227], s[48:49] op_sel_hi:[1,0]
	v_exp_f32_e32 v232, v232
	v_exp_f32_e32 v233, v233
	v_exp_f32_e32 v234, v234
	v_exp_f32_e32 v235, v235
	s_nop 0
	v_pk_add_f32 v[232:233], v[232:233], 1.0 op_sel_hi:[1,0]
	v_pk_add_f32 v[234:235], v[234:235], 1.0 op_sel_hi:[1,0]
	v_rcp_f32_e32 v232, v232
	v_rcp_f32_e32 v233, v233
	v_rcp_f32_e32 v234, v234
	v_rcp_f32_e32 v235, v235
	s_nop 0
	v_pk_mul_f32 v[224:225], v[224:225], v[232:233]
	v_pk_mul_f32 v[226:227], v[226:227], v[234:235]
	v_pk_mul_f32 v[224:225], v[224:225], v[228:229]
	v_pk_mul_f32 v[226:227], v[226:227], v[230:231]
	s_nop 0
	v_cvt_pk_bf16_f32 v168, v224, v225
	v_cvt_pk_bf16_f32 v169, v226, v227
	s_and_saveexec_b64 s[46:47], s[8:9]
	global_store_dwordx2 v[220:221], v[168:169], off
	s_or_b64 exec, exec, s[46:47]
	v_pk_fma_f32 v[224:225], v[54:55], v[138:139], v[142:143]
	v_pk_fma_f32 v[226:227], v[56:57], v[140:141], v[144:145]
	v_pk_fma_f32 v[228:229], v[30:31], v[154:155], v[158:159]
	v_pk_fma_f32 v[230:231], v[32:33], v[156:157], v[160:161]
	v_fmac_f32_dpp v224, v54, v134 row_shr:1 row_mask:0xf bank_mask:0xf bound_ctrl:1
	v_fmac_f32_dpp v225, v55, v135 row_shr:1 row_mask:0xf bank_mask:0xf bound_ctrl:1
	v_fmac_f32_dpp v226, v56, v136 row_shr:1 row_mask:0xf bank_mask:0xf bound_ctrl:1
	v_fmac_f32_dpp v227, v57, v137 row_shr:1 row_mask:0xf bank_mask:0xf bound_ctrl:1
	v_fmac_f32_dpp v228, v30, v150 row_shr:1 row_mask:0xf bank_mask:0xf bound_ctrl:1
	v_fmac_f32_dpp v229, v31, v151 row_shr:1 row_mask:0xf bank_mask:0xf bound_ctrl:1
	v_fmac_f32_dpp v230, v32, v152 row_shr:1 row_mask:0xf bank_mask:0xf bound_ctrl:1
	v_fmac_f32_dpp v231, v33, v153 row_shr:1 row_mask:0xf bank_mask:0xf bound_ctrl:1
	v_fmac_f32_dpp v224, v54, v130 row_shr:2 row_mask:0xf bank_mask:0xf bound_ctrl:1
	v_fmac_f32_dpp v225, v55, v131 row_shr:2 row_mask:0xf bank_mask:0xf bound_ctrl:1
	v_fmac_f32_dpp v226, v56, v132 row_shr:2 row_mask:0xf bank_mask:0xf bound_ctrl:1
	v_fmac_f32_dpp v227, v57, v133 row_shr:2 row_mask:0xf bank_mask:0xf bound_ctrl:1
	v_fmac_f32_dpp v228, v30, v146 row_shr:2 row_mask:0xf bank_mask:0xf bound_ctrl:1
	v_fmac_f32_dpp v229, v31, v147 row_shr:2 row_mask:0xf bank_mask:0xf bound_ctrl:1
	v_fmac_f32_dpp v230, v32, v148 row_shr:2 row_mask:0xf bank_mask:0xf bound_ctrl:1
	v_fmac_f32_dpp v231, v33, v149 row_shr:2 row_mask:0xf bank_mask:0xf bound_ctrl:1
	v_fmac_f32_dpp v224, v62, v134 row_shl:15 row_mask:0xf bank_mask:0xf bound_ctrl:1
	v_fmac_f32_dpp v225, v63, v135 row_shl:15 row_mask:0xf bank_mask:0xf bound_ctrl:1
	v_fmac_f32_dpp v226, v64, v136 row_shl:15 row_mask:0xf bank_mask:0xf bound_ctrl:1
	v_fmac_f32_dpp v227, v65, v137 row_shl:15 row_mask:0xf bank_mask:0xf bound_ctrl:1
	v_fmac_f32_dpp v228, v46, v150 row_shl:15 row_mask:0xf bank_mask:0xf bound_ctrl:1
	v_fmac_f32_dpp v229, v47, v151 row_shl:15 row_mask:0xf bank_mask:0xf bound_ctrl:1
	v_fmac_f32_dpp v230, v48, v152 row_shl:15 row_mask:0xf bank_mask:0xf bound_ctrl:1
	v_fmac_f32_dpp v231, v49, v153 row_shl:15 row_mask:0xf bank_mask:0xf bound_ctrl:1
	v_fmac_f32_dpp v224, v62, v130 row_shl:14 row_mask:0xf bank_mask:0xf bound_ctrl:1
	v_fmac_f32_dpp v225, v63, v131 row_shl:14 row_mask:0xf bank_mask:0xf bound_ctrl:1
	v_fmac_f32_dpp v226, v64, v132 row_shl:14 row_mask:0xf bank_mask:0xf bound_ctrl:1
	v_fmac_f32_dpp v227, v65, v133 row_shl:14 row_mask:0xf bank_mask:0xf bound_ctrl:1
	v_fmac_f32_dpp v228, v46, v146 row_shl:14 row_mask:0xf bank_mask:0xf bound_ctrl:1
	v_fmac_f32_dpp v229, v47, v147 row_shl:14 row_mask:0xf bank_mask:0xf bound_ctrl:1
	v_fmac_f32_dpp v230, v48, v148 row_shl:14 row_mask:0xf bank_mask:0xf bound_ctrl:1
	v_fmac_f32_dpp v231, v49, v149 row_shl:14 row_mask:0xf bank_mask:0xf bound_ctrl:1
	v_pk_mul_f32 v[232:233], v[224:225], s[48:49] op_sel_hi:[1,0]
	v_pk_mul_f32 v[234:235], v[226:227], s[48:49] op_sel_hi:[1,0]
	v_exp_f32_e32 v232, v232
	v_exp_f32_e32 v233, v233
	v_exp_f32_e32 v234, v234
	v_exp_f32_e32 v235, v235
	s_nop 0
	v_pk_add_f32 v[232:233], v[232:233], 1.0 op_sel_hi:[1,0]
	v_pk_add_f32 v[234:235], v[234:235], 1.0 op_sel_hi:[1,0]
	v_rcp_f32_e32 v232, v232
	v_rcp_f32_e32 v233, v233
	v_rcp_f32_e32 v234, v234
	v_rcp_f32_e32 v235, v235
	v_lshl_add_u64 v[220:221], v[220:221], 0, s[96:97]
	v_pk_mul_f32 v[224:225], v[224:225], v[232:233]
	v_pk_mul_f32 v[226:227], v[226:227], v[234:235]
	v_pk_mul_f32 v[224:225], v[224:225], v[228:229]
	v_pk_mul_f32 v[226:227], v[226:227], v[230:231]
	s_nop 0
	v_cvt_pk_bf16_f32 v168, v224, v225
	v_cvt_pk_bf16_f32 v169, v226, v227
	global_store_dwordx2 v[220:221], v[168:169], off
	v_pk_fma_f32 v[224:225], v[42:43], v[138:139], v[142:143]
	v_pk_fma_f32 v[226:227], v[44:45], v[140:141], v[144:145]
	v_pk_fma_f32 v[228:229], v[14:15], v[154:155], v[158:159]
	v_pk_fma_f32 v[230:231], v[16:17], v[156:157], v[160:161]
	v_fmac_f32_dpp v224, v42, v134 row_shr:1 row_mask:0xf bank_mask:0xf bound_ctrl:1
	v_fmac_f32_dpp v225, v43, v135 row_shr:1 row_mask:0xf bank_mask:0xf bound_ctrl:1
	v_fmac_f32_dpp v226, v44, v136 row_shr:1 row_mask:0xf bank_mask:0xf bound_ctrl:1
	v_fmac_f32_dpp v227, v45, v137 row_shr:1 row_mask:0xf bank_mask:0xf bound_ctrl:1
	v_fmac_f32_dpp v228, v14, v150 row_shr:1 row_mask:0xf bank_mask:0xf bound_ctrl:1
	v_fmac_f32_dpp v229, v15, v151 row_shr:1 row_mask:0xf bank_mask:0xf bound_ctrl:1
	v_fmac_f32_dpp v230, v16, v152 row_shr:1 row_mask:0xf bank_mask:0xf bound_ctrl:1
	v_fmac_f32_dpp v231, v17, v153 row_shr:1 row_mask:0xf bank_mask:0xf bound_ctrl:1
	v_fmac_f32_dpp v224, v42, v130 row_shr:2 row_mask:0xf bank_mask:0xf bound_ctrl:1
	v_fmac_f32_dpp v225, v43, v131 row_shr:2 row_mask:0xf bank_mask:0xf bound_ctrl:1
	v_fmac_f32_dpp v226, v44, v132 row_shr:2 row_mask:0xf bank_mask:0xf bound_ctrl:1
	v_fmac_f32_dpp v227, v45, v133 row_shr:2 row_mask:0xf bank_mask:0xf bound_ctrl:1
	v_fmac_f32_dpp v228, v14, v146 row_shr:2 row_mask:0xf bank_mask:0xf bound_ctrl:1
	v_fmac_f32_dpp v229, v15, v147 row_shr:2 row_mask:0xf bank_mask:0xf bound_ctrl:1
	v_fmac_f32_dpp v230, v16, v148 row_shr:2 row_mask:0xf bank_mask:0xf bound_ctrl:1
	v_fmac_f32_dpp v231, v17, v149 row_shr:2 row_mask:0xf bank_mask:0xf bound_ctrl:1
	v_fmac_f32_dpp v224, v54, v134 row_shl:15 row_mask:0xf bank_mask:0xf bound_ctrl:1
	v_fmac_f32_dpp v225, v55, v135 row_shl:15 row_mask:0xf bank_mask:0xf bound_ctrl:1
	v_fmac_f32_dpp v226, v56, v136 row_shl:15 row_mask:0xf bank_mask:0xf bound_ctrl:1
	v_fmac_f32_dpp v227, v57, v137 row_shl:15 row_mask:0xf bank_mask:0xf bound_ctrl:1
	v_fmac_f32_dpp v228, v30, v150 row_shl:15 row_mask:0xf bank_mask:0xf bound_ctrl:1
	v_fmac_f32_dpp v229, v31, v151 row_shl:15 row_mask:0xf bank_mask:0xf bound_ctrl:1
	v_fmac_f32_dpp v230, v32, v152 row_shl:15 row_mask:0xf bank_mask:0xf bound_ctrl:1
	v_fmac_f32_dpp v231, v33, v153 row_shl:15 row_mask:0xf bank_mask:0xf bound_ctrl:1
	v_fmac_f32_dpp v224, v54, v130 row_shl:14 row_mask:0xf bank_mask:0xf bound_ctrl:1
	v_fmac_f32_dpp v225, v55, v131 row_shl:14 row_mask:0xf bank_mask:0xf bound_ctrl:1
	v_fmac_f32_dpp v226, v56, v132 row_shl:14 row_mask:0xf bank_mask:0xf bound_ctrl:1
	v_fmac_f32_dpp v227, v57, v133 row_shl:14 row_mask:0xf bank_mask:0xf bound_ctrl:1
	v_fmac_f32_dpp v228, v30, v146 row_shl:14 row_mask:0xf bank_mask:0xf bound_ctrl:1
	v_fmac_f32_dpp v229, v31, v147 row_shl:14 row_mask:0xf bank_mask:0xf bound_ctrl:1
	v_fmac_f32_dpp v230, v32, v148 row_shl:14 row_mask:0xf bank_mask:0xf bound_ctrl:1
	v_fmac_f32_dpp v231, v33, v149 row_shl:14 row_mask:0xf bank_mask:0xf bound_ctrl:1
	v_pk_mul_f32 v[232:233], v[224:225], s[48:49] op_sel_hi:[1,0]
	v_pk_mul_f32 v[234:235], v[226:227], s[48:49] op_sel_hi:[1,0]
	v_exp_f32_e32 v232, v232
	v_exp_f32_e32 v233, v233
	v_exp_f32_e32 v234, v234
	v_exp_f32_e32 v235, v235
	s_nop 0
	v_pk_add_f32 v[232:233], v[232:233], 1.0 op_sel_hi:[1,0]
	v_pk_add_f32 v[234:235], v[234:235], 1.0 op_sel_hi:[1,0]
	v_rcp_f32_e32 v232, v232
	v_rcp_f32_e32 v233, v233
	v_rcp_f32_e32 v234, v234
	v_rcp_f32_e32 v235, v235
	v_lshl_add_u64 v[220:221], v[220:221], 0, s[96:97]
	v_pk_mul_f32 v[224:225], v[224:225], v[232:233]
	v_pk_mul_f32 v[226:227], v[226:227], v[234:235]
	v_pk_mul_f32 v[224:225], v[224:225], v[228:229]
	v_pk_mul_f32 v[226:227], v[226:227], v[230:231]
	s_nop 0
	v_cvt_pk_bf16_f32 v168, v224, v225
	v_cvt_pk_bf16_f32 v169, v226, v227
	global_store_dwordx2 v[220:221], v[168:169], off
	s_add_u32 s94, s26, s85
	s_addc_u32 s95, s27, 0
	v_lshl_add_u64 v[222:223], s[94:95], 0, v[216:217]
	v_lshl_add_u64 v[246:247], s[94:95], 0, v[218:219]
	s_and_saveexec_b64 s[46:47], s[6:7]
	global_store_dwordx4 v[222:223], v[26:29], off
	global_store_dwordx4 v[246:247], v[6:9], off
	s_or_b64 exec, exec, s[46:47]
	v_pk_fma_f32 v[224:225], v[26:27], v[138:139], v[142:143]
	v_pk_fma_f32 v[226:227], v[28:29], v[140:141], v[144:145]
	v_pk_fma_f32 v[228:229], v[6:7], v[154:155], v[158:159]
	v_pk_fma_f32 v[230:231], v[8:9], v[156:157], v[160:161]
	v_fmac_f32_dpp v224, v26, v134 row_shr:1 row_mask:0xf bank_mask:0xf bound_ctrl:1
	v_fmac_f32_dpp v225, v27, v135 row_shr:1 row_mask:0xf bank_mask:0xf bound_ctrl:1
	v_fmac_f32_dpp v226, v28, v136 row_shr:1 row_mask:0xf bank_mask:0xf bound_ctrl:1
	v_fmac_f32_dpp v227, v29, v137 row_shr:1 row_mask:0xf bank_mask:0xf bound_ctrl:1
	v_fmac_f32_dpp v228, v6, v150 row_shr:1 row_mask:0xf bank_mask:0xf bound_ctrl:1
	v_fmac_f32_dpp v229, v7, v151 row_shr:1 row_mask:0xf bank_mask:0xf bound_ctrl:1
	v_fmac_f32_dpp v230, v8, v152 row_shr:1 row_mask:0xf bank_mask:0xf bound_ctrl:1
	v_fmac_f32_dpp v231, v9, v153 row_shr:1 row_mask:0xf bank_mask:0xf bound_ctrl:1
	v_fmac_f32_dpp v224, v26, v130 row_shr:2 row_mask:0xf bank_mask:0xf bound_ctrl:1
	v_fmac_f32_dpp v225, v27, v131 row_shr:2 row_mask:0xf bank_mask:0xf bound_ctrl:1
	v_fmac_f32_dpp v226, v28, v132 row_shr:2 row_mask:0xf bank_mask:0xf bound_ctrl:1
	v_fmac_f32_dpp v227, v29, v133 row_shr:2 row_mask:0xf bank_mask:0xf bound_ctrl:1
	v_fmac_f32_dpp v228, v6, v146 row_shr:2 row_mask:0xf bank_mask:0xf bound_ctrl:1
	v_fmac_f32_dpp v229, v7, v147 row_shr:2 row_mask:0xf bank_mask:0xf bound_ctrl:1
	v_fmac_f32_dpp v230, v8, v148 row_shr:2 row_mask:0xf bank_mask:0xf bound_ctrl:1
	v_fmac_f32_dpp v231, v9, v149 row_shr:2 row_mask:0xf bank_mask:0xf bound_ctrl:1
	v_fmac_f32_dpp v224, v42, v134 row_shl:15 row_mask:0xf bank_mask:0xf bound_ctrl:1
	v_fmac_f32_dpp v225, v43, v135 row_shl:15 row_mask:0xf bank_mask:0xf bound_ctrl:1
	v_fmac_f32_dpp v226, v44, v136 row_shl:15 row_mask:0xf bank_mask:0xf bound_ctrl:1
	v_fmac_f32_dpp v227, v45, v137 row_shl:15 row_mask:0xf bank_mask:0xf bound_ctrl:1
	v_fmac_f32_dpp v228, v14, v150 row_shl:15 row_mask:0xf bank_mask:0xf bound_ctrl:1
	v_fmac_f32_dpp v229, v15, v151 row_shl:15 row_mask:0xf bank_mask:0xf bound_ctrl:1
	v_fmac_f32_dpp v230, v16, v152 row_shl:15 row_mask:0xf bank_mask:0xf bound_ctrl:1
	v_fmac_f32_dpp v231, v17, v153 row_shl:15 row_mask:0xf bank_mask:0xf bound_ctrl:1
	v_fmac_f32_dpp v224, v42, v130 row_shl:14 row_mask:0xf bank_mask:0xf bound_ctrl:1
	v_fmac_f32_dpp v225, v43, v131 row_shl:14 row_mask:0xf bank_mask:0xf bound_ctrl:1
	v_fmac_f32_dpp v226, v44, v132 row_shl:14 row_mask:0xf bank_mask:0xf bound_ctrl:1
	v_fmac_f32_dpp v227, v45, v133 row_shl:14 row_mask:0xf bank_mask:0xf bound_ctrl:1
	v_fmac_f32_dpp v228, v14, v146 row_shl:14 row_mask:0xf bank_mask:0xf bound_ctrl:1
	v_fmac_f32_dpp v229, v15, v147 row_shl:14 row_mask:0xf bank_mask:0xf bound_ctrl:1
	v_fmac_f32_dpp v230, v16, v148 row_shl:14 row_mask:0xf bank_mask:0xf bound_ctrl:1
	v_fmac_f32_dpp v231, v17, v149 row_shl:14 row_mask:0xf bank_mask:0xf bound_ctrl:1
	v_pk_mul_f32 v[232:233], v[224:225], s[48:49] op_sel_hi:[1,0]
	v_pk_mul_f32 v[234:235], v[226:227], s[48:49] op_sel_hi:[1,0]
	v_exp_f32_e32 v232, v232
	v_exp_f32_e32 v233, v233
	v_exp_f32_e32 v234, v234
	v_exp_f32_e32 v235, v235
	s_nop 0
	v_pk_add_f32 v[232:233], v[232:233], 1.0 op_sel_hi:[1,0]
	v_pk_add_f32 v[234:235], v[234:235], 1.0 op_sel_hi:[1,0]
	v_rcp_f32_e32 v232, v232
	v_rcp_f32_e32 v233, v233
	v_rcp_f32_e32 v234, v234
	v_rcp_f32_e32 v235, v235
	v_lshl_add_u64 v[220:221], v[220:221], 0, s[96:97]
	v_pk_mul_f32 v[224:225], v[224:225], v[232:233]
	v_pk_mul_f32 v[226:227], v[226:227], v[234:235]
	v_pk_mul_f32 v[224:225], v[224:225], v[228:229]
	v_pk_mul_f32 v[226:227], v[226:227], v[230:231]
	s_nop 0
	v_cvt_pk_bf16_f32 v168, v224, v225
	v_cvt_pk_bf16_f32 v169, v226, v227
	global_store_dwordx2 v[220:221], v[168:169], off
	s_add_i32 s84, s39, 0
	s_mul_i32 s85, s84, 0xb0000
	s_add_u32 s94, s22, s85
	s_addc_u32 s95, s23, 0
	v_lshl_add_u64 v[220:221], s[94:95], 0, v[210:211]
	s_mul_i32 s85, s84, 0x16000
	s_add_u32 s94, s24, s85
	s_addc_u32 s95, s25, 0
	v_lshl_add_u64 v[222:223], s[94:95], 0, v[212:213]
	v_lshl_add_u64 v[246:247], s[94:95], 0, v[214:215]
	s_and_saveexec_b64 s[46:47], s[4:5]
	global_store_dwordx4 v[222:223], v[122:125], off offset:64
	global_store_dwordx4 v[246:247], v[102:105], off offset:64
	s_or_b64 exec, exec, s[46:47]
	v_pk_fma_f32 v[224:225], v[122:123], v[186:187], v[190:191]
	v_pk_fma_f32 v[226:227], v[124:125], v[188:189], v[192:193]
	v_pk_fma_f32 v[228:229], v[102:103], v[202:203], v[206:207]
	v_pk_fma_f32 v[230:231], v[104:105], v[204:205], v[208:209]
	v_fmac_f32_dpp v224, v122, v182 row_shr:1 row_mask:0xf bank_mask:0xf bound_ctrl:1
	v_fmac_f32_dpp v225, v123, v183 row_shr:1 row_mask:0xf bank_mask:0xf bound_ctrl:1
	v_fmac_f32_dpp v226, v124, v184 row_shr:1 row_mask:0xf bank_mask:0xf bound_ctrl:1
	v_fmac_f32_dpp v227, v125, v185 row_shr:1 row_mask:0xf bank_mask:0xf bound_ctrl:1
	v_fmac_f32_dpp v228, v102, v198 row_shr:1 row_mask:0xf bank_mask:0xf bound_ctrl:1
	v_fmac_f32_dpp v229, v103, v199 row_shr:1 row_mask:0xf bank_mask:0xf bound_ctrl:1
	v_fmac_f32_dpp v230, v104, v200 row_shr:1 row_mask:0xf bank_mask:0xf bound_ctrl:1
	v_fmac_f32_dpp v231, v105, v201 row_shr:1 row_mask:0xf bank_mask:0xf bound_ctrl:1
	v_fmac_f32_dpp v224, v122, v178 row_shr:2 row_mask:0xf bank_mask:0xf bound_ctrl:1
	v_fmac_f32_dpp v225, v123, v179 row_shr:2 row_mask:0xf bank_mask:0xf bound_ctrl:1
	v_fmac_f32_dpp v226, v124, v180 row_shr:2 row_mask:0xf bank_mask:0xf bound_ctrl:1
	v_fmac_f32_dpp v227, v125, v181 row_shr:2 row_mask:0xf bank_mask:0xf bound_ctrl:1
	v_fmac_f32_dpp v228, v102, v194 row_shr:2 row_mask:0xf bank_mask:0xf bound_ctrl:1
	v_fmac_f32_dpp v229, v103, v195 row_shr:2 row_mask:0xf bank_mask:0xf bound_ctrl:1
	v_fmac_f32_dpp v230, v104, v196 row_shr:2 row_mask:0xf bank_mask:0xf bound_ctrl:1
	v_fmac_f32_dpp v231, v105, v197 row_shr:2 row_mask:0xf bank_mask:0xf bound_ctrl:1
	v_pk_mul_f32 v[232:233], v[224:225], s[48:49] op_sel_hi:[1,0]
	v_pk_mul_f32 v[234:235], v[226:227], s[48:49] op_sel_hi:[1,0]
	v_exp_f32_e32 v232, v232
	v_exp_f32_e32 v233, v233
	v_exp_f32_e32 v234, v234
	v_exp_f32_e32 v235, v235
	s_nop 0
	v_pk_add_f32 v[232:233], v[232:233], 1.0 op_sel_hi:[1,0]
	v_pk_add_f32 v[234:235], v[234:235], 1.0 op_sel_hi:[1,0]
	v_rcp_f32_e32 v232, v232
	v_rcp_f32_e32 v233, v233
	v_rcp_f32_e32 v234, v234
	v_rcp_f32_e32 v235, v235
	s_nop 0
	v_pk_mul_f32 v[224:225], v[224:225], v[232:233]
	v_pk_mul_f32 v[226:227], v[226:227], v[234:235]
	v_pk_mul_f32 v[224:225], v[224:225], v[228:229]
	v_pk_mul_f32 v[226:227], v[226:227], v[230:231]
	s_nop 0
	v_cvt_pk_bf16_f32 v168, v224, v225
	v_cvt_pk_bf16_f32 v169, v226, v227
	s_and_saveexec_b64 s[46:47], s[8:9]
	global_store_dwordx2 v[220:221], v[168:169], off offset:32
	s_or_b64 exec, exec, s[46:47]
	v_pk_fma_f32 v[224:225], v[114:115], v[186:187], v[190:191]
	v_pk_fma_f32 v[226:227], v[116:117], v[188:189], v[192:193]
	v_pk_fma_f32 v[228:229], v[86:87], v[202:203], v[206:207]
	v_pk_fma_f32 v[230:231], v[88:89], v[204:205], v[208:209]
	v_fmac_f32_dpp v224, v114, v182 row_shr:1 row_mask:0xf bank_mask:0xf bound_ctrl:1
	v_fmac_f32_dpp v225, v115, v183 row_shr:1 row_mask:0xf bank_mask:0xf bound_ctrl:1
	v_fmac_f32_dpp v226, v116, v184 row_shr:1 row_mask:0xf bank_mask:0xf bound_ctrl:1
	v_fmac_f32_dpp v227, v117, v185 row_shr:1 row_mask:0xf bank_mask:0xf bound_ctrl:1
	v_fmac_f32_dpp v228, v86, v198 row_shr:1 row_mask:0xf bank_mask:0xf bound_ctrl:1
	v_fmac_f32_dpp v229, v87, v199 row_shr:1 row_mask:0xf bank_mask:0xf bound_ctrl:1
	v_fmac_f32_dpp v230, v88, v200 row_shr:1 row_mask:0xf bank_mask:0xf bound_ctrl:1
	v_fmac_f32_dpp v231, v89, v201 row_shr:1 row_mask:0xf bank_mask:0xf bound_ctrl:1
	v_fmac_f32_dpp v224, v114, v178 row_shr:2 row_mask:0xf bank_mask:0xf bound_ctrl:1
	v_fmac_f32_dpp v225, v115, v179 row_shr:2 row_mask:0xf bank_mask:0xf bound_ctrl:1
	v_fmac_f32_dpp v226, v116, v180 row_shr:2 row_mask:0xf bank_mask:0xf bound_ctrl:1
	v_fmac_f32_dpp v227, v117, v181 row_shr:2 row_mask:0xf bank_mask:0xf bound_ctrl:1
	v_fmac_f32_dpp v228, v86, v194 row_shr:2 row_mask:0xf bank_mask:0xf bound_ctrl:1
	v_fmac_f32_dpp v229, v87, v195 row_shr:2 row_mask:0xf bank_mask:0xf bound_ctrl:1
	v_fmac_f32_dpp v230, v88, v196 row_shr:2 row_mask:0xf bank_mask:0xf bound_ctrl:1
	v_fmac_f32_dpp v231, v89, v197 row_shr:2 row_mask:0xf bank_mask:0xf bound_ctrl:1
	v_fmac_f32_dpp v224, v122, v182 row_shl:15 row_mask:0xf bank_mask:0xf bound_ctrl:1
	v_fmac_f32_dpp v225, v123, v183 row_shl:15 row_mask:0xf bank_mask:0xf bound_ctrl:1
	v_fmac_f32_dpp v226, v124, v184 row_shl:15 row_mask:0xf bank_mask:0xf bound_ctrl:1
	v_fmac_f32_dpp v227, v125, v185 row_shl:15 row_mask:0xf bank_mask:0xf bound_ctrl:1
	v_fmac_f32_dpp v228, v102, v198 row_shl:15 row_mask:0xf bank_mask:0xf bound_ctrl:1
	v_fmac_f32_dpp v229, v103, v199 row_shl:15 row_mask:0xf bank_mask:0xf bound_ctrl:1
	v_fmac_f32_dpp v230, v104, v200 row_shl:15 row_mask:0xf bank_mask:0xf bound_ctrl:1
	v_fmac_f32_dpp v231, v105, v201 row_shl:15 row_mask:0xf bank_mask:0xf bound_ctrl:1
	v_fmac_f32_dpp v224, v122, v178 row_shl:14 row_mask:0xf bank_mask:0xf bound_ctrl:1
	v_fmac_f32_dpp v225, v123, v179 row_shl:14 row_mask:0xf bank_mask:0xf bound_ctrl:1
	v_fmac_f32_dpp v226, v124, v180 row_shl:14 row_mask:0xf bank_mask:0xf bound_ctrl:1
	v_fmac_f32_dpp v227, v125, v181 row_shl:14 row_mask:0xf bank_mask:0xf bound_ctrl:1
	v_fmac_f32_dpp v228, v102, v194 row_shl:14 row_mask:0xf bank_mask:0xf bound_ctrl:1
	v_fmac_f32_dpp v229, v103, v195 row_shl:14 row_mask:0xf bank_mask:0xf bound_ctrl:1
	v_fmac_f32_dpp v230, v104, v196 row_shl:14 row_mask:0xf bank_mask:0xf bound_ctrl:1
	v_fmac_f32_dpp v231, v105, v197 row_shl:14 row_mask:0xf bank_mask:0xf bound_ctrl:1
	v_pk_mul_f32 v[232:233], v[224:225], s[48:49] op_sel_hi:[1,0]
	v_pk_mul_f32 v[234:235], v[226:227], s[48:49] op_sel_hi:[1,0]
	v_exp_f32_e32 v232, v232
	v_exp_f32_e32 v233, v233
	v_exp_f32_e32 v234, v234
	v_exp_f32_e32 v235, v235
	s_nop 0
	v_pk_add_f32 v[232:233], v[232:233], 1.0 op_sel_hi:[1,0]
	v_pk_add_f32 v[234:235], v[234:235], 1.0 op_sel_hi:[1,0]
	v_rcp_f32_e32 v232, v232
	v_rcp_f32_e32 v233, v233
	v_rcp_f32_e32 v234, v234
	v_rcp_f32_e32 v235, v235
	v_lshl_add_u64 v[220:221], v[220:221], 0, s[96:97]
	v_pk_mul_f32 v[224:225], v[224:225], v[232:233]
	v_pk_mul_f32 v[226:227], v[226:227], v[234:235]
	v_pk_mul_f32 v[224:225], v[224:225], v[228:229]
	v_pk_mul_f32 v[226:227], v[226:227], v[230:231]
	s_nop 0
	v_cvt_pk_bf16_f32 v168, v224, v225
	v_cvt_pk_bf16_f32 v169, v226, v227
	global_store_dwordx2 v[220:221], v[168:169], off offset:32
	v_pk_fma_f32 v[224:225], v[98:99], v[186:187], v[190:191]
	v_pk_fma_f32 v[226:227], v[100:101], v[188:189], v[192:193]
	v_pk_fma_f32 v[228:229], v[74:75], v[202:203], v[206:207]
	v_pk_fma_f32 v[230:231], v[76:77], v[204:205], v[208:209]
	v_fmac_f32_dpp v224, v98, v182 row_shr:1 row_mask:0xf bank_mask:0xf bound_ctrl:1
	v_fmac_f32_dpp v225, v99, v183 row_shr:1 row_mask:0xf bank_mask:0xf bound_ctrl:1
	v_fmac_f32_dpp v226, v100, v184 row_shr:1 row_mask:0xf bank_mask:0xf bound_ctrl:1
	v_fmac_f32_dpp v227, v101, v185 row_shr:1 row_mask:0xf bank_mask:0xf bound_ctrl:1
	v_fmac_f32_dpp v228, v74, v198 row_shr:1 row_mask:0xf bank_mask:0xf bound_ctrl:1
	v_fmac_f32_dpp v229, v75, v199 row_shr:1 row_mask:0xf bank_mask:0xf bound_ctrl:1
	v_fmac_f32_dpp v230, v76, v200 row_shr:1 row_mask:0xf bank_mask:0xf bound_ctrl:1
	v_fmac_f32_dpp v231, v77, v201 row_shr:1 row_mask:0xf bank_mask:0xf bound_ctrl:1
	v_fmac_f32_dpp v224, v98, v178 row_shr:2 row_mask:0xf bank_mask:0xf bound_ctrl:1
	v_fmac_f32_dpp v225, v99, v179 row_shr:2 row_mask:0xf bank_mask:0xf bound_ctrl:1
	v_fmac_f32_dpp v226, v100, v180 row_shr:2 row_mask:0xf bank_mask:0xf bound_ctrl:1
	v_fmac_f32_dpp v227, v101, v181 row_shr:2 row_mask:0xf bank_mask:0xf bound_ctrl:1
	v_fmac_f32_dpp v228, v74, v194 row_shr:2 row_mask:0xf bank_mask:0xf bound_ctrl:1
	v_fmac_f32_dpp v229, v75, v195 row_shr:2 row_mask:0xf bank_mask:0xf bound_ctrl:1
	v_fmac_f32_dpp v230, v76, v196 row_shr:2 row_mask:0xf bank_mask:0xf bound_ctrl:1
	v_fmac_f32_dpp v231, v77, v197 row_shr:2 row_mask:0xf bank_mask:0xf bound_ctrl:1
	v_fmac_f32_dpp v224, v114, v182 row_shl:15 row_mask:0xf bank_mask:0xf bound_ctrl:1
	v_fmac_f32_dpp v225, v115, v183 row_shl:15 row_mask:0xf bank_mask:0xf bound_ctrl:1
	v_fmac_f32_dpp v226, v116, v184 row_shl:15 row_mask:0xf bank_mask:0xf bound_ctrl:1
	v_fmac_f32_dpp v227, v117, v185 row_shl:15 row_mask:0xf bank_mask:0xf bound_ctrl:1
	v_fmac_f32_dpp v228, v86, v198 row_shl:15 row_mask:0xf bank_mask:0xf bound_ctrl:1
	v_fmac_f32_dpp v229, v87, v199 row_shl:15 row_mask:0xf bank_mask:0xf bound_ctrl:1
	v_fmac_f32_dpp v230, v88, v200 row_shl:15 row_mask:0xf bank_mask:0xf bound_ctrl:1
	v_fmac_f32_dpp v231, v89, v201 row_shl:15 row_mask:0xf bank_mask:0xf bound_ctrl:1
	v_fmac_f32_dpp v224, v114, v178 row_shl:14 row_mask:0xf bank_mask:0xf bound_ctrl:1
	v_fmac_f32_dpp v225, v115, v179 row_shl:14 row_mask:0xf bank_mask:0xf bound_ctrl:1
	v_fmac_f32_dpp v226, v116, v180 row_shl:14 row_mask:0xf bank_mask:0xf bound_ctrl:1
	v_fmac_f32_dpp v227, v117, v181 row_shl:14 row_mask:0xf bank_mask:0xf bound_ctrl:1
	v_fmac_f32_dpp v228, v86, v194 row_shl:14 row_mask:0xf bank_mask:0xf bound_ctrl:1
	v_fmac_f32_dpp v229, v87, v195 row_shl:14 row_mask:0xf bank_mask:0xf bound_ctrl:1
	v_fmac_f32_dpp v230, v88, v196 row_shl:14 row_mask:0xf bank_mask:0xf bound_ctrl:1
	v_fmac_f32_dpp v231, v89, v197 row_shl:14 row_mask:0xf bank_mask:0xf bound_ctrl:1
	v_pk_mul_f32 v[232:233], v[224:225], s[48:49] op_sel_hi:[1,0]
	v_pk_mul_f32 v[234:235], v[226:227], s[48:49] op_sel_hi:[1,0]
	v_exp_f32_e32 v232, v232
	v_exp_f32_e32 v233, v233
	v_exp_f32_e32 v234, v234
	v_exp_f32_e32 v235, v235
	s_nop 0
	v_pk_add_f32 v[232:233], v[232:233], 1.0 op_sel_hi:[1,0]
	v_pk_add_f32 v[234:235], v[234:235], 1.0 op_sel_hi:[1,0]
	v_rcp_f32_e32 v232, v232
	v_rcp_f32_e32 v233, v233
	v_rcp_f32_e32 v234, v234
	v_rcp_f32_e32 v235, v235
	v_lshl_add_u64 v[220:221], v[220:221], 0, s[96:97]
	v_pk_mul_f32 v[224:225], v[224:225], v[232:233]
	v_pk_mul_f32 v[226:227], v[226:227], v[234:235]
	v_pk_mul_f32 v[224:225], v[224:225], v[228:229]
	v_pk_mul_f32 v[226:227], v[226:227], v[230:231]
	s_nop 0
	v_cvt_pk_bf16_f32 v168, v224, v225
	v_cvt_pk_bf16_f32 v169, v226, v227
	global_store_dwordx2 v[220:221], v[168:169], off offset:32
	s_add_u32 s94, s26, s85
	s_addc_u32 s95, s27, 0
	v_lshl_add_u64 v[222:223], s[94:95], 0, v[216:217]
	v_lshl_add_u64 v[246:247], s[94:95], 0, v[218:219]
	s_and_saveexec_b64 s[46:47], s[6:7]
	global_store_dwordx4 v[222:223], v[82:85], off offset:64
	global_store_dwordx4 v[246:247], v[66:69], off offset:64
	s_or_b64 exec, exec, s[46:47]
	v_pk_fma_f32 v[224:225], v[82:83], v[186:187], v[190:191]
	v_pk_fma_f32 v[226:227], v[84:85], v[188:189], v[192:193]
	v_pk_fma_f32 v[228:229], v[66:67], v[202:203], v[206:207]
	v_pk_fma_f32 v[230:231], v[68:69], v[204:205], v[208:209]
	v_fmac_f32_dpp v224, v82, v182 row_shr:1 row_mask:0xf bank_mask:0xf bound_ctrl:1
	v_fmac_f32_dpp v225, v83, v183 row_shr:1 row_mask:0xf bank_mask:0xf bound_ctrl:1
	v_fmac_f32_dpp v226, v84, v184 row_shr:1 row_mask:0xf bank_mask:0xf bound_ctrl:1
	v_fmac_f32_dpp v227, v85, v185 row_shr:1 row_mask:0xf bank_mask:0xf bound_ctrl:1
	v_fmac_f32_dpp v228, v66, v198 row_shr:1 row_mask:0xf bank_mask:0xf bound_ctrl:1
	v_fmac_f32_dpp v229, v67, v199 row_shr:1 row_mask:0xf bank_mask:0xf bound_ctrl:1
	v_fmac_f32_dpp v230, v68, v200 row_shr:1 row_mask:0xf bank_mask:0xf bound_ctrl:1
	v_fmac_f32_dpp v231, v69, v201 row_shr:1 row_mask:0xf bank_mask:0xf bound_ctrl:1
	v_fmac_f32_dpp v224, v82, v178 row_shr:2 row_mask:0xf bank_mask:0xf bound_ctrl:1
	v_fmac_f32_dpp v225, v83, v179 row_shr:2 row_mask:0xf bank_mask:0xf bound_ctrl:1
	v_fmac_f32_dpp v226, v84, v180 row_shr:2 row_mask:0xf bank_mask:0xf bound_ctrl:1
	v_fmac_f32_dpp v227, v85, v181 row_shr:2 row_mask:0xf bank_mask:0xf bound_ctrl:1
	v_fmac_f32_dpp v228, v66, v194 row_shr:2 row_mask:0xf bank_mask:0xf bound_ctrl:1
	v_fmac_f32_dpp v229, v67, v195 row_shr:2 row_mask:0xf bank_mask:0xf bound_ctrl:1
	v_fmac_f32_dpp v230, v68, v196 row_shr:2 row_mask:0xf bank_mask:0xf bound_ctrl:1
	v_fmac_f32_dpp v231, v69, v197 row_shr:2 row_mask:0xf bank_mask:0xf bound_ctrl:1
	v_fmac_f32_dpp v224, v98, v182 row_shl:15 row_mask:0xf bank_mask:0xf bound_ctrl:1
	v_fmac_f32_dpp v225, v99, v183 row_shl:15 row_mask:0xf bank_mask:0xf bound_ctrl:1
	v_fmac_f32_dpp v226, v100, v184 row_shl:15 row_mask:0xf bank_mask:0xf bound_ctrl:1
	v_fmac_f32_dpp v227, v101, v185 row_shl:15 row_mask:0xf bank_mask:0xf bound_ctrl:1
	v_fmac_f32_dpp v228, v74, v198 row_shl:15 row_mask:0xf bank_mask:0xf bound_ctrl:1
	v_fmac_f32_dpp v229, v75, v199 row_shl:15 row_mask:0xf bank_mask:0xf bound_ctrl:1
	v_fmac_f32_dpp v230, v76, v200 row_shl:15 row_mask:0xf bank_mask:0xf bound_ctrl:1
	v_fmac_f32_dpp v231, v77, v201 row_shl:15 row_mask:0xf bank_mask:0xf bound_ctrl:1
	v_fmac_f32_dpp v224, v98, v178 row_shl:14 row_mask:0xf bank_mask:0xf bound_ctrl:1
	v_fmac_f32_dpp v225, v99, v179 row_shl:14 row_mask:0xf bank_mask:0xf bound_ctrl:1
	v_fmac_f32_dpp v226, v100, v180 row_shl:14 row_mask:0xf bank_mask:0xf bound_ctrl:1
	v_fmac_f32_dpp v227, v101, v181 row_shl:14 row_mask:0xf bank_mask:0xf bound_ctrl:1
	v_fmac_f32_dpp v228, v74, v194 row_shl:14 row_mask:0xf bank_mask:0xf bound_ctrl:1
	v_fmac_f32_dpp v229, v75, v195 row_shl:14 row_mask:0xf bank_mask:0xf bound_ctrl:1
	v_fmac_f32_dpp v230, v76, v196 row_shl:14 row_mask:0xf bank_mask:0xf bound_ctrl:1
	v_fmac_f32_dpp v231, v77, v197 row_shl:14 row_mask:0xf bank_mask:0xf bound_ctrl:1
	v_pk_mul_f32 v[232:233], v[224:225], s[48:49] op_sel_hi:[1,0]
	v_pk_mul_f32 v[234:235], v[226:227], s[48:49] op_sel_hi:[1,0]
	v_exp_f32_e32 v232, v232
	v_exp_f32_e32 v233, v233
	v_exp_f32_e32 v234, v234
	v_exp_f32_e32 v235, v235
	s_nop 0
	v_pk_add_f32 v[232:233], v[232:233], 1.0 op_sel_hi:[1,0]
	v_pk_add_f32 v[234:235], v[234:235], 1.0 op_sel_hi:[1,0]
	v_rcp_f32_e32 v232, v232
	v_rcp_f32_e32 v233, v233
	v_rcp_f32_e32 v234, v234
	v_rcp_f32_e32 v235, v235
	v_lshl_add_u64 v[220:221], v[220:221], 0, s[96:97]
	v_pk_mul_f32 v[224:225], v[224:225], v[232:233]
	v_pk_mul_f32 v[226:227], v[226:227], v[234:235]
	v_pk_mul_f32 v[224:225], v[224:225], v[228:229]
	v_pk_mul_f32 v[226:227], v[226:227], v[230:231]
	s_nop 0
	v_cvt_pk_bf16_f32 v168, v224, v225
	v_cvt_pk_bf16_f32 v169, v226, v227
	global_store_dwordx2 v[220:221], v[168:169], off offset:32
	s_add_i32 s84, s39, 2
	s_mul_i32 s85, s84, 0xb0000
	s_add_u32 s94, s22, s85
	s_addc_u32 s95, s23, 0
	v_lshl_add_u64 v[220:221], s[94:95], 0, v[210:211]
	s_mul_i32 s85, s84, 0x16000
	s_add_u32 s94, s24, s85
	s_addc_u32 s95, s25, 0
	v_lshl_add_u64 v[222:223], s[94:95], 0, v[212:213]
	v_lshl_add_u64 v[246:247], s[94:95], 0, v[214:215]
	s_and_saveexec_b64 s[46:47], s[4:5]
	global_store_dwordx4 v[222:223], v[58:61], off offset:64
	global_store_dwordx4 v[246:247], v[38:41], off offset:64
	s_or_b64 exec, exec, s[46:47]
	v_pk_fma_f32 v[224:225], v[58:59], v[186:187], v[190:191]
	v_pk_fma_f32 v[226:227], v[60:61], v[188:189], v[192:193]
	v_pk_fma_f32 v[228:229], v[38:39], v[202:203], v[206:207]
	v_pk_fma_f32 v[230:231], v[40:41], v[204:205], v[208:209]
	v_fmac_f32_dpp v224, v58, v182 row_shr:1 row_mask:0xf bank_mask:0xf bound_ctrl:1
	v_fmac_f32_dpp v225, v59, v183 row_shr:1 row_mask:0xf bank_mask:0xf bound_ctrl:1
	v_fmac_f32_dpp v226, v60, v184 row_shr:1 row_mask:0xf bank_mask:0xf bound_ctrl:1
	v_fmac_f32_dpp v227, v61, v185 row_shr:1 row_mask:0xf bank_mask:0xf bound_ctrl:1
	v_fmac_f32_dpp v228, v38, v198 row_shr:1 row_mask:0xf bank_mask:0xf bound_ctrl:1
	v_fmac_f32_dpp v229, v39, v199 row_shr:1 row_mask:0xf bank_mask:0xf bound_ctrl:1
	v_fmac_f32_dpp v230, v40, v200 row_shr:1 row_mask:0xf bank_mask:0xf bound_ctrl:1
	v_fmac_f32_dpp v231, v41, v201 row_shr:1 row_mask:0xf bank_mask:0xf bound_ctrl:1
	v_fmac_f32_dpp v224, v58, v178 row_shr:2 row_mask:0xf bank_mask:0xf bound_ctrl:1
	v_fmac_f32_dpp v225, v59, v179 row_shr:2 row_mask:0xf bank_mask:0xf bound_ctrl:1
	v_fmac_f32_dpp v226, v60, v180 row_shr:2 row_mask:0xf bank_mask:0xf bound_ctrl:1
	v_fmac_f32_dpp v227, v61, v181 row_shr:2 row_mask:0xf bank_mask:0xf bound_ctrl:1
	v_fmac_f32_dpp v228, v38, v194 row_shr:2 row_mask:0xf bank_mask:0xf bound_ctrl:1
	v_fmac_f32_dpp v229, v39, v195 row_shr:2 row_mask:0xf bank_mask:0xf bound_ctrl:1
	v_fmac_f32_dpp v230, v40, v196 row_shr:2 row_mask:0xf bank_mask:0xf bound_ctrl:1
	v_fmac_f32_dpp v231, v41, v197 row_shr:2 row_mask:0xf bank_mask:0xf bound_ctrl:1
	v_pk_mul_f32 v[232:233], v[224:225], s[48:49] op_sel_hi:[1,0]
	v_pk_mul_f32 v[234:235], v[226:227], s[48:49] op_sel_hi:[1,0]
	v_exp_f32_e32 v232, v232
	v_exp_f32_e32 v233, v233
	v_exp_f32_e32 v234, v234
	v_exp_f32_e32 v235, v235
	s_nop 0
	v_pk_add_f32 v[232:233], v[232:233], 1.0 op_sel_hi:[1,0]
	v_pk_add_f32 v[234:235], v[234:235], 1.0 op_sel_hi:[1,0]
	v_rcp_f32_e32 v232, v232
	v_rcp_f32_e32 v233, v233
	v_rcp_f32_e32 v234, v234
	v_rcp_f32_e32 v235, v235
	s_nop 0
	v_pk_mul_f32 v[224:225], v[224:225], v[232:233]
	v_pk_mul_f32 v[226:227], v[226:227], v[234:235]
	v_pk_mul_f32 v[224:225], v[224:225], v[228:229]
	v_pk_mul_f32 v[226:227], v[226:227], v[230:231]
	s_nop 0
	v_cvt_pk_bf16_f32 v168, v224, v225
	v_cvt_pk_bf16_f32 v169, v226, v227
	s_and_saveexec_b64 s[46:47], s[8:9]
	global_store_dwordx2 v[220:221], v[168:169], off offset:32
	s_or_b64 exec, exec, s[46:47]
	v_pk_fma_f32 v[224:225], v[50:51], v[186:187], v[190:191]
	v_pk_fma_f32 v[226:227], v[52:53], v[188:189], v[192:193]
	v_pk_fma_f32 v[228:229], v[22:23], v[202:203], v[206:207]
	v_pk_fma_f32 v[230:231], v[24:25], v[204:205], v[208:209]
	v_fmac_f32_dpp v224, v50, v182 row_shr:1 row_mask:0xf bank_mask:0xf bound_ctrl:1
	v_fmac_f32_dpp v225, v51, v183 row_shr:1 row_mask:0xf bank_mask:0xf bound_ctrl:1
	v_fmac_f32_dpp v226, v52, v184 row_shr:1 row_mask:0xf bank_mask:0xf bound_ctrl:1
	v_fmac_f32_dpp v227, v53, v185 row_shr:1 row_mask:0xf bank_mask:0xf bound_ctrl:1
	v_fmac_f32_dpp v228, v22, v198 row_shr:1 row_mask:0xf bank_mask:0xf bound_ctrl:1
	v_fmac_f32_dpp v229, v23, v199 row_shr:1 row_mask:0xf bank_mask:0xf bound_ctrl:1
	v_fmac_f32_dpp v230, v24, v200 row_shr:1 row_mask:0xf bank_mask:0xf bound_ctrl:1
	v_fmac_f32_dpp v231, v25, v201 row_shr:1 row_mask:0xf bank_mask:0xf bound_ctrl:1
	v_fmac_f32_dpp v224, v50, v178 row_shr:2 row_mask:0xf bank_mask:0xf bound_ctrl:1
	v_fmac_f32_dpp v225, v51, v179 row_shr:2 row_mask:0xf bank_mask:0xf bound_ctrl:1
	v_fmac_f32_dpp v226, v52, v180 row_shr:2 row_mask:0xf bank_mask:0xf bound_ctrl:1
	v_fmac_f32_dpp v227, v53, v181 row_shr:2 row_mask:0xf bank_mask:0xf bound_ctrl:1
	v_fmac_f32_dpp v228, v22, v194 row_shr:2 row_mask:0xf bank_mask:0xf bound_ctrl:1
	v_fmac_f32_dpp v229, v23, v195 row_shr:2 row_mask:0xf bank_mask:0xf bound_ctrl:1
	v_fmac_f32_dpp v230, v24, v196 row_shr:2 row_mask:0xf bank_mask:0xf bound_ctrl:1
	v_fmac_f32_dpp v231, v25, v197 row_shr:2 row_mask:0xf bank_mask:0xf bound_ctrl:1
	v_fmac_f32_dpp v224, v58, v182 row_shl:15 row_mask:0xf bank_mask:0xf bound_ctrl:1
	v_fmac_f32_dpp v225, v59, v183 row_shl:15 row_mask:0xf bank_mask:0xf bound_ctrl:1
	v_fmac_f32_dpp v226, v60, v184 row_shl:15 row_mask:0xf bank_mask:0xf bound_ctrl:1
	v_fmac_f32_dpp v227, v61, v185 row_shl:15 row_mask:0xf bank_mask:0xf bound_ctrl:1
	v_fmac_f32_dpp v228, v38, v198 row_shl:15 row_mask:0xf bank_mask:0xf bound_ctrl:1
	v_fmac_f32_dpp v229, v39, v199 row_shl:15 row_mask:0xf bank_mask:0xf bound_ctrl:1
	v_fmac_f32_dpp v230, v40, v200 row_shl:15 row_mask:0xf bank_mask:0xf bound_ctrl:1
	v_fmac_f32_dpp v231, v41, v201 row_shl:15 row_mask:0xf bank_mask:0xf bound_ctrl:1
	v_fmac_f32_dpp v224, v58, v178 row_shl:14 row_mask:0xf bank_mask:0xf bound_ctrl:1
	v_fmac_f32_dpp v225, v59, v179 row_shl:14 row_mask:0xf bank_mask:0xf bound_ctrl:1
	v_fmac_f32_dpp v226, v60, v180 row_shl:14 row_mask:0xf bank_mask:0xf bound_ctrl:1
	v_fmac_f32_dpp v227, v61, v181 row_shl:14 row_mask:0xf bank_mask:0xf bound_ctrl:1
	v_fmac_f32_dpp v228, v38, v194 row_shl:14 row_mask:0xf bank_mask:0xf bound_ctrl:1
	v_fmac_f32_dpp v229, v39, v195 row_shl:14 row_mask:0xf bank_mask:0xf bound_ctrl:1
	v_fmac_f32_dpp v230, v40, v196 row_shl:14 row_mask:0xf bank_mask:0xf bound_ctrl:1
	v_fmac_f32_dpp v231, v41, v197 row_shl:14 row_mask:0xf bank_mask:0xf bound_ctrl:1
	v_pk_mul_f32 v[232:233], v[224:225], s[48:49] op_sel_hi:[1,0]
	v_pk_mul_f32 v[234:235], v[226:227], s[48:49] op_sel_hi:[1,0]
	v_exp_f32_e32 v232, v232
	v_exp_f32_e32 v233, v233
	v_exp_f32_e32 v234, v234
	v_exp_f32_e32 v235, v235
	s_nop 0
	v_pk_add_f32 v[232:233], v[232:233], 1.0 op_sel_hi:[1,0]
	v_pk_add_f32 v[234:235], v[234:235], 1.0 op_sel_hi:[1,0]
	v_rcp_f32_e32 v232, v232
	v_rcp_f32_e32 v233, v233
	v_rcp_f32_e32 v234, v234
	v_rcp_f32_e32 v235, v235
	v_lshl_add_u64 v[220:221], v[220:221], 0, s[96:97]
	v_pk_mul_f32 v[224:225], v[224:225], v[232:233]
	v_pk_mul_f32 v[226:227], v[226:227], v[234:235]
	v_pk_mul_f32 v[224:225], v[224:225], v[228:229]
	v_pk_mul_f32 v[226:227], v[226:227], v[230:231]
	s_nop 0
	v_cvt_pk_bf16_f32 v168, v224, v225
	v_cvt_pk_bf16_f32 v169, v226, v227
	global_store_dwordx2 v[220:221], v[168:169], off offset:32
	v_pk_fma_f32 v[224:225], v[34:35], v[186:187], v[190:191]
	v_pk_fma_f32 v[226:227], v[36:37], v[188:189], v[192:193]
	v_pk_fma_f32 v[228:229], v[10:11], v[202:203], v[206:207]
	v_pk_fma_f32 v[230:231], v[12:13], v[204:205], v[208:209]
	v_fmac_f32_dpp v224, v34, v182 row_shr:1 row_mask:0xf bank_mask:0xf bound_ctrl:1
	v_fmac_f32_dpp v225, v35, v183 row_shr:1 row_mask:0xf bank_mask:0xf bound_ctrl:1
	v_fmac_f32_dpp v226, v36, v184 row_shr:1 row_mask:0xf bank_mask:0xf bound_ctrl:1
	v_fmac_f32_dpp v227, v37, v185 row_shr:1 row_mask:0xf bank_mask:0xf bound_ctrl:1
	v_fmac_f32_dpp v228, v10, v198 row_shr:1 row_mask:0xf bank_mask:0xf bound_ctrl:1
	v_fmac_f32_dpp v229, v11, v199 row_shr:1 row_mask:0xf bank_mask:0xf bound_ctrl:1
	v_fmac_f32_dpp v230, v12, v200 row_shr:1 row_mask:0xf bank_mask:0xf bound_ctrl:1
	v_fmac_f32_dpp v231, v13, v201 row_shr:1 row_mask:0xf bank_mask:0xf bound_ctrl:1
	v_fmac_f32_dpp v224, v34, v178 row_shr:2 row_mask:0xf bank_mask:0xf bound_ctrl:1
	v_fmac_f32_dpp v225, v35, v179 row_shr:2 row_mask:0xf bank_mask:0xf bound_ctrl:1
	v_fmac_f32_dpp v226, v36, v180 row_shr:2 row_mask:0xf bank_mask:0xf bound_ctrl:1
	v_fmac_f32_dpp v227, v37, v181 row_shr:2 row_mask:0xf bank_mask:0xf bound_ctrl:1
	v_fmac_f32_dpp v228, v10, v194 row_shr:2 row_mask:0xf bank_mask:0xf bound_ctrl:1
	v_fmac_f32_dpp v229, v11, v195 row_shr:2 row_mask:0xf bank_mask:0xf bound_ctrl:1
	v_fmac_f32_dpp v230, v12, v196 row_shr:2 row_mask:0xf bank_mask:0xf bound_ctrl:1
	v_fmac_f32_dpp v231, v13, v197 row_shr:2 row_mask:0xf bank_mask:0xf bound_ctrl:1
	v_fmac_f32_dpp v224, v50, v182 row_shl:15 row_mask:0xf bank_mask:0xf bound_ctrl:1
	v_fmac_f32_dpp v225, v51, v183 row_shl:15 row_mask:0xf bank_mask:0xf bound_ctrl:1
	v_fmac_f32_dpp v226, v52, v184 row_shl:15 row_mask:0xf bank_mask:0xf bound_ctrl:1
	v_fmac_f32_dpp v227, v53, v185 row_shl:15 row_mask:0xf bank_mask:0xf bound_ctrl:1
	v_fmac_f32_dpp v228, v22, v198 row_shl:15 row_mask:0xf bank_mask:0xf bound_ctrl:1
	v_fmac_f32_dpp v229, v23, v199 row_shl:15 row_mask:0xf bank_mask:0xf bound_ctrl:1
	v_fmac_f32_dpp v230, v24, v200 row_shl:15 row_mask:0xf bank_mask:0xf bound_ctrl:1
	v_fmac_f32_dpp v231, v25, v201 row_shl:15 row_mask:0xf bank_mask:0xf bound_ctrl:1
	v_fmac_f32_dpp v224, v50, v178 row_shl:14 row_mask:0xf bank_mask:0xf bound_ctrl:1
	v_fmac_f32_dpp v225, v51, v179 row_shl:14 row_mask:0xf bank_mask:0xf bound_ctrl:1
	v_fmac_f32_dpp v226, v52, v180 row_shl:14 row_mask:0xf bank_mask:0xf bound_ctrl:1
	v_fmac_f32_dpp v227, v53, v181 row_shl:14 row_mask:0xf bank_mask:0xf bound_ctrl:1
	v_fmac_f32_dpp v228, v22, v194 row_shl:14 row_mask:0xf bank_mask:0xf bound_ctrl:1
	v_fmac_f32_dpp v229, v23, v195 row_shl:14 row_mask:0xf bank_mask:0xf bound_ctrl:1
	v_fmac_f32_dpp v230, v24, v196 row_shl:14 row_mask:0xf bank_mask:0xf bound_ctrl:1
	v_fmac_f32_dpp v231, v25, v197 row_shl:14 row_mask:0xf bank_mask:0xf bound_ctrl:1
	v_pk_mul_f32 v[232:233], v[224:225], s[48:49] op_sel_hi:[1,0]
	v_pk_mul_f32 v[234:235], v[226:227], s[48:49] op_sel_hi:[1,0]
	v_exp_f32_e32 v232, v232
	v_exp_f32_e32 v233, v233
	v_exp_f32_e32 v234, v234
	v_exp_f32_e32 v235, v235
	s_nop 0
	v_pk_add_f32 v[232:233], v[232:233], 1.0 op_sel_hi:[1,0]
	v_pk_add_f32 v[234:235], v[234:235], 1.0 op_sel_hi:[1,0]
	v_rcp_f32_e32 v232, v232
	v_rcp_f32_e32 v233, v233
	v_rcp_f32_e32 v234, v234
	v_rcp_f32_e32 v235, v235
	v_lshl_add_u64 v[220:221], v[220:221], 0, s[96:97]
	v_pk_mul_f32 v[224:225], v[224:225], v[232:233]
	v_pk_mul_f32 v[226:227], v[226:227], v[234:235]
	v_pk_mul_f32 v[224:225], v[224:225], v[228:229]
	v_pk_mul_f32 v[226:227], v[226:227], v[230:231]
	s_nop 0
	v_cvt_pk_bf16_f32 v168, v224, v225
	v_cvt_pk_bf16_f32 v169, v226, v227
	global_store_dwordx2 v[220:221], v[168:169], off offset:32
	s_add_u32 s94, s26, s85
	s_addc_u32 s95, s27, 0
	v_lshl_add_u64 v[222:223], s[94:95], 0, v[216:217]
	v_lshl_add_u64 v[246:247], s[94:95], 0, v[218:219]
	s_and_saveexec_b64 s[46:47], s[6:7]
	global_store_dwordx4 v[222:223], v[18:21], off offset:64
	global_store_dwordx4 v[246:247], v[2:5], off offset:64
	s_or_b64 exec, exec, s[46:47]
	v_pk_fma_f32 v[224:225], v[18:19], v[186:187], v[190:191]
	v_pk_fma_f32 v[226:227], v[20:21], v[188:189], v[192:193]
	v_pk_fma_f32 v[228:229], v[2:3], v[202:203], v[206:207]
	v_pk_fma_f32 v[230:231], v[4:5], v[204:205], v[208:209]
	v_fmac_f32_dpp v224, v18, v182 row_shr:1 row_mask:0xf bank_mask:0xf bound_ctrl:1
	v_fmac_f32_dpp v225, v19, v183 row_shr:1 row_mask:0xf bank_mask:0xf bound_ctrl:1
	v_fmac_f32_dpp v226, v20, v184 row_shr:1 row_mask:0xf bank_mask:0xf bound_ctrl:1
	v_fmac_f32_dpp v227, v21, v185 row_shr:1 row_mask:0xf bank_mask:0xf bound_ctrl:1
	v_fmac_f32_dpp v228, v2, v198 row_shr:1 row_mask:0xf bank_mask:0xf bound_ctrl:1
	v_fmac_f32_dpp v229, v3, v199 row_shr:1 row_mask:0xf bank_mask:0xf bound_ctrl:1
	v_fmac_f32_dpp v230, v4, v200 row_shr:1 row_mask:0xf bank_mask:0xf bound_ctrl:1
	v_fmac_f32_dpp v231, v5, v201 row_shr:1 row_mask:0xf bank_mask:0xf bound_ctrl:1
	v_fmac_f32_dpp v224, v18, v178 row_shr:2 row_mask:0xf bank_mask:0xf bound_ctrl:1
	v_fmac_f32_dpp v225, v19, v179 row_shr:2 row_mask:0xf bank_mask:0xf bound_ctrl:1
	v_fmac_f32_dpp v226, v20, v180 row_shr:2 row_mask:0xf bank_mask:0xf bound_ctrl:1
	v_fmac_f32_dpp v227, v21, v181 row_shr:2 row_mask:0xf bank_mask:0xf bound_ctrl:1
	v_fmac_f32_dpp v228, v2, v194 row_shr:2 row_mask:0xf bank_mask:0xf bound_ctrl:1
	v_fmac_f32_dpp v229, v3, v195 row_shr:2 row_mask:0xf bank_mask:0xf bound_ctrl:1
	v_fmac_f32_dpp v230, v4, v196 row_shr:2 row_mask:0xf bank_mask:0xf bound_ctrl:1
	v_fmac_f32_dpp v231, v5, v197 row_shr:2 row_mask:0xf bank_mask:0xf bound_ctrl:1
	v_fmac_f32_dpp v224, v34, v182 row_shl:15 row_mask:0xf bank_mask:0xf bound_ctrl:1
	v_fmac_f32_dpp v225, v35, v183 row_shl:15 row_mask:0xf bank_mask:0xf bound_ctrl:1
	v_fmac_f32_dpp v226, v36, v184 row_shl:15 row_mask:0xf bank_mask:0xf bound_ctrl:1
	v_fmac_f32_dpp v227, v37, v185 row_shl:15 row_mask:0xf bank_mask:0xf bound_ctrl:1
	v_fmac_f32_dpp v228, v10, v198 row_shl:15 row_mask:0xf bank_mask:0xf bound_ctrl:1
	v_fmac_f32_dpp v229, v11, v199 row_shl:15 row_mask:0xf bank_mask:0xf bound_ctrl:1
	v_fmac_f32_dpp v230, v12, v200 row_shl:15 row_mask:0xf bank_mask:0xf bound_ctrl:1
	v_fmac_f32_dpp v231, v13, v201 row_shl:15 row_mask:0xf bank_mask:0xf bound_ctrl:1
	v_fmac_f32_dpp v224, v34, v178 row_shl:14 row_mask:0xf bank_mask:0xf bound_ctrl:1
	v_fmac_f32_dpp v225, v35, v179 row_shl:14 row_mask:0xf bank_mask:0xf bound_ctrl:1
	v_fmac_f32_dpp v226, v36, v180 row_shl:14 row_mask:0xf bank_mask:0xf bound_ctrl:1
	v_fmac_f32_dpp v227, v37, v181 row_shl:14 row_mask:0xf bank_mask:0xf bound_ctrl:1
	v_fmac_f32_dpp v228, v10, v194 row_shl:14 row_mask:0xf bank_mask:0xf bound_ctrl:1
	v_fmac_f32_dpp v229, v11, v195 row_shl:14 row_mask:0xf bank_mask:0xf bound_ctrl:1
	v_fmac_f32_dpp v230, v12, v196 row_shl:14 row_mask:0xf bank_mask:0xf bound_ctrl:1
	v_fmac_f32_dpp v231, v13, v197 row_shl:14 row_mask:0xf bank_mask:0xf bound_ctrl:1
	v_pk_mul_f32 v[232:233], v[224:225], s[48:49] op_sel_hi:[1,0]
	v_pk_mul_f32 v[234:235], v[226:227], s[48:49] op_sel_hi:[1,0]
	v_exp_f32_e32 v232, v232
	v_exp_f32_e32 v233, v233
	v_exp_f32_e32 v234, v234
	v_exp_f32_e32 v235, v235
	s_nop 0
	v_pk_add_f32 v[232:233], v[232:233], 1.0 op_sel_hi:[1,0]
	v_pk_add_f32 v[234:235], v[234:235], 1.0 op_sel_hi:[1,0]
	v_rcp_f32_e32 v232, v232
	v_rcp_f32_e32 v233, v233
	v_rcp_f32_e32 v234, v234
	v_rcp_f32_e32 v235, v235
	v_lshl_add_u64 v[220:221], v[220:221], 0, s[96:97]
	v_pk_mul_f32 v[224:225], v[224:225], v[232:233]
	v_pk_mul_f32 v[226:227], v[226:227], v[234:235]
	v_pk_mul_f32 v[224:225], v[224:225], v[228:229]
	v_pk_mul_f32 v[226:227], v[226:227], v[230:231]
	s_nop 0
	v_cvt_pk_bf16_f32 v168, v224, v225
	v_cvt_pk_bf16_f32 v169, v226, v227
	global_store_dwordx2 v[220:221], v[168:169], off offset:32
	s_branch .LBB0_1094

.LBB0_1296:
	s_add_u32 s28, s28, 0x160080
	s_addc_u32 s29, s29, 0
	s_add_u32 s58, s30, 0x100
	s_addc_u32 s59, s31, 0
	s_mov_b32 s60, -2
	ds_read_b128 v[126:129], v175
	ds_read_b128 v[134:137], v175 offset:1024
	ds_read_b128 v[138:141], v175 offset:2048
	ds_read_b128 v[142:145], v175 offset:3072
	s_add_u32 s30, s28, 0xffea0080
	s_addc_u32 s31, s29, -1
	s_cmpk_eq_i32 s60, 0x54
	s_cselect_b32 s35, s7, s31
	s_cselect_b32 s34, s6, s30
	s_cselect_b32 s31, s9, s59
	s_cselect_b32 s30, s8, s58
	v_lshl_add_u64 v[162:163], s[28:29], 0, v[150:151]
	s_add_i32 m0, s43, 0xc000
	ds_read_b128 v[158:161], v176
	ds_read_b128 v[178:181], v176 offset:1024
	ds_read_b128 v[182:185], v176 offset:2048
	ds_read_b128 v[186:189], v176 offset:3072
	ds_read_b128 v[190:193], v176 offset:4096
	ds_read_b128 v[194:197], v176 offset:5120
	ds_read_b128 v[198:201], v176 offset:6144
	ds_read_b128 v[202:205], v176 offset:7168
	global_load_lds_dwordx4 v[162:163], off
	v_lshl_add_u64 v[162:163], s[28:29], 0, v[152:153]
	s_add_i32 m0, s43, 0xe000
	s_nop 0
	global_load_lds_dwordx4 v[162:163], off
	s_waitcnt lgkmcnt(8)
	s_barrier
	s_waitcnt lgkmcnt(0)
	s_setprio 1
	s_waitcnt lgkmcnt(0)
	v_mfma_f32_16x16x32_bf16 v[130:133], v[126:129], v[158:161], 0
	v_mfma_f32_16x16x32_bf16 v[122:125], v[138:141], v[158:161], 0
	v_mfma_f32_16x16x32_bf16 v[118:121], v[126:129], v[182:185], 0
	v_mfma_f32_16x16x32_bf16 v[114:117], v[138:141], v[182:185], 0
	v_mfma_f32_16x16x32_bf16 v[102:105], v[126:129], v[190:193], 0
	v_mfma_f32_16x16x32_bf16 v[98:101], v[138:141], v[190:193], 0
	v_mfma_f32_16x16x32_bf16 v[86:89], v[126:129], v[198:201], 0
	v_mfma_f32_16x16x32_bf16 v[82:85], v[138:141], v[198:201], 0
	v_mfma_f32_16x16x32_bf16 v[130:133], v[134:137], v[178:181], v[130:133]
	v_mfma_f32_16x16x32_bf16 v[122:125], v[142:145], v[178:181], v[122:125]
	v_mfma_f32_16x16x32_bf16 v[118:121], v[134:137], v[186:189], v[118:121]
	v_mfma_f32_16x16x32_bf16 v[114:117], v[142:145], v[186:189], v[114:117]
	v_mfma_f32_16x16x32_bf16 v[102:105], v[134:137], v[194:197], v[102:105]
	v_mfma_f32_16x16x32_bf16 v[98:101], v[142:145], v[194:197], v[98:101]
	v_mfma_f32_16x16x32_bf16 v[86:89], v[134:137], v[202:205], v[86:89]
	v_mfma_f32_16x16x32_bf16 v[82:85], v[142:145], v[202:205], v[82:85]
	s_setprio 0
	s_barrier
	s_add_i32 s61, s51, s40
	v_lshl_add_u64 v[162:163], s[30:31], 0, v[146:147]
	s_mov_b32 m0, s61
	ds_read_b128 v[206:209], v177
	ds_read_b128 v[210:213], v177 offset:1024
	ds_read_b128 v[214:217], v177 offset:2048
	ds_read_b128 v[218:221], v177 offset:3072
	global_load_lds_dwordx4 v[162:163], off
	v_lshl_add_u64 v[168:169], s[30:31], 0, v[148:149]
	s_add_i32 m0, s61, 0x2000
	s_nop 0
	global_load_lds_dwordx4 v[168:169], off
	s_barrier
	s_waitcnt lgkmcnt(0)
	s_setprio 1
	s_waitcnt lgkmcnt(0)
	v_mfma_f32_16x16x32_bf16 v[110:113], v[206:209], v[158:161], 0
	v_mfma_f32_16x16x32_bf16 v[106:109], v[214:217], v[158:161], 0
	v_mfma_f32_16x16x32_bf16 v[94:97], v[206:209], v[182:185], 0
	v_mfma_f32_16x16x32_bf16 v[90:93], v[214:217], v[182:185], 0
	v_mfma_f32_16x16x32_bf16 v[78:81], v[206:209], v[190:193], 0
	v_mfma_f32_16x16x32_bf16 v[74:77], v[214:217], v[190:193], 0
	v_mfma_f32_16x16x32_bf16 v[70:73], v[206:209], v[198:201], 0
	v_mfma_f32_16x16x32_bf16 v[66:69], v[214:217], v[198:201], 0
	v_mfma_f32_16x16x32_bf16 v[110:113], v[210:213], v[178:181], v[110:113]
	v_mfma_f32_16x16x32_bf16 v[106:109], v[218:221], v[178:181], v[106:109]
	v_mfma_f32_16x16x32_bf16 v[94:97], v[210:213], v[186:189], v[94:97]
	v_mfma_f32_16x16x32_bf16 v[90:93], v[218:221], v[186:189], v[90:93]
	v_mfma_f32_16x16x32_bf16 v[78:81], v[210:213], v[194:197], v[78:81]
	v_mfma_f32_16x16x32_bf16 v[74:77], v[218:221], v[194:197], v[74:77]
	v_mfma_f32_16x16x32_bf16 v[70:73], v[210:213], v[202:205], v[70:73]
	v_mfma_f32_16x16x32_bf16 v[66:69], v[218:221], v[202:205], v[66:69]
	s_setprio 0
	s_mov_b32 m0, s43
	v_lshl_add_u64 v[222:223], s[34:35], 0, v[146:147]
	s_barrier
	ds_read_b128 v[158:161], v176 offset:16384
	ds_read_b128 v[178:181], v176 offset:17408
	ds_read_b128 v[182:185], v176 offset:18432
	ds_read_b128 v[186:189], v176 offset:19456
	ds_read_b128 v[190:193], v176 offset:20480
	ds_read_b128 v[194:197], v176 offset:21504
	ds_read_b128 v[198:201], v176 offset:22528
	ds_read_b128 v[202:205], v176 offset:23552
	global_load_lds_dwordx4 v[222:223], off
	v_lshl_add_u64 v[224:225], s[34:35], 0, v[148:149]
	s_mov_b32 m0, s44
	s_nop 0
	global_load_lds_dwordx4 v[224:225], off
	s_barrier
	s_waitcnt lgkmcnt(0)
	s_setprio 1
	s_waitcnt lgkmcnt(0)
	v_mfma_f32_16x16x32_bf16 v[62:65], v[126:129], v[158:161], 0
	v_mfma_f32_16x16x32_bf16 v[58:61], v[138:141], v[158:161], 0
	v_mfma_f32_16x16x32_bf16 v[54:57], v[126:129], v[182:185], 0
	v_mfma_f32_16x16x32_bf16 v[46:49], v[138:141], v[182:185], 0
	v_mfma_f32_16x16x32_bf16 v[38:41], v[126:129], v[190:193], 0
	v_mfma_f32_16x16x32_bf16 v[30:33], v[138:141], v[190:193], 0
	v_mfma_f32_16x16x32_bf16 v[22:25], v[126:129], v[198:201], 0
	v_mfma_f32_16x16x32_bf16 v[14:17], v[138:141], v[198:201], 0
	v_mfma_f32_16x16x32_bf16 v[62:65], v[134:137], v[178:181], v[62:65]
	v_mfma_f32_16x16x32_bf16 v[58:61], v[142:145], v[178:181], v[58:61]
	v_mfma_f32_16x16x32_bf16 v[54:57], v[134:137], v[186:189], v[54:57]
	v_mfma_f32_16x16x32_bf16 v[46:49], v[142:145], v[186:189], v[46:49]
	v_mfma_f32_16x16x32_bf16 v[38:41], v[134:137], v[194:197], v[38:41]
	v_mfma_f32_16x16x32_bf16 v[30:33], v[142:145], v[194:197], v[30:33]
	v_mfma_f32_16x16x32_bf16 v[22:25], v[134:137], v[202:205], v[22:25]
	v_mfma_f32_16x16x32_bf16 v[14:17], v[142:145], v[202:205], v[14:17]
	s_setprio 0
	s_barrier
	s_add_u32 s62, s30, 0x160000
	s_addc_u32 s63, s31, 0
	s_add_i32 s61, s52, s40
	v_lshl_add_u64 v[126:127], s[62:63], 0, v[146:147]
	s_mov_b32 m0, s61
	s_nop 0
	global_load_lds_dwordx4 v[126:127], off
	v_lshl_add_u64 v[126:127], s[62:63], 0, v[148:149]
	s_add_i32 m0, s61, 0x2000
	s_nop 0
	global_load_lds_dwordx4 v[126:127], off
	s_waitcnt vmcnt(6)
	s_barrier
	s_setprio 1
	v_mfma_f32_16x16x32_bf16 v[50:53], v[206:209], v[158:161], 0
	v_mfma_f32_16x16x32_bf16 v[42:45], v[214:217], v[158:161], 0
	v_mfma_f32_16x16x32_bf16 v[34:37], v[206:209], v[182:185], 0
	v_mfma_f32_16x16x32_bf16 v[26:29], v[214:217], v[182:185], 0
	v_mfma_f32_16x16x32_bf16 v[18:21], v[206:209], v[190:193], 0
	v_mfma_f32_16x16x32_bf16 v[10:13], v[214:217], v[190:193], 0
	v_mfma_f32_16x16x32_bf16 v[6:9], v[206:209], v[198:201], 0
	v_mfma_f32_16x16x32_bf16 v[2:5], v[214:217], v[198:201], 0
	v_mfma_f32_16x16x32_bf16 v[50:53], v[210:213], v[178:181], v[50:53]
	v_mfma_f32_16x16x32_bf16 v[42:45], v[218:221], v[178:181], v[42:45]
	v_mfma_f32_16x16x32_bf16 v[34:37], v[210:213], v[186:189], v[34:37]
	v_mfma_f32_16x16x32_bf16 v[26:29], v[218:221], v[186:189], v[26:29]
	v_mfma_f32_16x16x32_bf16 v[18:21], v[210:213], v[194:197], v[18:21]
	v_mfma_f32_16x16x32_bf16 v[10:13], v[218:221], v[194:197], v[10:13]
	v_mfma_f32_16x16x32_bf16 v[6:9], v[210:213], v[202:205], v[6:9]
	v_mfma_f32_16x16x32_bf16 v[2:5], v[218:221], v[202:205], v[2:5]
	s_setprio 0
	s_add_i32 s61, 0, 0x18000
	v_add_u32_e32 v142, s61, v173
	s_barrier
	ds_read_b128 v[126:129], v142
	ds_read_b128 v[134:137], v142 offset:1024
	ds_read_b128 v[138:141], v142 offset:2048
	ds_read_b128 v[142:145], v142 offset:3072
	s_add_u32 s34, s34, 0x160000
	s_addc_u32 s35, s35, 0
	s_mov_b32 m0, s45
	v_lshl_add_u64 v[206:207], s[34:35], 0, v[146:147]
	ds_read_b128 v[158:161], v176 offset:32768
	ds_read_b128 v[178:181], v176 offset:33792
	ds_read_b128 v[182:185], v176 offset:34816
	ds_read_b128 v[186:189], v176 offset:35840
	ds_read_b128 v[190:193], v176 offset:36864
	ds_read_b128 v[194:197], v176 offset:37888
	ds_read_b128 v[198:201], v176 offset:38912
	ds_read_b128 v[202:205], v176 offset:39936
	global_load_lds_dwordx4 v[206:207], off
	v_lshl_add_u64 v[206:207], s[34:35], 0, v[148:149]
	s_mov_b32 m0, s46
	s_nop 0
	global_load_lds_dwordx4 v[206:207], off
	s_waitcnt lgkmcnt(8)
	s_barrier
	s_waitcnt lgkmcnt(0)
	s_setprio 1
	s_waitcnt lgkmcnt(0)
	v_mfma_f32_16x16x32_bf16 v[130:133], v[126:129], v[158:161], v[130:133]
	v_mfma_f32_16x16x32_bf16 v[122:125], v[138:141], v[158:161], v[122:125]
	v_mfma_f32_16x16x32_bf16 v[118:121], v[126:129], v[182:185], v[118:121]
	v_mfma_f32_16x16x32_bf16 v[114:117], v[138:141], v[182:185], v[114:117]
	v_mfma_f32_16x16x32_bf16 v[102:105], v[126:129], v[190:193], v[102:105]
	v_mfma_f32_16x16x32_bf16 v[98:101], v[138:141], v[190:193], v[98:101]
	v_mfma_f32_16x16x32_bf16 v[86:89], v[126:129], v[198:201], v[86:89]
	v_mfma_f32_16x16x32_bf16 v[82:85], v[138:141], v[198:201], v[82:85]
	v_mfma_f32_16x16x32_bf16 v[130:133], v[134:137], v[178:181], v[130:133]
	v_mfma_f32_16x16x32_bf16 v[122:125], v[142:145], v[178:181], v[122:125]
	v_mfma_f32_16x16x32_bf16 v[118:121], v[134:137], v[186:189], v[118:121]
	v_mfma_f32_16x16x32_bf16 v[114:117], v[142:145], v[186:189], v[114:117]
	v_mfma_f32_16x16x32_bf16 v[102:105], v[134:137], v[194:197], v[102:105]
	v_mfma_f32_16x16x32_bf16 v[98:101], v[142:145], v[194:197], v[98:101]
	v_mfma_f32_16x16x32_bf16 v[86:89], v[134:137], v[202:205], v[86:89]
	v_mfma_f32_16x16x32_bf16 v[82:85], v[142:145], v[202:205], v[82:85]
	s_setprio 0
	s_barrier
	s_add_i32 s34, 0, 0x1c000
	s_add_i32 s35, s61, s40
	v_add_u32_e32 v218, s34, v173
	v_lshl_add_u64 v[162:163], v[162:163], 0, s[18:19]
	s_mov_b32 m0, s35
	ds_read_b128 v[206:209], v218
	ds_read_b128 v[210:213], v218 offset:1024
	ds_read_b128 v[214:217], v218 offset:2048
	ds_read_b128 v[218:221], v218 offset:3072
	global_load_lds_dwordx4 v[162:163], off
	v_lshl_add_u64 v[162:163], v[168:169], 0, s[18:19]
	s_add_i32 m0, s35, 0x2000
	s_nop 0
	global_load_lds_dwordx4 v[162:163], off
	s_barrier
	s_waitcnt lgkmcnt(0)
	s_setprio 1
	s_waitcnt lgkmcnt(0)
	v_mfma_f32_16x16x32_bf16 v[110:113], v[206:209], v[158:161], v[110:113]
	v_mfma_f32_16x16x32_bf16 v[106:109], v[214:217], v[158:161], v[106:109]
	v_mfma_f32_16x16x32_bf16 v[94:97], v[206:209], v[182:185], v[94:97]
	v_mfma_f32_16x16x32_bf16 v[90:93], v[214:217], v[182:185], v[90:93]
	v_mfma_f32_16x16x32_bf16 v[78:81], v[206:209], v[190:193], v[78:81]
	v_mfma_f32_16x16x32_bf16 v[74:77], v[214:217], v[190:193], v[74:77]
	v_mfma_f32_16x16x32_bf16 v[70:73], v[206:209], v[198:201], v[70:73]
	v_mfma_f32_16x16x32_bf16 v[66:69], v[214:217], v[198:201], v[66:69]
	v_mfma_f32_16x16x32_bf16 v[110:113], v[210:213], v[178:181], v[110:113]
	v_mfma_f32_16x16x32_bf16 v[106:109], v[218:221], v[178:181], v[106:109]
	v_mfma_f32_16x16x32_bf16 v[94:97], v[210:213], v[186:189], v[94:97]
	v_mfma_f32_16x16x32_bf16 v[90:93], v[218:221], v[186:189], v[90:93]
	v_mfma_f32_16x16x32_bf16 v[78:81], v[210:213], v[194:197], v[78:81]
	v_mfma_f32_16x16x32_bf16 v[74:77], v[218:221], v[194:197], v[74:77]
	v_mfma_f32_16x16x32_bf16 v[70:73], v[210:213], v[202:205], v[70:73]
	v_mfma_f32_16x16x32_bf16 v[66:69], v[218:221], v[202:205], v[66:69]
	s_setprio 0
	s_mov_b32 m0, s48
	v_lshl_add_u64 v[162:163], v[222:223], 0, s[18:19]
	s_barrier
	ds_read_b128 v[158:161], v176 offset:49152
	ds_read_b128 v[178:181], v176 offset:50176
	ds_read_b128 v[182:185], v176 offset:51200
	ds_read_b128 v[186:189], v176 offset:52224
	ds_read_b128 v[190:193], v176 offset:53248
	ds_read_b128 v[194:197], v176 offset:54272
	ds_read_b128 v[198:201], v176 offset:55296
	ds_read_b128 v[202:205], v176 offset:56320
	global_load_lds_dwordx4 v[162:163], off
	v_lshl_add_u64 v[162:163], v[224:225], 0, s[18:19]
	s_mov_b32 m0, s49
	s_nop 0
	global_load_lds_dwordx4 v[162:163], off
	s_barrier
	s_waitcnt lgkmcnt(0)
	s_setprio 1
	s_waitcnt lgkmcnt(0)
	v_mfma_f32_16x16x32_bf16 v[62:65], v[126:129], v[158:161], v[62:65]
	v_mfma_f32_16x16x32_bf16 v[58:61], v[138:141], v[158:161], v[58:61]
	v_mfma_f32_16x16x32_bf16 v[54:57], v[126:129], v[182:185], v[54:57]
	v_mfma_f32_16x16x32_bf16 v[46:49], v[138:141], v[182:185], v[46:49]
	v_mfma_f32_16x16x32_bf16 v[38:41], v[126:129], v[190:193], v[38:41]
	v_mfma_f32_16x16x32_bf16 v[30:33], v[138:141], v[190:193], v[30:33]
	v_mfma_f32_16x16x32_bf16 v[22:25], v[126:129], v[198:201], v[22:25]
	v_mfma_f32_16x16x32_bf16 v[14:17], v[138:141], v[198:201], v[14:17]
	v_mfma_f32_16x16x32_bf16 v[62:65], v[134:137], v[178:181], v[62:65]
	v_mfma_f32_16x16x32_bf16 v[58:61], v[142:145], v[178:181], v[58:61]
	v_mfma_f32_16x16x32_bf16 v[54:57], v[134:137], v[186:189], v[54:57]
	v_mfma_f32_16x16x32_bf16 v[46:49], v[142:145], v[186:189], v[46:49]
	v_mfma_f32_16x16x32_bf16 v[38:41], v[134:137], v[194:197], v[38:41]
	v_mfma_f32_16x16x32_bf16 v[30:33], v[142:145], v[194:197], v[30:33]
	v_mfma_f32_16x16x32_bf16 v[22:25], v[134:137], v[202:205], v[22:25]
	v_mfma_f32_16x16x32_bf16 v[14:17], v[142:145], v[202:205], v[14:17]
	s_setprio 0
	s_barrier
	s_add_u32 s30, s30, 0x160080
	s_addc_u32 s31, s31, 0
	s_add_i32 s34, s34, s40
	v_lshl_add_u64 v[126:127], s[30:31], 0, v[146:147]
	s_mov_b32 m0, s34
	s_nop 0
	global_load_lds_dwordx4 v[126:127], off
	v_lshl_add_u64 v[126:127], s[30:31], 0, v[148:149]
	s_add_i32 m0, s34, 0x2000
	s_nop 0
	global_load_lds_dwordx4 v[126:127], off
	s_waitcnt vmcnt(6)
	s_barrier
	s_setprio 1
	v_mfma_f32_16x16x32_bf16 v[50:53], v[206:209], v[158:161], v[50:53]
	v_mfma_f32_16x16x32_bf16 v[42:45], v[214:217], v[158:161], v[42:45]
	v_mfma_f32_16x16x32_bf16 v[34:37], v[206:209], v[182:185], v[34:37]
	v_mfma_f32_16x16x32_bf16 v[26:29], v[214:217], v[182:185], v[26:29]
	v_mfma_f32_16x16x32_bf16 v[18:21], v[206:209], v[190:193], v[18:21]
	v_mfma_f32_16x16x32_bf16 v[10:13], v[214:217], v[190:193], v[10:13]
	v_mfma_f32_16x16x32_bf16 v[6:9], v[206:209], v[198:201], v[6:9]
	v_mfma_f32_16x16x32_bf16 v[2:5], v[214:217], v[198:201], v[2:5]
	v_mfma_f32_16x16x32_bf16 v[50:53], v[210:213], v[178:181], v[50:53]
	v_mfma_f32_16x16x32_bf16 v[42:45], v[218:221], v[178:181], v[42:45]
	v_mfma_f32_16x16x32_bf16 v[34:37], v[210:213], v[186:189], v[34:37]
	v_mfma_f32_16x16x32_bf16 v[26:29], v[218:221], v[186:189], v[26:29]
	v_mfma_f32_16x16x32_bf16 v[18:21], v[210:213], v[194:197], v[18:21]
	v_mfma_f32_16x16x32_bf16 v[10:13], v[218:221], v[194:197], v[10:13]
	v_mfma_f32_16x16x32_bf16 v[6:9], v[210:213], v[202:205], v[6:9]
	v_mfma_f32_16x16x32_bf16 v[2:5], v[218:221], v[202:205], v[2:5]
	s_setprio 0
	s_add_i32 s60, s60, 2
	s_add_u32 s28, s28, 0x100
	s_addc_u32 s29, s29, 0
	s_add_u32 s58, s58, 0x100
	s_addc_u32 s59, s59, 0
	s_cmpk_gt_u32 s60, 0x55
	s_barrier
	s_cbranch_scc0 .LBB0_1297
	s_branch .Lp10_loop_exit

.Lp10_loop_exit:
	s_lshl_b32 s30, s56, 8
	s_add_i32 s29, s30, 0xffffc000
	s_lshr_b32 s29, s29, 4
	s_ashr_i32 s28, s56, 4
	s_or_b32 s29, s29, 4
	s_cmp_lt_i32 s56, 64
	s_cselect_b32 s28, s28, s29
	v_lshl_or_b32 v126, s57, 8, v174
	s_mul_hi_i32 s29, s28, 0xc000
	s_mul_i32 s28, s28, 0xc000
	v_add_u32_e32 v168, s30, v172
	s_add_u32 s28, s12, s28
	v_ashrrev_i32_e32 v127, 31, v126
	v_ashrrev_i32_e32 v169, 31, v168
	s_addc_u32 s29, s13, s29
	v_lshlrev_b64 v[158:159], 2, v[126:127]
	v_lshlrev_b64 v[162:163], 13, v[168:169]
	v_or_b32_e32 v194, 16, v168
	v_or_b32_e32 v210, 32, v168
	v_or_b32_e32 v168, 48, v168
	v_lshl_add_u64 v[126:127], s[28:29], 0, v[158:159]
	v_ashrrev_i32_e32 v195, 31, v194
	v_ashrrev_i32_e32 v211, 31, v210
	v_ashrrev_i32_e32 v169, 31, v168
	v_lshl_add_u64 v[128:129], v[126:127], 0, s[20:21]
	v_add_co_u32_e32 v126, vcc, s53, v126
	v_lshl_add_u64 v[160:161], s[14:15], 0, v[158:159]
	v_lshlrev_b64 v[242:243], 13, v[194:195]
	v_lshlrev_b64 v[244:245], 13, v[210:211]
	v_lshlrev_b64 v[168:169], 13, v[168:169]
	v_addc_co_u32_e32 v127, vcc, 0, v127, vcc
	v_lshl_add_u64 v[190:191], v[160:161], 0, v[162:163]
	v_lshl_add_u64 v[206:207], v[160:161], 0, v[242:243]
	v_lshl_add_u64 v[222:223], v[160:161], 0, v[244:245]
	v_lshl_add_u64 v[238:239], v[160:161], 0, v[168:169]
	global_load_dwordx4 v[138:141], v[128:129], off offset:64
	global_load_dwordx4 v[134:137], v[128:129], off offset:512
	global_load_dwordx4 v[142:145], v[126:127], off
	s_nop 0
	global_load_dwordx4 v[126:129], v[128:129], off offset:576
	s_nop 0
	global_load_dwordx4 v[178:181], v[190:191], off
	global_load_dwordx4 v[182:185], v[190:191], off offset:64
	global_load_dwordx4 v[186:189], v[190:191], off offset:512
	s_nop 0
	global_load_dwordx4 v[190:193], v[190:191], off offset:576
	s_nop 0
	global_load_dwordx4 v[194:197], v[206:207], off
	global_load_dwordx4 v[198:201], v[206:207], off offset:64
	global_load_dwordx4 v[202:205], v[206:207], off offset:512
	s_nop 0
	global_load_dwordx4 v[206:209], v[206:207], off offset:576
	s_nop 0
	global_load_dwordx4 v[210:213], v[222:223], off
	global_load_dwordx4 v[214:217], v[222:223], off offset:64
	global_load_dwordx4 v[218:221], v[222:223], off offset:512
	s_nop 0
	global_load_dwordx4 v[222:225], v[222:223], off offset:576
	s_nop 0
	global_load_dwordx4 v[226:229], v[238:239], off
	global_load_dwordx4 v[230:233], v[238:239], off offset:64
	global_load_dwordx4 v[234:237], v[238:239], off offset:512
	s_nop 0
	global_load_dwordx4 v[238:241], v[238:239], off offset:576
	v_lshl_add_u64 v[246:247], s[14:15], 0, v[162:163]
	v_lshl_add_u64 v[246:247], v[246:247], 0, v[158:159]
	s_waitcnt vmcnt(0)
	v_pk_fma_f32 v[108:109], v[108:109], v[128:129], v[192:193]
	v_pk_fma_f32 v[106:107], v[106:107], v[126:127], v[190:191]
	v_pk_fma_f32 v[112:113], v[112:113], v[136:137], v[188:189]
	v_pk_fma_f32 v[110:111], v[110:111], v[134:135], v[186:187]
	global_store_dwordx4 v[246:247], v[106:109], off offset:576
	global_store_dwordx4 v[246:247], v[110:113], off offset:512
	v_pk_fma_f32 v[92:93], v[92:93], v[128:129], v[208:209]
	v_lshl_add_u64 v[106:107], s[14:15], 0, v[242:243]
	v_lshl_add_u64 v[110:111], v[106:107], 0, v[158:159]
	v_pk_fma_f32 v[90:91], v[90:91], v[126:127], v[206:207]
	v_pk_fma_f32 v[96:97], v[96:97], v[136:137], v[204:205]
	v_pk_fma_f32 v[94:95], v[94:95], v[134:135], v[202:203]
	global_store_dwordx4 v[110:111], v[90:93], off offset:576
	global_store_dwordx4 v[110:111], v[94:97], off offset:512
	v_pk_fma_f32 v[76:77], v[76:77], v[128:129], v[224:225]
	v_lshl_add_u64 v[90:91], s[14:15], 0, v[244:245]
	v_lshl_add_u64 v[94:95], v[90:91], 0, v[158:159]
	v_pk_fma_f32 v[74:75], v[74:75], v[126:127], v[222:223]
	v_pk_fma_f32 v[80:81], v[80:81], v[136:137], v[220:221]
	v_pk_fma_f32 v[78:79], v[78:79], v[134:135], v[218:219]
	global_store_dwordx4 v[94:95], v[74:77], off offset:576
	v_pk_fma_f32 v[108:109], v[120:121], v[144:145], v[196:197]
	v_pk_fma_f32 v[106:107], v[118:119], v[142:143], v[194:195]
	v_lshl_add_u64 v[74:75], s[14:15], 0, v[168:169]
	v_pk_fma_f32 v[92:93], v[104:105], v[144:145], v[212:213]
	v_pk_fma_f32 v[90:91], v[102:103], v[142:143], v[210:211]
	global_store_dwordx4 v[94:95], v[78:81], off offset:512
	v_pk_fma_f32 v[76:77], v[88:89], v[144:145], v[228:229]
	v_pk_fma_f32 v[132:133], v[132:133], v[144:145], v[180:181]
	v_lshl_add_u64 v[78:79], v[74:75], 0, v[158:159]
	v_pk_fma_f32 v[74:75], v[86:87], v[142:143], v[226:227]
	v_pk_fma_f32 v[130:131], v[130:131], v[142:143], v[178:179]
	v_pk_fma_f32 v[124:125], v[124:125], v[140:141], v[184:185]
	v_pk_fma_f32 v[122:123], v[122:123], v[138:139], v[182:183]
	global_store_dwordx4 v[110:111], v[106:109], off
	global_store_dwordx4 v[94:95], v[90:93], off
	global_store_dwordx4 v[78:79], v[74:77], off
	v_pk_fma_f32 v[108:109], v[116:117], v[140:141], v[200:201]
	v_pk_fma_f32 v[106:107], v[114:115], v[138:139], v[198:199]
	v_pk_fma_f32 v[92:93], v[100:101], v[140:141], v[216:217]
	v_pk_fma_f32 v[90:91], v[98:99], v[138:139], v[214:215]
	v_pk_fma_f32 v[76:77], v[84:85], v[140:141], v[232:233]
	v_pk_fma_f32 v[74:75], v[82:83], v[138:139], v[230:231]
	v_pk_fma_f32 v[72:73], v[72:73], v[136:137], v[236:237]
	v_pk_fma_f32 v[70:71], v[70:71], v[134:135], v[234:235]
	v_pk_fma_f32 v[68:69], v[68:69], v[128:129], v[240:241]
	v_pk_fma_f32 v[66:67], v[66:67], v[126:127], v[238:239]
	v_lshl_add_u64 v[168:169], v[162:163], 0, s[22:23]
	global_store_dwordx4 v[246:247], v[130:133], off
	global_store_dwordx4 v[246:247], v[122:125], off offset:64
	global_store_dwordx4 v[110:111], v[106:109], off offset:64
	global_store_dwordx4 v[94:95], v[90:93], off offset:64
	global_store_dwordx4 v[78:79], v[74:77], off offset:64
	global_store_dwordx4 v[78:79], v[70:73], off offset:512
	global_store_dwordx4 v[78:79], v[66:69], off offset:576
	v_lshl_add_u64 v[182:183], v[162:163], 0, s[24:25]
	v_lshl_add_u64 v[108:109], v[162:163], 0, s[26:27]
	v_lshl_add_u64 v[66:67], v[160:161], 0, v[168:169]
	global_load_dwordx4 v[110:113], v[66:67], off
	global_load_dwordx4 v[114:117], v[66:67], off offset:64
	global_load_dwordx4 v[118:121], v[66:67], off offset:512
	global_load_dwordx4 v[122:125], v[66:67], off offset:576
	v_lshl_add_u64 v[66:67], v[160:161], 0, v[182:183]
	global_load_dwordx4 v[130:133], v[66:67], off
	global_load_dwordx4 v[178:181], v[66:67], off offset:64
	global_load_dwordx4 v[102:105], v[66:67], off offset:512
	global_load_dwordx4 v[98:101], v[66:67], off offset:576
	v_lshl_add_u64 v[66:67], v[160:161], 0, v[108:109]
	v_lshl_add_u64 v[106:107], v[162:163], 0, s[16:17]
	global_load_dwordx4 v[94:97], v[66:67], off
	global_load_dwordx4 v[90:93], v[66:67], off offset:64
	global_load_dwordx4 v[86:89], v[66:67], off offset:512
	global_load_dwordx4 v[82:85], v[66:67], off offset:576
	v_lshl_add_u64 v[66:67], v[160:161], 0, v[106:107]
	global_load_dwordx4 v[78:81], v[66:67], off
	global_load_dwordx4 v[74:77], v[66:67], off offset:64
	global_load_dwordx4 v[70:73], v[66:67], off offset:512
	s_nop 0
	global_load_dwordx4 v[66:69], v[66:67], off offset:576
	v_lshl_add_u64 v[160:161], s[14:15], 0, v[168:169]
	v_lshl_add_u64 v[160:161], v[160:161], 0, v[158:159]
	s_waitcnt vmcnt(0)
	v_pk_fma_f32 v[44:45], v[44:45], v[128:129], v[124:125]
	v_pk_fma_f32 v[42:43], v[42:43], v[126:127], v[122:123]
	v_pk_fma_f32 v[52:53], v[52:53], v[136:137], v[120:121]
	v_pk_fma_f32 v[50:51], v[50:51], v[134:135], v[118:119]
	global_store_dwordx4 v[160:161], v[42:45], off offset:576
	global_store_dwordx4 v[160:161], v[50:53], off offset:512
	v_pk_fma_f32 v[28:29], v[28:29], v[128:129], v[100:101]
	v_lshl_add_u64 v[42:43], s[14:15], 0, v[182:183]
	v_lshl_add_u64 v[50:51], v[42:43], 0, v[158:159]
	v_pk_fma_f32 v[26:27], v[26:27], v[126:127], v[98:99]
	v_pk_fma_f32 v[36:37], v[36:37], v[136:137], v[104:105]
	v_pk_fma_f32 v[34:35], v[34:35], v[134:135], v[102:103]
	global_store_dwordx4 v[50:51], v[26:29], off offset:576
	global_store_dwordx4 v[50:51], v[34:37], off offset:512
	v_pk_fma_f32 v[12:13], v[12:13], v[128:129], v[84:85]
	v_lshl_add_u64 v[26:27], s[14:15], 0, v[108:109]
	v_lshl_add_u64 v[34:35], v[26:27], 0, v[158:159]
	v_pk_fma_f32 v[10:11], v[10:11], v[126:127], v[82:83]
	v_pk_fma_f32 v[20:21], v[20:21], v[136:137], v[88:89]
	v_pk_fma_f32 v[18:19], v[18:19], v[134:135], v[86:87]
	global_store_dwordx4 v[34:35], v[10:13], off offset:576
	v_pk_fma_f32 v[44:45], v[56:57], v[144:145], v[132:133]
	v_pk_fma_f32 v[42:43], v[54:55], v[142:143], v[130:131]
	v_lshl_add_u64 v[10:11], s[14:15], 0, v[106:107]
	v_pk_fma_f32 v[28:29], v[40:41], v[144:145], v[96:97]
	v_pk_fma_f32 v[26:27], v[38:39], v[142:143], v[94:95]
	global_store_dwordx4 v[34:35], v[18:21], off offset:512
	v_pk_fma_f32 v[12:13], v[24:25], v[144:145], v[80:81]
	v_pk_fma_f32 v[64:65], v[64:65], v[144:145], v[112:113]
	v_lshl_add_u64 v[18:19], v[10:11], 0, v[158:159]
	v_pk_fma_f32 v[10:11], v[22:23], v[142:143], v[78:79]
	v_pk_fma_f32 v[62:63], v[62:63], v[142:143], v[110:111]
	v_pk_fma_f32 v[60:61], v[60:61], v[140:141], v[116:117]
	v_pk_fma_f32 v[58:59], v[58:59], v[138:139], v[114:115]
	global_store_dwordx4 v[50:51], v[42:45], off
	global_store_dwordx4 v[34:35], v[26:29], off
	global_store_dwordx4 v[18:19], v[10:13], off
	v_pk_fma_f32 v[44:45], v[48:49], v[140:141], v[180:181]
	v_pk_fma_f32 v[42:43], v[46:47], v[138:139], v[178:179]
	v_pk_fma_f32 v[28:29], v[32:33], v[140:141], v[92:93]
	v_pk_fma_f32 v[26:27], v[30:31], v[138:139], v[90:91]
	v_pk_fma_f32 v[12:13], v[16:17], v[140:141], v[76:77]
	v_pk_fma_f32 v[10:11], v[14:15], v[138:139], v[74:75]
	v_pk_fma_f32 v[8:9], v[8:9], v[136:137], v[72:73]
	v_pk_fma_f32 v[6:7], v[6:7], v[134:135], v[70:71]
	v_pk_fma_f32 v[4:5], v[4:5], v[128:129], v[68:69]
	v_pk_fma_f32 v[2:3], v[2:3], v[126:127], v[66:67]
	s_and_b64 vcc, exec, s[4:5]
	s_mov_b32 s57, s54
	s_mov_b32 s56, s55
	s_mov_b64 s[30:31], s[8:9]
	s_mov_b64 s[28:29], s[6:7]
	global_store_dwordx4 v[160:161], v[62:65], off
	global_store_dwordx4 v[160:161], v[58:61], off offset:64
	global_store_dwordx4 v[50:51], v[42:45], off offset:64
	global_store_dwordx4 v[34:35], v[26:29], off offset:64
	global_store_dwordx4 v[18:19], v[10:13], off offset:64
	global_store_dwordx4 v[18:19], v[6:9], off offset:512
	global_store_dwordx4 v[18:19], v[2:5], off offset:576
	s_cbranch_vccz .LBB0_1286
	s_waitcnt vmcnt(0)
	s_cmpk_gt_u32 s38, 0xff
	s_cbranch_scc1 .LBB0_1301
	s_barrier
